# GEMM K-loops: first iteration peeled with SrcC=0 on each accumulator's first MFMA; the 128 per-tile v_mov zero-inits removed
# speedup vs baseline: 1.0098x; 1.0087x over previous
; #define PG8_STAGE(bufoff, gbase, voff) do { _Pragma("unroll") for (int _i = 0; _i < 2; ++_i) \
;         __builtin_amdgcn_global_load_lds((const unsigned*)((const char*)(gbase) + (voff)[_i]), (LAS unsigned*)(lds + (bufoff) + ldsw + _i * 8192), 16, 0, 0); } while (0)
; #define PG8_LDA(dst, b, h) do { _Pragma("unroll") for (int m = 0; m < 4; ++m) _Pragma("unroll") for (int k = 0; k < 2; ++k) dst[m][k] = *(const LAS bf16x8*)(lds + PG8_SA(b, h) + aoff + m * 2048 + k * 1024); } while (0)
; #define PG8_LDB(dst, b, h) do { _Pragma("unroll") for (int n = 0; n < 2; ++n) _Pragma("unroll") for (int k = 0; k < 2; ++k) dst[n][k] = *(const LAS bf16x8*)(lds + PG8_SB(b, h) + boff + n * 2048 + k * 1024); } while (0)
; #define PG8_MMA(ai, bj, At, Bt) do { __builtin_amdgcn_s_setprio(1); _Pragma("unroll") for (int m = 0; m < 4; ++m) _Pragma("unroll") for (int n = 0; n < 2; ++n) _Pragma("unroll") for (int k = 0; k < 2; ++k) \
;         acc[ai][bj][m][n] = __builtin_amdgcn_mfma_f32_16x16x32_bf16(Bt[n][k], At[m][k], acc[ai][bj][m][n], 0, 0, 0); __builtin_amdgcn_s_setprio(0); } while (0)
; #define PG8_WAIT_V(n) asm volatile("s_waitcnt vmcnt(" #n ")" ::: "memory")
; #define PG8_WAIT_L(n) asm volatile("s_waitcnt lgkmcnt(" #n ")" ::: "memory")
; __device__ __forceinline__ void gemm_phase(LAS unsigned char* lds, const Params& p, const bf16_t* gA, const bf16_t* gBt, const int gM, const int gN, const int gK, const int epi, const int perm, bf16_t* const Hp, const int goff, const float coef) {
;     ...
;         const char* nA = has_next ? (const char*)gA + (size_t)nxt.pm * tstep + (nxt.ks > 0 ? nxt.ks * ksl : 0) : cA; const char* nB = has_next ? (const char*)gBt + (size_t)nxt.pn * tstep + (nxt.ks > 0 ? nxt.ks * ksl : 0) : cB;
;         const int nt = cur.ks >= 0 ? ntf / 4 : ntf;
;         for (int t = 0; t < nt; t += 2) {
;             const bool last = (t == nt - 2);
;             const char* a1 = cA + (size_t)(t + 1) * kstep;
;             const char* a2 = last ? nA : cA + (size_t)(t + 2) * kstep; const char* b2 = last ? nB : cB + (size_t)(t + 2) * kstep;
;             const char* a3 = a2 + kstep; const char* b3 = b2 + kstep;
;             PG8_LDB(B0, 0, 0); PG8_LDB(B1, 0, 1); PG8_SCHED; PG8_LDA(At, 0, 0); PG8_STAGE(PG8_SA(1, 1), a1 + hstep, voffA);
;             PG8_WAIT_V(8); PG8_WAIT_L(0); PG8_BAR; PG8_MMA(0, 0, At, B0); PG8_MMA(0, 1, At, B1); PG8_BAR; PG8_SCHED;
.LBB0_169:
	s_ashr_i32 s25, s24, 31
	s_lshl_b64 s[30:31], s[24:25], 20
	s_add_u32 s25, s3, s30
	s_addc_u32 s27, s10, s31
	s_lshl_b64 s[30:31], s[0:1], 10
	s_cmp_gt_i32 s0, 0
	s_cselect_b32 s52, s30, 0
	s_cselect_b32 s51, s31, 0
	s_add_u32 s30, s25, s52
	s_addc_u32 s31, s27, s51
	s_and_b64 s[34:35], s[28:29], exec
	s_cselect_b32 s25, s31, s45
	s_cselect_b32 s50, s30, s44
	s_ashr_i32 s27, s26, 31
	s_lshl_b64 s[34:35], s[26:27], 20
	s_add_u32 s27, s74, s34
	s_addc_u32 s35, s75, s35
	s_add_u32 s34, s27, s52
	s_addc_u32 s35, s35, s51
	s_and_b64 s[52:53], s[28:29], exec
	s_cselect_b32 s27, s35, s47
	s_cselect_b32 s51, s34, s46
	s_cmp_gt_i32 s49, -1
	s_cselect_b32 s52, 8, 32
	s_add_i32 s53, s52, -2
	s_add_u32 s44, s44, 0x80080
	s_addc_u32 s45, s45, 0
	s_add_u32 s54, s46, 0x100
	s_mov_b32 s48, 0
	s_addc_u32 s55, s47, 0
	ds_read_b128 v[158:161], v155
	ds_read_b128 v[162:165], v155 offset:1024
	ds_read_b128 v[166:169], v155 offset:2048
	ds_read_b128 v[170:173], v155 offset:3072
	ds_read_b128 v[174:177], v156
	ds_read_b128 v[178:181], v156 offset:1024
	ds_read_b128 v[182:185], v156 offset:2048
	ds_read_b128 v[186:189], v156 offset:3072
	s_add_i32 s56, s48, 2
	s_add_u32 s46, s44, 0xfff80080
	s_addc_u32 s47, s45, -1
	s_cmp_eq_u32 s53, s48
	s_cselect_b32 s48, s50, s46
	s_cselect_b32 s49, s25, s47
	s_cselect_b32 s47, s27, s55
	s_cselect_b32 s46, s51, s54
	v_lshl_add_u64 v[144:145], s[44:45], 0, v[136:137]
	s_add_i32 m0, s14, 0xc000
	ds_read_b128 v[190:193], v157
	ds_read_b128 v[194:197], v157 offset:1024
	ds_read_b128 v[198:201], v157 offset:2048
	ds_read_b128 v[202:205], v157 offset:3072
	ds_read_b128 v[206:209], v157 offset:4096
	ds_read_b128 v[210:213], v157 offset:5120
	ds_read_b128 v[214:217], v157 offset:6144
	ds_read_b128 v[218:221], v157 offset:7168
	global_load_lds_dwordx4 v[144:145], off
	v_lshl_add_u64 v[144:145], s[44:45], 0, v[138:139]
	s_add_i32 m0, s14, 0xe000
	s_nop 0
	global_load_lds_dwordx4 v[144:145], off
	s_waitcnt vmcnt(8)
	s_waitcnt lgkmcnt(0)
	s_barrier
	s_waitcnt lgkmcnt(0)
	v_mfma_f32_16x16x32_bf16 v[124:127], v[158:161], v[190:193], 0
	v_mfma_f32_16x16x32_bf16 v[120:123], v[166:169], v[190:193], 0
	v_mfma_f32_16x16x32_bf16 v[108:111], v[158:161], v[198:201], 0
	v_mfma_f32_16x16x32_bf16 v[104:107], v[166:169], v[198:201], 0
	v_mfma_f32_16x16x32_bf16 v[92:95], v[158:161], v[206:209], 0
	v_mfma_f32_16x16x32_bf16 v[88:91], v[166:169], v[206:209], 0
	v_mfma_f32_16x16x32_bf16 v[76:79], v[158:161], v[214:217], 0
	v_mfma_f32_16x16x32_bf16 v[72:75], v[166:169], v[214:217], 0
	v_mfma_f32_16x16x32_bf16 v[124:127], v[162:165], v[194:197], v[124:127]
	v_mfma_f32_16x16x32_bf16 v[120:123], v[170:173], v[194:197], v[120:123]
	v_mfma_f32_16x16x32_bf16 v[108:111], v[162:165], v[202:205], v[108:111]
	v_mfma_f32_16x16x32_bf16 v[104:107], v[170:173], v[202:205], v[104:107]
	v_mfma_f32_16x16x32_bf16 v[92:95], v[162:165], v[210:213], v[92:95]
	v_mfma_f32_16x16x32_bf16 v[88:91], v[170:173], v[210:213], v[88:91]
	v_mfma_f32_16x16x32_bf16 v[76:79], v[162:165], v[218:221], v[76:79]
	v_mfma_f32_16x16x32_bf16 v[72:75], v[170:173], v[218:221], v[72:75]
	v_mfma_f32_16x16x32_bf16 v[116:119], v[174:177], v[190:193], 0
	v_mfma_f32_16x16x32_bf16 v[112:115], v[182:185], v[190:193], 0
	v_mfma_f32_16x16x32_bf16 v[100:103], v[174:177], v[198:201], 0
	v_mfma_f32_16x16x32_bf16 v[96:99], v[182:185], v[198:201], 0
	v_mfma_f32_16x16x32_bf16 v[84:87], v[174:177], v[206:209], 0
	v_mfma_f32_16x16x32_bf16 v[80:83], v[182:185], v[206:209], 0
	v_mfma_f32_16x16x32_bf16 v[68:71], v[174:177], v[214:217], 0
	v_mfma_f32_16x16x32_bf16 v[64:67], v[182:185], v[214:217], 0
	v_mfma_f32_16x16x32_bf16 v[116:119], v[178:181], v[194:197], v[116:119]
	v_mfma_f32_16x16x32_bf16 v[112:115], v[186:189], v[194:197], v[112:115]
	v_mfma_f32_16x16x32_bf16 v[100:103], v[178:181], v[202:205], v[100:103]
	v_mfma_f32_16x16x32_bf16 v[96:99], v[186:189], v[202:205], v[96:99]
	v_mfma_f32_16x16x32_bf16 v[84:87], v[178:181], v[210:213], v[84:87]
	v_mfma_f32_16x16x32_bf16 v[80:83], v[186:189], v[210:213], v[80:83]
	v_mfma_f32_16x16x32_bf16 v[68:71], v[178:181], v[218:221], v[68:71]
	v_mfma_f32_16x16x32_bf16 v[64:67], v[186:189], v[218:221], v[64:67]
	s_barrier
	s_add_i32 s57, s23, s11
	v_lshl_add_u64 v[144:145], s[46:47], 0, v[130:131]
	s_mov_b32 m0, s57
	ds_read_b128 v[190:193], v157 offset:16384
	ds_read_b128 v[194:197], v157 offset:17408
	ds_read_b128 v[198:201], v157 offset:18432
	ds_read_b128 v[202:205], v157 offset:19456
	ds_read_b128 v[206:209], v157 offset:20480
	ds_read_b128 v[210:213], v157 offset:21504
	ds_read_b128 v[214:217], v157 offset:22528
	ds_read_b128 v[218:221], v157 offset:23552
	global_load_lds_dwordx4 v[144:145], off
	s_add_i32 m0, s57, 0x2000
	s_add_u32 s58, s46, 0x80000
	v_lshl_add_u64 v[222:223], s[46:47], 0, v[134:135]
	s_addc_u32 s59, s47, 0
	s_add_i32 s57, s33, s11
	global_load_lds_dwordx4 v[222:223], off
	v_lshl_add_u64 v[224:225], s[58:59], 0, v[130:131]
	s_mov_b32 m0, s57
	v_lshl_add_u64 v[226:227], s[48:49], 0, v[132:133]
	global_load_lds_dwordx4 v[224:225], off
	v_lshl_add_u64 v[224:225], s[58:59], 0, v[134:135]
	s_add_i32 m0, s57, 0x2000
	s_nop 0
	global_load_lds_dwordx4 v[224:225], off
	v_lshl_add_u64 v[224:225], s[48:49], 0, v[128:129]
	s_mov_b32 m0, s14
	s_nop 0
	global_load_lds_dwordx4 v[224:225], off
	s_mov_b32 m0, s15
	s_nop 0
	global_load_lds_dwordx4 v[226:227], off
	s_waitcnt vmcnt(8)
	s_waitcnt lgkmcnt(0)
	s_barrier
; #define PG8_STAGE(bufoff, gbase, voff) do { _Pragma("unroll") for (int _i = 0; _i < 2; ++_i) \
;         __builtin_amdgcn_global_load_lds((const unsigned*)((const char*)(gbase) + (voff)[_i]), (LAS unsigned*)(lds + (bufoff) + ldsw + _i * 8192), 16, 0, 0); } while (0)
; #define PG8_LDA(dst, b, h) do { _Pragma("unroll") for (int m = 0; m < 4; ++m) _Pragma("unroll") for (int k = 0; k < 2; ++k) dst[m][k] = *(const LAS bf16x8*)(lds + PG8_SA(b, h) + aoff + m * 2048 + k * 1024); } while (0)
; #define PG8_LDB(dst, b, h) do { _Pragma("unroll") for (int n = 0; n < 2; ++n) _Pragma("unroll") for (int k = 0; k < 2; ++k) dst[n][k] = *(const LAS bf16x8*)(lds + PG8_SB(b, h) + boff + n * 2048 + k * 1024); } while (0)
; #define PG8_MMA(ai, bj, At, Bt) do { __builtin_amdgcn_s_setprio(1); _Pragma("unroll") for (int m = 0; m < 4; ++m) _Pragma("unroll") for (int n = 0; n < 2; ++n) _Pragma("unroll") for (int k = 0; k < 2; ++k) \
;         acc[ai][bj][m][n] = __builtin_amdgcn_mfma_f32_16x16x32_bf16(Bt[n][k], At[m][k], acc[ai][bj][m][n], 0, 0, 0); __builtin_amdgcn_s_setprio(0); } while (0)
; #define PG8_WAIT_V(n) asm volatile("s_waitcnt vmcnt(" #n ")" ::: "memory")
; #define PG8_WAIT_L(n) asm volatile("s_waitcnt lgkmcnt(" #n ")" ::: "memory")
; #define PG8_BAR __builtin_amdgcn_s_barrier()
; #define PG8_SCHED __builtin_amdgcn_sched_barrier(0)
; __device__ __forceinline__ void gemm_phase(LAS unsigned char* lds, const Params& p, const bf16_t* gA, const bf16_t* gBt, const int gM, const int gN, const int gK, const int epi, const int perm, bf16_t* const Hp, const int goff, const float coef) {
;     ...
;             PG8_WAIT_V(8); PG8_WAIT_L(0); PG8_BAR; PG8_MMA(0, 0, At, B0); PG8_MMA(0, 1, At, B1); PG8_BAR; PG8_SCHED;
;             PG8_LDA(At, 0, 1); PG8_STAGE(PG8_SB(0, 0), b2, voffB); PG8_STAGE(PG8_SB(0, 1), b2 + hstep, voffB); PG8_STAGE(PG8_SA(0, 0), a2, voffA);
;             PG8_WAIT_V(8); PG8_WAIT_L(0); PG8_BAR; PG8_MMA(1, 0, At, B0); PG8_MMA(1, 1, At, B1); PG8_BAR; PG8_SCHED;
;             PG8_LDB(B0, 1, 0); PG8_LDB(B1, 1, 1); PG8_SCHED; PG8_LDA(At, 1, 0); PG8_STAGE(PG8_SA(0, 1), a2 + hstep, voffA);
;             PG8_WAIT_V(8); PG8_WAIT_L(0); PG8_BAR; PG8_MMA(0, 0, At, B0); PG8_MMA(0, 1, At, B1); PG8_BAR; PG8_SCHED;
	s_waitcnt lgkmcnt(0)
	v_mfma_f32_16x16x32_bf16 v[60:63], v[158:161], v[190:193], 0
	v_mfma_f32_16x16x32_bf16 v[56:59], v[166:169], v[190:193], 0
	v_mfma_f32_16x16x32_bf16 v[44:47], v[158:161], v[198:201], 0
	v_mfma_f32_16x16x32_bf16 v[40:43], v[166:169], v[198:201], 0
	v_mfma_f32_16x16x32_bf16 v[28:31], v[158:161], v[206:209], 0
	v_mfma_f32_16x16x32_bf16 v[24:27], v[166:169], v[206:209], 0
	v_mfma_f32_16x16x32_bf16 v[12:15], v[158:161], v[214:217], 0
	v_mfma_f32_16x16x32_bf16 v[8:11], v[166:169], v[214:217], 0
	v_mfma_f32_16x16x32_bf16 v[60:63], v[162:165], v[194:197], v[60:63]
	v_mfma_f32_16x16x32_bf16 v[56:59], v[170:173], v[194:197], v[56:59]
	v_mfma_f32_16x16x32_bf16 v[44:47], v[162:165], v[202:205], v[44:47]
	v_mfma_f32_16x16x32_bf16 v[40:43], v[170:173], v[202:205], v[40:43]
	v_mfma_f32_16x16x32_bf16 v[28:31], v[162:165], v[210:213], v[28:31]
	v_mfma_f32_16x16x32_bf16 v[24:27], v[170:173], v[210:213], v[24:27]
	v_mfma_f32_16x16x32_bf16 v[12:15], v[162:165], v[218:221], v[12:15]
	v_mfma_f32_16x16x32_bf16 v[8:11], v[170:173], v[218:221], v[8:11]
	v_mfma_f32_16x16x32_bf16 v[52:55], v[174:177], v[190:193], 0
	v_mfma_f32_16x16x32_bf16 v[48:51], v[182:185], v[190:193], 0
	v_mfma_f32_16x16x32_bf16 v[36:39], v[174:177], v[198:201], 0
	v_mfma_f32_16x16x32_bf16 v[32:35], v[182:185], v[198:201], 0
	v_mfma_f32_16x16x32_bf16 v[20:23], v[174:177], v[206:209], 0
	v_mfma_f32_16x16x32_bf16 v[16:19], v[182:185], v[206:209], 0
	v_mfma_f32_16x16x32_bf16 v[4:7], v[174:177], v[214:217], 0
	v_mfma_f32_16x16x32_bf16 v[0:3], v[182:185], v[214:217], 0
	v_mfma_f32_16x16x32_bf16 v[52:55], v[178:181], v[194:197], v[52:55]
	v_mfma_f32_16x16x32_bf16 v[48:51], v[186:189], v[194:197], v[48:51]
	v_mfma_f32_16x16x32_bf16 v[36:39], v[178:181], v[202:205], v[36:39]
	v_mfma_f32_16x16x32_bf16 v[32:35], v[186:189], v[202:205], v[32:35]
	v_mfma_f32_16x16x32_bf16 v[20:23], v[178:181], v[210:213], v[20:23]
	v_mfma_f32_16x16x32_bf16 v[16:19], v[186:189], v[210:213], v[16:19]
	v_mfma_f32_16x16x32_bf16 v[4:7], v[178:181], v[218:221], v[4:7]
	v_mfma_f32_16x16x32_bf16 v[0:3], v[186:189], v[218:221], v[0:3]
	s_barrier
	s_add_i32 s57, 0, 0x18000
	s_add_i32 s58, 0, 0x1c000
	v_add_u32_e32 v170, s57, v146
	v_add_u32_e32 v186, s58, v146
	ds_read_b128 v[158:161], v170
	ds_read_b128 v[162:165], v170 offset:1024
	ds_read_b128 v[166:169], v170 offset:2048
	ds_read_b128 v[170:173], v170 offset:3072
	ds_read_b128 v[174:177], v186
	ds_read_b128 v[178:181], v186 offset:1024
	ds_read_b128 v[182:185], v186 offset:2048
	ds_read_b128 v[186:189], v186 offset:3072
	s_add_u32 s48, s48, 0x80000
	s_addc_u32 s49, s49, 0
	s_mov_b32 m0, s16
	v_lshl_add_u64 v[228:229], s[48:49], 0, v[128:129]
	ds_read_b128 v[190:193], v157 offset:32768
	ds_read_b128 v[194:197], v157 offset:33792
	ds_read_b128 v[198:201], v157 offset:34816
	ds_read_b128 v[202:205], v157 offset:35840
	ds_read_b128 v[206:209], v157 offset:36864
	ds_read_b128 v[210:213], v157 offset:37888
	ds_read_b128 v[214:217], v157 offset:38912
	ds_read_b128 v[218:221], v157 offset:39936
	global_load_lds_dwordx4 v[228:229], off
	v_lshl_add_u64 v[228:229], s[48:49], 0, v[132:133]
	s_mov_b32 m0, s17
	s_nop 0
	global_load_lds_dwordx4 v[228:229], off
	s_waitcnt vmcnt(8)
	s_waitcnt lgkmcnt(0)
	s_barrier
	s_waitcnt lgkmcnt(0)
	v_mfma_f32_16x16x32_bf16 v[124:127], v[158:161], v[190:193], v[124:127]
	v_mfma_f32_16x16x32_bf16 v[120:123], v[166:169], v[190:193], v[120:123]
	v_mfma_f32_16x16x32_bf16 v[108:111], v[158:161], v[198:201], v[108:111]
	v_mfma_f32_16x16x32_bf16 v[104:107], v[166:169], v[198:201], v[104:107]
	v_mfma_f32_16x16x32_bf16 v[92:95], v[158:161], v[206:209], v[92:95]
	v_mfma_f32_16x16x32_bf16 v[88:91], v[166:169], v[206:209], v[88:91]
	v_mfma_f32_16x16x32_bf16 v[76:79], v[158:161], v[214:217], v[76:79]
	v_mfma_f32_16x16x32_bf16 v[72:75], v[166:169], v[214:217], v[72:75]
	v_mfma_f32_16x16x32_bf16 v[124:127], v[162:165], v[194:197], v[124:127]
	v_mfma_f32_16x16x32_bf16 v[120:123], v[170:173], v[194:197], v[120:123]
	v_mfma_f32_16x16x32_bf16 v[108:111], v[162:165], v[202:205], v[108:111]
	v_mfma_f32_16x16x32_bf16 v[104:107], v[170:173], v[202:205], v[104:107]
	v_mfma_f32_16x16x32_bf16 v[92:95], v[162:165], v[210:213], v[92:95]
	v_mfma_f32_16x16x32_bf16 v[88:91], v[170:173], v[210:213], v[88:91]
	v_mfma_f32_16x16x32_bf16 v[76:79], v[162:165], v[218:221], v[76:79]
	v_mfma_f32_16x16x32_bf16 v[72:75], v[170:173], v[218:221], v[72:75]
	v_mfma_f32_16x16x32_bf16 v[116:119], v[174:177], v[190:193], v[116:119]
	v_mfma_f32_16x16x32_bf16 v[112:115], v[182:185], v[190:193], v[112:115]
	v_mfma_f32_16x16x32_bf16 v[100:103], v[174:177], v[198:201], v[100:103]
	v_mfma_f32_16x16x32_bf16 v[96:99], v[182:185], v[198:201], v[96:99]
	v_mfma_f32_16x16x32_bf16 v[84:87], v[174:177], v[206:209], v[84:87]
	v_mfma_f32_16x16x32_bf16 v[80:83], v[182:185], v[206:209], v[80:83]
	v_mfma_f32_16x16x32_bf16 v[68:71], v[174:177], v[214:217], v[68:71]
	v_mfma_f32_16x16x32_bf16 v[64:67], v[182:185], v[214:217], v[64:67]
	v_mfma_f32_16x16x32_bf16 v[116:119], v[178:181], v[194:197], v[116:119]
	v_mfma_f32_16x16x32_bf16 v[112:115], v[186:189], v[194:197], v[112:115]
	v_mfma_f32_16x16x32_bf16 v[100:103], v[178:181], v[202:205], v[100:103]
	v_mfma_f32_16x16x32_bf16 v[96:99], v[186:189], v[202:205], v[96:99]
	v_mfma_f32_16x16x32_bf16 v[84:87], v[178:181], v[210:213], v[84:87]
	v_mfma_f32_16x16x32_bf16 v[80:83], v[186:189], v[210:213], v[80:83]
	v_mfma_f32_16x16x32_bf16 v[68:71], v[178:181], v[218:221], v[68:71]
	v_mfma_f32_16x16x32_bf16 v[64:67], v[186:189], v[218:221], v[64:67]
	s_barrier
; #define PG8_STAGE(bufoff, gbase, voff) do { _Pragma("unroll") for (int _i = 0; _i < 2; ++_i) \
;         __builtin_amdgcn_global_load_lds((const unsigned*)((const char*)(gbase) + (voff)[_i]), (LAS unsigned*)(lds + (bufoff) + ldsw + _i * 8192), 16, 0, 0); } while (0)
; #define PG8_LDA(dst, b, h) do { _Pragma("unroll") for (int m = 0; m < 4; ++m) _Pragma("unroll") for (int k = 0; k < 2; ++k) dst[m][k] = *(const LAS bf16x8*)(lds + PG8_SA(b, h) + aoff + m * 2048 + k * 1024); } while (0)
; #define PG8_LDB(dst, b, h) do { _Pragma("unroll") for (int n = 0; n < 2; ++n) _Pragma("unroll") for (int k = 0; k < 2; ++k) dst[n][k] = *(const LAS bf16x8*)(lds + PG8_SB(b, h) + boff + n * 2048 + k * 1024); } while (0)
; #define PG8_MMA(ai, bj, At, Bt) do { __builtin_amdgcn_s_setprio(1); _Pragma("unroll") for (int m = 0; m < 4; ++m) _Pragma("unroll") for (int n = 0; n < 2; ++n) _Pragma("unroll") for (int k = 0; k < 2; ++k) \
;         acc[ai][bj][m][n] = __builtin_amdgcn_mfma_f32_16x16x32_bf16(Bt[n][k], At[m][k], acc[ai][bj][m][n], 0, 0, 0); __builtin_amdgcn_s_setprio(0); } while (0)
; #define PG8_WAIT_V(n) asm volatile("s_waitcnt vmcnt(" #n ")" ::: "memory")
; #define PG8_WAIT_L(n) asm volatile("s_waitcnt lgkmcnt(" #n ")" ::: "memory")
; __device__ __forceinline__ void gemm_phase(LAS unsigned char* lds, const Params& p, const bf16_t* gA, const bf16_t* gBt, const int gM, const int gN, const int gK, const int epi, const int perm, bf16_t* const Hp, const int goff, const float coef) {
;     ...
;         for (int t = 0; t < nt; t += 2) {
;             const bool last = (t == nt - 2);
;             const char* a1 = cA + (size_t)(t + 1) * kstep;
;             const char* a2 = last ? nA : cA + (size_t)(t + 2) * kstep; const char* b2 = last ? nB : cB + (size_t)(t + 2) * kstep;
;             const char* a3 = a2 + kstep; const char* b3 = b2 + kstep;
;             PG8_LDB(B0, 0, 0); PG8_LDB(B1, 0, 1); PG8_SCHED; PG8_LDA(At, 0, 0); PG8_STAGE(PG8_SA(1, 1), a1 + hstep, voffA);
;             PG8_WAIT_V(8); PG8_WAIT_L(0); PG8_BAR; PG8_MMA(0, 0, At, B0); PG8_MMA(0, 1, At, B1); PG8_BAR; PG8_SCHED;
;     ...
;             PG8_LDA(At, 1, 1); PG8_STAGE(PG8_SB(1, 0), b3, voffB); PG8_STAGE(PG8_SB(1, 1), b3 + hstep, voffB); PG8_STAGE(PG8_SA(1, 0), a3, voffA);
;             PG8_WAIT_V(8); PG8_WAIT_L(0); PG8_BAR; PG8_MMA(1, 0, At, B0); PG8_MMA(1, 1, At, B1); PG8_BAR; PG8_SCHED;
	s_add_i32 s48, s57, s11
	v_lshl_add_u64 v[144:145], v[144:145], 0, s[8:9]
	s_mov_b32 m0, s48
	ds_read_b128 v[190:193], v157 offset:49152
	ds_read_b128 v[194:197], v157 offset:50176
	ds_read_b128 v[198:201], v157 offset:51200
	ds_read_b128 v[202:205], v157 offset:52224
	ds_read_b128 v[206:209], v157 offset:53248
	ds_read_b128 v[210:213], v157 offset:54272
	ds_read_b128 v[214:217], v157 offset:55296
	ds_read_b128 v[218:221], v157 offset:56320
	global_load_lds_dwordx4 v[144:145], off
	s_add_i32 m0, s48, 0x2000
	s_add_u32 s46, s46, 0x80080
	v_lshl_add_u64 v[144:145], v[222:223], 0, s[8:9]
	s_addc_u32 s47, s47, 0
	s_add_i32 s48, s58, s11
	global_load_lds_dwordx4 v[144:145], off
	v_lshl_add_u64 v[144:145], s[46:47], 0, v[130:131]
	s_mov_b32 m0, s48
	s_nop 0
	global_load_lds_dwordx4 v[144:145], off
	v_lshl_add_u64 v[144:145], s[46:47], 0, v[134:135]
	s_add_i32 m0, s48, 0x2000
	s_nop 0
	global_load_lds_dwordx4 v[144:145], off
	v_lshl_add_u64 v[144:145], v[224:225], 0, s[8:9]
	s_mov_b32 m0, s19
	s_nop 0
	global_load_lds_dwordx4 v[144:145], off
	v_lshl_add_u64 v[144:145], v[226:227], 0, s[8:9]
	s_mov_b32 m0, s20
	s_nop 0
	global_load_lds_dwordx4 v[144:145], off
	s_waitcnt vmcnt(8)
	s_waitcnt lgkmcnt(0)
	s_barrier
	s_waitcnt lgkmcnt(0)
	v_mfma_f32_16x16x32_bf16 v[60:63], v[158:161], v[190:193], v[60:63]
	v_mfma_f32_16x16x32_bf16 v[56:59], v[166:169], v[190:193], v[56:59]
	v_mfma_f32_16x16x32_bf16 v[44:47], v[158:161], v[198:201], v[44:47]
	v_mfma_f32_16x16x32_bf16 v[40:43], v[166:169], v[198:201], v[40:43]
	v_mfma_f32_16x16x32_bf16 v[28:31], v[158:161], v[206:209], v[28:31]
	v_mfma_f32_16x16x32_bf16 v[24:27], v[166:169], v[206:209], v[24:27]
	v_mfma_f32_16x16x32_bf16 v[12:15], v[158:161], v[214:217], v[12:15]
	v_mfma_f32_16x16x32_bf16 v[8:11], v[166:169], v[214:217], v[8:11]
	v_mfma_f32_16x16x32_bf16 v[60:63], v[162:165], v[194:197], v[60:63]
	v_mfma_f32_16x16x32_bf16 v[56:59], v[170:173], v[194:197], v[56:59]
	v_mfma_f32_16x16x32_bf16 v[44:47], v[162:165], v[202:205], v[44:47]
	v_mfma_f32_16x16x32_bf16 v[40:43], v[170:173], v[202:205], v[40:43]
	v_mfma_f32_16x16x32_bf16 v[28:31], v[162:165], v[210:213], v[28:31]
	v_mfma_f32_16x16x32_bf16 v[24:27], v[170:173], v[210:213], v[24:27]
	v_mfma_f32_16x16x32_bf16 v[12:15], v[162:165], v[218:221], v[12:15]
	v_mfma_f32_16x16x32_bf16 v[8:11], v[170:173], v[218:221], v[8:11]
	v_mfma_f32_16x16x32_bf16 v[52:55], v[174:177], v[190:193], v[52:55]
	v_mfma_f32_16x16x32_bf16 v[48:51], v[182:185], v[190:193], v[48:51]
	v_mfma_f32_16x16x32_bf16 v[36:39], v[174:177], v[198:201], v[36:39]
	v_mfma_f32_16x16x32_bf16 v[32:35], v[182:185], v[198:201], v[32:35]
	v_mfma_f32_16x16x32_bf16 v[20:23], v[174:177], v[206:209], v[20:23]
	v_mfma_f32_16x16x32_bf16 v[16:19], v[182:185], v[206:209], v[16:19]
	v_mfma_f32_16x16x32_bf16 v[4:7], v[174:177], v[214:217], v[4:7]
	v_mfma_f32_16x16x32_bf16 v[0:3], v[182:185], v[214:217], v[0:3]
	v_mfma_f32_16x16x32_bf16 v[52:55], v[178:181], v[194:197], v[52:55]
	v_mfma_f32_16x16x32_bf16 v[48:51], v[186:189], v[194:197], v[48:51]
	v_mfma_f32_16x16x32_bf16 v[36:39], v[178:181], v[202:205], v[36:39]
	v_mfma_f32_16x16x32_bf16 v[32:35], v[186:189], v[202:205], v[32:35]
	v_mfma_f32_16x16x32_bf16 v[20:23], v[178:181], v[210:213], v[20:23]
	v_mfma_f32_16x16x32_bf16 v[16:19], v[186:189], v[210:213], v[16:19]
	v_mfma_f32_16x16x32_bf16 v[4:7], v[178:181], v[218:221], v[4:7]
	v_mfma_f32_16x16x32_bf16 v[0:3], v[186:189], v[218:221], v[0:3]
	s_barrier
	s_add_u32 s44, s44, 0x100
	s_addc_u32 s45, s45, 0
	s_add_u32 s54, s54, 0x100
	s_addc_u32 s55, s55, 0
	s_cmp_ge_u32 s56, s52
	s_mov_b32 s48, s56
	s_cbranch_scc1 .Lpeel_exit_0
.LBB0_170:
	ds_read_b128 v[158:161], v155
	ds_read_b128 v[162:165], v155 offset:1024
	ds_read_b128 v[166:169], v155 offset:2048
	ds_read_b128 v[170:173], v155 offset:3072
	ds_read_b128 v[174:177], v156
	ds_read_b128 v[178:181], v156 offset:1024
	ds_read_b128 v[182:185], v156 offset:2048
	ds_read_b128 v[186:189], v156 offset:3072
	s_add_i32 s56, s48, 2
	s_add_u32 s46, s44, 0xfff80080
	s_addc_u32 s47, s45, -1
	s_cmp_eq_u32 s53, s48
	s_cselect_b32 s48, s50, s46
	s_cselect_b32 s49, s25, s47
	s_cselect_b32 s47, s27, s55
	s_cselect_b32 s46, s51, s54
	v_lshl_add_u64 v[144:145], s[44:45], 0, v[136:137]
	s_add_i32 m0, s14, 0xc000
	ds_read_b128 v[190:193], v157
	ds_read_b128 v[194:197], v157 offset:1024
	ds_read_b128 v[198:201], v157 offset:2048
	ds_read_b128 v[202:205], v157 offset:3072
	ds_read_b128 v[206:209], v157 offset:4096
	ds_read_b128 v[210:213], v157 offset:5120
	ds_read_b128 v[214:217], v157 offset:6144
	ds_read_b128 v[218:221], v157 offset:7168
	global_load_lds_dwordx4 v[144:145], off
	v_lshl_add_u64 v[144:145], s[44:45], 0, v[138:139]
	s_add_i32 m0, s14, 0xe000
	s_nop 0
	global_load_lds_dwordx4 v[144:145], off
	s_waitcnt vmcnt(8)
	s_waitcnt lgkmcnt(0)
	s_barrier
; #define PG8_STAGE(bufoff, gbase, voff) do { _Pragma("unroll") for (int _i = 0; _i < 2; ++_i) \
;         __builtin_amdgcn_global_load_lds((const unsigned*)((const char*)(gbase) + (voff)[_i]), (LAS unsigned*)(lds + (bufoff) + ldsw + _i * 8192), 16, 0, 0); } while (0)
; #define PG8_LDA(dst, b, h) do { _Pragma("unroll") for (int m = 0; m < 4; ++m) _Pragma("unroll") for (int k = 0; k < 2; ++k) dst[m][k] = *(const LAS bf16x8*)(lds + PG8_SA(b, h) + aoff + m * 2048 + k * 1024); } while (0)
; #define PG8_LDB(dst, b, h) do { _Pragma("unroll") for (int n = 0; n < 2; ++n) _Pragma("unroll") for (int k = 0; k < 2; ++k) dst[n][k] = *(const LAS bf16x8*)(lds + PG8_SB(b, h) + boff + n * 2048 + k * 1024); } while (0)
; #define PG8_MMA(ai, bj, At, Bt) do { __builtin_amdgcn_s_setprio(1); _Pragma("unroll") for (int m = 0; m < 4; ++m) _Pragma("unroll") for (int n = 0; n < 2; ++n) _Pragma("unroll") for (int k = 0; k < 2; ++k) \
;         acc[ai][bj][m][n] = __builtin_amdgcn_mfma_f32_16x16x32_bf16(Bt[n][k], At[m][k], acc[ai][bj][m][n], 0, 0, 0); __builtin_amdgcn_s_setprio(0); } while (0)
; #define PG8_WAIT_V(n) asm volatile("s_waitcnt vmcnt(" #n ")" ::: "memory")
; #define PG8_WAIT_L(n) asm volatile("s_waitcnt lgkmcnt(" #n ")" ::: "memory")
; #define PG8_BAR __builtin_amdgcn_s_barrier()
; #define PG8_SCHED __builtin_amdgcn_sched_barrier(0)
; __device__ __forceinline__ void gemm_phase(LAS unsigned char* lds, const Params& p, const bf16_t* gA, const bf16_t* gBt, const int gM, const int gN, const int gK, const int epi, const int perm, bf16_t* const Hp, const int goff, const float coef) {
;     ...
;             PG8_WAIT_V(8); PG8_WAIT_L(0); PG8_BAR; PG8_MMA(0, 0, At, B0); PG8_MMA(0, 1, At, B1); PG8_BAR; PG8_SCHED;
;             PG8_LDA(At, 0, 1); PG8_STAGE(PG8_SB(0, 0), b2, voffB); PG8_STAGE(PG8_SB(0, 1), b2 + hstep, voffB); PG8_STAGE(PG8_SA(0, 0), a2, voffA);
;             PG8_WAIT_V(8); PG8_WAIT_L(0); PG8_BAR; PG8_MMA(1, 0, At, B0); PG8_MMA(1, 1, At, B1); PG8_BAR; PG8_SCHED;
;             PG8_LDB(B0, 1, 0); PG8_LDB(B1, 1, 1); PG8_SCHED; PG8_LDA(At, 1, 0); PG8_STAGE(PG8_SA(0, 1), a2 + hstep, voffA);
;             PG8_WAIT_V(8); PG8_WAIT_L(0); PG8_BAR; PG8_MMA(0, 0, At, B0); PG8_MMA(0, 1, At, B1); PG8_BAR; PG8_SCHED;
	s_waitcnt lgkmcnt(0)
	v_mfma_f32_16x16x32_bf16 v[124:127], v[158:161], v[190:193], v[124:127]
	v_mfma_f32_16x16x32_bf16 v[120:123], v[166:169], v[190:193], v[120:123]
	v_mfma_f32_16x16x32_bf16 v[108:111], v[158:161], v[198:201], v[108:111]
	v_mfma_f32_16x16x32_bf16 v[104:107], v[166:169], v[198:201], v[104:107]
	v_mfma_f32_16x16x32_bf16 v[92:95], v[158:161], v[206:209], v[92:95]
	v_mfma_f32_16x16x32_bf16 v[88:91], v[166:169], v[206:209], v[88:91]
	v_mfma_f32_16x16x32_bf16 v[76:79], v[158:161], v[214:217], v[76:79]
	v_mfma_f32_16x16x32_bf16 v[72:75], v[166:169], v[214:217], v[72:75]
	v_mfma_f32_16x16x32_bf16 v[124:127], v[162:165], v[194:197], v[124:127]
	v_mfma_f32_16x16x32_bf16 v[120:123], v[170:173], v[194:197], v[120:123]
	v_mfma_f32_16x16x32_bf16 v[108:111], v[162:165], v[202:205], v[108:111]
	v_mfma_f32_16x16x32_bf16 v[104:107], v[170:173], v[202:205], v[104:107]
	v_mfma_f32_16x16x32_bf16 v[92:95], v[162:165], v[210:213], v[92:95]
	v_mfma_f32_16x16x32_bf16 v[88:91], v[170:173], v[210:213], v[88:91]
	v_mfma_f32_16x16x32_bf16 v[76:79], v[162:165], v[218:221], v[76:79]
	v_mfma_f32_16x16x32_bf16 v[72:75], v[170:173], v[218:221], v[72:75]
	v_mfma_f32_16x16x32_bf16 v[116:119], v[174:177], v[190:193], v[116:119]
	v_mfma_f32_16x16x32_bf16 v[112:115], v[182:185], v[190:193], v[112:115]
	v_mfma_f32_16x16x32_bf16 v[100:103], v[174:177], v[198:201], v[100:103]
	v_mfma_f32_16x16x32_bf16 v[96:99], v[182:185], v[198:201], v[96:99]
	v_mfma_f32_16x16x32_bf16 v[84:87], v[174:177], v[206:209], v[84:87]
	v_mfma_f32_16x16x32_bf16 v[80:83], v[182:185], v[206:209], v[80:83]
	v_mfma_f32_16x16x32_bf16 v[68:71], v[174:177], v[214:217], v[68:71]
	v_mfma_f32_16x16x32_bf16 v[64:67], v[182:185], v[214:217], v[64:67]
	v_mfma_f32_16x16x32_bf16 v[116:119], v[178:181], v[194:197], v[116:119]
	v_mfma_f32_16x16x32_bf16 v[112:115], v[186:189], v[194:197], v[112:115]
	v_mfma_f32_16x16x32_bf16 v[100:103], v[178:181], v[202:205], v[100:103]
	v_mfma_f32_16x16x32_bf16 v[96:99], v[186:189], v[202:205], v[96:99]
	v_mfma_f32_16x16x32_bf16 v[84:87], v[178:181], v[210:213], v[84:87]
	v_mfma_f32_16x16x32_bf16 v[80:83], v[186:189], v[210:213], v[80:83]
	v_mfma_f32_16x16x32_bf16 v[68:71], v[178:181], v[218:221], v[68:71]
	v_mfma_f32_16x16x32_bf16 v[64:67], v[186:189], v[218:221], v[64:67]
	s_barrier
	s_add_i32 s57, s23, s11
	v_lshl_add_u64 v[144:145], s[46:47], 0, v[130:131]
	s_mov_b32 m0, s57
	ds_read_b128 v[190:193], v157 offset:16384
	ds_read_b128 v[194:197], v157 offset:17408
	ds_read_b128 v[198:201], v157 offset:18432
	ds_read_b128 v[202:205], v157 offset:19456
	ds_read_b128 v[206:209], v157 offset:20480
	ds_read_b128 v[210:213], v157 offset:21504
	ds_read_b128 v[214:217], v157 offset:22528
	ds_read_b128 v[218:221], v157 offset:23552
	global_load_lds_dwordx4 v[144:145], off
	s_add_i32 m0, s57, 0x2000
	s_add_u32 s58, s46, 0x80000
	v_lshl_add_u64 v[222:223], s[46:47], 0, v[134:135]
	s_addc_u32 s59, s47, 0
	s_add_i32 s57, s33, s11
	global_load_lds_dwordx4 v[222:223], off
	v_lshl_add_u64 v[224:225], s[58:59], 0, v[130:131]
	s_mov_b32 m0, s57
	v_lshl_add_u64 v[226:227], s[48:49], 0, v[132:133]
	global_load_lds_dwordx4 v[224:225], off
	v_lshl_add_u64 v[224:225], s[58:59], 0, v[134:135]
	s_add_i32 m0, s57, 0x2000
	s_nop 0
	global_load_lds_dwordx4 v[224:225], off
	v_lshl_add_u64 v[224:225], s[48:49], 0, v[128:129]
	s_mov_b32 m0, s14
	s_nop 0
	global_load_lds_dwordx4 v[224:225], off
	s_mov_b32 m0, s15
	s_nop 0
	global_load_lds_dwordx4 v[226:227], off
	s_waitcnt vmcnt(8)
	s_waitcnt lgkmcnt(0)
	s_barrier
	s_waitcnt lgkmcnt(0)
	v_mfma_f32_16x16x32_bf16 v[60:63], v[158:161], v[190:193], v[60:63]
	v_mfma_f32_16x16x32_bf16 v[56:59], v[166:169], v[190:193], v[56:59]
	v_mfma_f32_16x16x32_bf16 v[44:47], v[158:161], v[198:201], v[44:47]
	v_mfma_f32_16x16x32_bf16 v[40:43], v[166:169], v[198:201], v[40:43]
	v_mfma_f32_16x16x32_bf16 v[28:31], v[158:161], v[206:209], v[28:31]
	v_mfma_f32_16x16x32_bf16 v[24:27], v[166:169], v[206:209], v[24:27]
	v_mfma_f32_16x16x32_bf16 v[12:15], v[158:161], v[214:217], v[12:15]
	v_mfma_f32_16x16x32_bf16 v[8:11], v[166:169], v[214:217], v[8:11]
	v_mfma_f32_16x16x32_bf16 v[60:63], v[162:165], v[194:197], v[60:63]
	v_mfma_f32_16x16x32_bf16 v[56:59], v[170:173], v[194:197], v[56:59]
	v_mfma_f32_16x16x32_bf16 v[44:47], v[162:165], v[202:205], v[44:47]
	v_mfma_f32_16x16x32_bf16 v[40:43], v[170:173], v[202:205], v[40:43]
	v_mfma_f32_16x16x32_bf16 v[28:31], v[162:165], v[210:213], v[28:31]
	v_mfma_f32_16x16x32_bf16 v[24:27], v[170:173], v[210:213], v[24:27]
	v_mfma_f32_16x16x32_bf16 v[12:15], v[162:165], v[218:221], v[12:15]
	v_mfma_f32_16x16x32_bf16 v[8:11], v[170:173], v[218:221], v[8:11]
	v_mfma_f32_16x16x32_bf16 v[52:55], v[174:177], v[190:193], v[52:55]
	v_mfma_f32_16x16x32_bf16 v[48:51], v[182:185], v[190:193], v[48:51]
	v_mfma_f32_16x16x32_bf16 v[36:39], v[174:177], v[198:201], v[36:39]
	v_mfma_f32_16x16x32_bf16 v[32:35], v[182:185], v[198:201], v[32:35]
	v_mfma_f32_16x16x32_bf16 v[20:23], v[174:177], v[206:209], v[20:23]
	v_mfma_f32_16x16x32_bf16 v[16:19], v[182:185], v[206:209], v[16:19]
	v_mfma_f32_16x16x32_bf16 v[4:7], v[174:177], v[214:217], v[4:7]
	v_mfma_f32_16x16x32_bf16 v[0:3], v[182:185], v[214:217], v[0:3]
	v_mfma_f32_16x16x32_bf16 v[52:55], v[178:181], v[194:197], v[52:55]
	v_mfma_f32_16x16x32_bf16 v[48:51], v[186:189], v[194:197], v[48:51]
	v_mfma_f32_16x16x32_bf16 v[36:39], v[178:181], v[202:205], v[36:39]
	v_mfma_f32_16x16x32_bf16 v[32:35], v[186:189], v[202:205], v[32:35]
	v_mfma_f32_16x16x32_bf16 v[20:23], v[178:181], v[210:213], v[20:23]
	v_mfma_f32_16x16x32_bf16 v[16:19], v[186:189], v[210:213], v[16:19]
	v_mfma_f32_16x16x32_bf16 v[4:7], v[178:181], v[218:221], v[4:7]
	v_mfma_f32_16x16x32_bf16 v[0:3], v[186:189], v[218:221], v[0:3]
	s_barrier
; #define PG8_STAGE(bufoff, gbase, voff) do { _Pragma("unroll") for (int _i = 0; _i < 2; ++_i) \
;         __builtin_amdgcn_global_load_lds((const unsigned*)((const char*)(gbase) + (voff)[_i]), (LAS unsigned*)(lds + (bufoff) + ldsw + _i * 8192), 16, 0, 0); } while (0)
; #define PG8_LDA(dst, b, h) do { _Pragma("unroll") for (int m = 0; m < 4; ++m) _Pragma("unroll") for (int k = 0; k < 2; ++k) dst[m][k] = *(const LAS bf16x8*)(lds + PG8_SA(b, h) + aoff + m * 2048 + k * 1024); } while (0)
; #define PG8_MMA(ai, bj, At, Bt) do { __builtin_amdgcn_s_setprio(1); _Pragma("unroll") for (int m = 0; m < 4; ++m) _Pragma("unroll") for (int n = 0; n < 2; ++n) _Pragma("unroll") for (int k = 0; k < 2; ++k) \
;         acc[ai][bj][m][n] = __builtin_amdgcn_mfma_f32_16x16x32_bf16(Bt[n][k], At[m][k], acc[ai][bj][m][n], 0, 0, 0); __builtin_amdgcn_s_setprio(0); } while (0)
; #define PG8_WAIT_V(n) asm volatile("s_waitcnt vmcnt(" #n ")" ::: "memory")
; #define PG8_WAIT_L(n) asm volatile("s_waitcnt lgkmcnt(" #n ")" ::: "memory")
; #define PG8_BAR __builtin_amdgcn_s_barrier()
; #define PG8_SCHED __builtin_amdgcn_sched_barrier(0)
; __device__ __forceinline__ void gemm_phase(LAS unsigned char* lds, const Params& p, const bf16_t* gA, const bf16_t* gBt, const int gM, const int gN, const int gK, const int epi, const int perm, bf16_t* const Hp, const int goff, const float coef) {
;     ...
;             PG8_LDA(At, 1, 1); PG8_STAGE(PG8_SB(1, 0), b3, voffB); PG8_STAGE(PG8_SB(1, 1), b3 + hstep, voffB); PG8_STAGE(PG8_SA(1, 0), a3, voffA);
;             PG8_WAIT_V(8); PG8_WAIT_L(0); PG8_BAR; PG8_MMA(1, 0, At, B0); PG8_MMA(1, 1, At, B1); PG8_BAR; PG8_SCHED;
;         }
;         if (wr == 0) PG8_BAR;
	s_add_i32 s57, 0, 0x18000
	s_add_i32 s58, 0, 0x1c000
	v_add_u32_e32 v170, s57, v146
	v_add_u32_e32 v186, s58, v146
	ds_read_b128 v[158:161], v170
	ds_read_b128 v[162:165], v170 offset:1024
	ds_read_b128 v[166:169], v170 offset:2048
	ds_read_b128 v[170:173], v170 offset:3072
	ds_read_b128 v[174:177], v186
	ds_read_b128 v[178:181], v186 offset:1024
	ds_read_b128 v[182:185], v186 offset:2048
	ds_read_b128 v[186:189], v186 offset:3072
	s_add_u32 s48, s48, 0x80000
	s_addc_u32 s49, s49, 0
	s_mov_b32 m0, s16
	v_lshl_add_u64 v[228:229], s[48:49], 0, v[128:129]
	ds_read_b128 v[190:193], v157 offset:32768
	ds_read_b128 v[194:197], v157 offset:33792
	ds_read_b128 v[198:201], v157 offset:34816
	ds_read_b128 v[202:205], v157 offset:35840
	ds_read_b128 v[206:209], v157 offset:36864
	ds_read_b128 v[210:213], v157 offset:37888
	ds_read_b128 v[214:217], v157 offset:38912
	ds_read_b128 v[218:221], v157 offset:39936
	global_load_lds_dwordx4 v[228:229], off
	v_lshl_add_u64 v[228:229], s[48:49], 0, v[132:133]
	s_mov_b32 m0, s17
	s_nop 0
	global_load_lds_dwordx4 v[228:229], off
	s_waitcnt vmcnt(8)
	s_waitcnt lgkmcnt(0)
	s_barrier
	s_waitcnt lgkmcnt(0)
	v_mfma_f32_16x16x32_bf16 v[124:127], v[158:161], v[190:193], v[124:127]
	v_mfma_f32_16x16x32_bf16 v[120:123], v[166:169], v[190:193], v[120:123]
	v_mfma_f32_16x16x32_bf16 v[108:111], v[158:161], v[198:201], v[108:111]
	v_mfma_f32_16x16x32_bf16 v[104:107], v[166:169], v[198:201], v[104:107]
	v_mfma_f32_16x16x32_bf16 v[92:95], v[158:161], v[206:209], v[92:95]
	v_mfma_f32_16x16x32_bf16 v[88:91], v[166:169], v[206:209], v[88:91]
	v_mfma_f32_16x16x32_bf16 v[76:79], v[158:161], v[214:217], v[76:79]
	v_mfma_f32_16x16x32_bf16 v[72:75], v[166:169], v[214:217], v[72:75]
	v_mfma_f32_16x16x32_bf16 v[124:127], v[162:165], v[194:197], v[124:127]
	v_mfma_f32_16x16x32_bf16 v[120:123], v[170:173], v[194:197], v[120:123]
	v_mfma_f32_16x16x32_bf16 v[108:111], v[162:165], v[202:205], v[108:111]
	v_mfma_f32_16x16x32_bf16 v[104:107], v[170:173], v[202:205], v[104:107]
	v_mfma_f32_16x16x32_bf16 v[92:95], v[162:165], v[210:213], v[92:95]
	v_mfma_f32_16x16x32_bf16 v[88:91], v[170:173], v[210:213], v[88:91]
	v_mfma_f32_16x16x32_bf16 v[76:79], v[162:165], v[218:221], v[76:79]
	v_mfma_f32_16x16x32_bf16 v[72:75], v[170:173], v[218:221], v[72:75]
	v_mfma_f32_16x16x32_bf16 v[116:119], v[174:177], v[190:193], v[116:119]
	v_mfma_f32_16x16x32_bf16 v[112:115], v[182:185], v[190:193], v[112:115]
	v_mfma_f32_16x16x32_bf16 v[100:103], v[174:177], v[198:201], v[100:103]
	v_mfma_f32_16x16x32_bf16 v[96:99], v[182:185], v[198:201], v[96:99]
	v_mfma_f32_16x16x32_bf16 v[84:87], v[174:177], v[206:209], v[84:87]
	v_mfma_f32_16x16x32_bf16 v[80:83], v[182:185], v[206:209], v[80:83]
	v_mfma_f32_16x16x32_bf16 v[68:71], v[174:177], v[214:217], v[68:71]
	v_mfma_f32_16x16x32_bf16 v[64:67], v[182:185], v[214:217], v[64:67]
	v_mfma_f32_16x16x32_bf16 v[116:119], v[178:181], v[194:197], v[116:119]
	v_mfma_f32_16x16x32_bf16 v[112:115], v[186:189], v[194:197], v[112:115]
	v_mfma_f32_16x16x32_bf16 v[100:103], v[178:181], v[202:205], v[100:103]
	v_mfma_f32_16x16x32_bf16 v[96:99], v[186:189], v[202:205], v[96:99]
	v_mfma_f32_16x16x32_bf16 v[84:87], v[178:181], v[210:213], v[84:87]
	v_mfma_f32_16x16x32_bf16 v[80:83], v[186:189], v[210:213], v[80:83]
	v_mfma_f32_16x16x32_bf16 v[68:71], v[178:181], v[218:221], v[68:71]
	v_mfma_f32_16x16x32_bf16 v[64:67], v[186:189], v[218:221], v[64:67]
	s_barrier
	s_add_i32 s48, s57, s11
	v_lshl_add_u64 v[144:145], v[144:145], 0, s[8:9]
	s_mov_b32 m0, s48
	ds_read_b128 v[190:193], v157 offset:49152
	ds_read_b128 v[194:197], v157 offset:50176
	ds_read_b128 v[198:201], v157 offset:51200
	ds_read_b128 v[202:205], v157 offset:52224
	ds_read_b128 v[206:209], v157 offset:53248
	ds_read_b128 v[210:213], v157 offset:54272
	ds_read_b128 v[214:217], v157 offset:55296
	ds_read_b128 v[218:221], v157 offset:56320
	global_load_lds_dwordx4 v[144:145], off
	s_add_i32 m0, s48, 0x2000
	s_add_u32 s46, s46, 0x80080
	v_lshl_add_u64 v[144:145], v[222:223], 0, s[8:9]
	s_addc_u32 s47, s47, 0
	s_add_i32 s48, s58, s11
	global_load_lds_dwordx4 v[144:145], off
	v_lshl_add_u64 v[144:145], s[46:47], 0, v[130:131]
	s_mov_b32 m0, s48
	s_nop 0
	global_load_lds_dwordx4 v[144:145], off
	v_lshl_add_u64 v[144:145], s[46:47], 0, v[134:135]
	s_add_i32 m0, s48, 0x2000
	s_nop 0
	global_load_lds_dwordx4 v[144:145], off
	v_lshl_add_u64 v[144:145], v[224:225], 0, s[8:9]
	s_mov_b32 m0, s19
	s_nop 0
	global_load_lds_dwordx4 v[144:145], off
	v_lshl_add_u64 v[144:145], v[226:227], 0, s[8:9]
	s_mov_b32 m0, s20
	s_nop 0
	global_load_lds_dwordx4 v[144:145], off
	s_waitcnt vmcnt(8)
	s_waitcnt lgkmcnt(0)
	s_barrier
	s_waitcnt lgkmcnt(0)
	v_mfma_f32_16x16x32_bf16 v[60:63], v[158:161], v[190:193], v[60:63]
	v_mfma_f32_16x16x32_bf16 v[56:59], v[166:169], v[190:193], v[56:59]
	v_mfma_f32_16x16x32_bf16 v[44:47], v[158:161], v[198:201], v[44:47]
	v_mfma_f32_16x16x32_bf16 v[40:43], v[166:169], v[198:201], v[40:43]
	v_mfma_f32_16x16x32_bf16 v[28:31], v[158:161], v[206:209], v[28:31]
	v_mfma_f32_16x16x32_bf16 v[24:27], v[166:169], v[206:209], v[24:27]
	v_mfma_f32_16x16x32_bf16 v[12:15], v[158:161], v[214:217], v[12:15]
	v_mfma_f32_16x16x32_bf16 v[8:11], v[166:169], v[214:217], v[8:11]
	v_mfma_f32_16x16x32_bf16 v[60:63], v[162:165], v[194:197], v[60:63]
	v_mfma_f32_16x16x32_bf16 v[56:59], v[170:173], v[194:197], v[56:59]
	v_mfma_f32_16x16x32_bf16 v[44:47], v[162:165], v[202:205], v[44:47]
	v_mfma_f32_16x16x32_bf16 v[40:43], v[170:173], v[202:205], v[40:43]
	v_mfma_f32_16x16x32_bf16 v[28:31], v[162:165], v[210:213], v[28:31]
	v_mfma_f32_16x16x32_bf16 v[24:27], v[170:173], v[210:213], v[24:27]
	v_mfma_f32_16x16x32_bf16 v[12:15], v[162:165], v[218:221], v[12:15]
	v_mfma_f32_16x16x32_bf16 v[8:11], v[170:173], v[218:221], v[8:11]
	v_mfma_f32_16x16x32_bf16 v[52:55], v[174:177], v[190:193], v[52:55]
	v_mfma_f32_16x16x32_bf16 v[48:51], v[182:185], v[190:193], v[48:51]
	v_mfma_f32_16x16x32_bf16 v[36:39], v[174:177], v[198:201], v[36:39]
	v_mfma_f32_16x16x32_bf16 v[32:35], v[182:185], v[198:201], v[32:35]
	v_mfma_f32_16x16x32_bf16 v[20:23], v[174:177], v[206:209], v[20:23]
	v_mfma_f32_16x16x32_bf16 v[16:19], v[182:185], v[206:209], v[16:19]
	v_mfma_f32_16x16x32_bf16 v[4:7], v[174:177], v[214:217], v[4:7]
	v_mfma_f32_16x16x32_bf16 v[0:3], v[182:185], v[214:217], v[0:3]
	v_mfma_f32_16x16x32_bf16 v[52:55], v[178:181], v[194:197], v[52:55]
	v_mfma_f32_16x16x32_bf16 v[48:51], v[186:189], v[194:197], v[48:51]
	v_mfma_f32_16x16x32_bf16 v[36:39], v[178:181], v[202:205], v[36:39]
	v_mfma_f32_16x16x32_bf16 v[32:35], v[186:189], v[202:205], v[32:35]
	v_mfma_f32_16x16x32_bf16 v[20:23], v[178:181], v[210:213], v[20:23]
	v_mfma_f32_16x16x32_bf16 v[16:19], v[186:189], v[210:213], v[16:19]
	v_mfma_f32_16x16x32_bf16 v[4:7], v[178:181], v[218:221], v[4:7]
	v_mfma_f32_16x16x32_bf16 v[0:3], v[186:189], v[218:221], v[0:3]
	s_barrier
	s_add_u32 s44, s44, 0x100
	s_addc_u32 s45, s45, 0
	s_add_u32 s54, s54, 0x100
	s_addc_u32 s55, s55, 0
	s_cmp_ge_u32 s56, s52
	s_mov_b32 s48, s56
	s_cbranch_scc0 .LBB0_170
; #define PG8_BAR __builtin_amdgcn_s_barrier()
; __device__ __forceinline__ void gemm_phase(LAS unsigned char* lds, const Params& p, const bf16_t* gA, const bf16_t* gBt, const int gM, const int gN, const int gK, const int epi, const int perm, bf16_t* const Hp, const int goff, const float coef) {
;     ...
;         if (wr == 0) PG8_BAR;
;         gemm_epilogue(p, epi, Hp, goff, coef, acc, cur, wr, wc, fr, fq);
.Lpeel_exit_0:
	s_and_b64 vcc, exec, s[12:13]
	s_cbranch_vccz .LBB0_173
	s_barrier

; #define PG8_STAGE(bufoff, gbase, voff) do { _Pragma("unroll") for (int _i = 0; _i < 2; ++_i) \
;         __builtin_amdgcn_global_load_lds((const unsigned*)((const char*)(gbase) + (voff)[_i]), (LAS unsigned*)(lds + (bufoff) + ldsw + _i * 8192), 16, 0, 0); } while (0)
; #define PG8_LDA(dst, b, h) do { _Pragma("unroll") for (int m = 0; m < 4; ++m) _Pragma("unroll") for (int k = 0; k < 2; ++k) dst[m][k] = *(const LAS bf16x8*)(lds + PG8_SA(b, h) + aoff + m * 2048 + k * 1024); } while (0)
; #define PG8_LDB(dst, b, h) do { _Pragma("unroll") for (int n = 0; n < 2; ++n) _Pragma("unroll") for (int k = 0; k < 2; ++k) dst[n][k] = *(const LAS bf16x8*)(lds + PG8_SB(b, h) + boff + n * 2048 + k * 1024); } while (0)
; #define PG8_MMA(ai, bj, At, Bt) do { __builtin_amdgcn_s_setprio(1); _Pragma("unroll") for (int m = 0; m < 4; ++m) _Pragma("unroll") for (int n = 0; n < 2; ++n) _Pragma("unroll") for (int k = 0; k < 2; ++k) \
;         acc[ai][bj][m][n] = __builtin_amdgcn_mfma_f32_16x16x32_bf16(Bt[n][k], At[m][k], acc[ai][bj][m][n], 0, 0, 0); __builtin_amdgcn_s_setprio(0); } while (0)
; #define PG8_WAIT_V(n) asm volatile("s_waitcnt vmcnt(" #n ")" ::: "memory")
; #define PG8_WAIT_L(n) asm volatile("s_waitcnt lgkmcnt(" #n ")" ::: "memory")
; #define PG8_BAR __builtin_amdgcn_s_barrier()
; #define PG8_SCHED __builtin_amdgcn_sched_barrier(0)
; __device__ __forceinline__ void gemm_phase(LAS unsigned char* lds, const Params& p, const bf16_t* gA, const bf16_t* gBt, const int gM, const int gN, const int gK, const int epi, const int perm, bf16_t* const Hp, const int goff, const float coef) {
;     ...
;         const int nt = cur.ks >= 0 ? ntf / 4 : ntf;
;         for (int t = 0; t < nt; t += 2) {
;             const bool last = (t == nt - 2);
;             const char* a1 = cA + (size_t)(t + 1) * kstep;
;             const char* a2 = last ? nA : cA + (size_t)(t + 2) * kstep; const char* b2 = last ? nB : cB + (size_t)(t + 2) * kstep;
;             const char* a3 = a2 + kstep; const char* b3 = b2 + kstep;
;             PG8_LDB(B0, 0, 0); PG8_LDB(B1, 0, 1); PG8_SCHED; PG8_LDA(At, 0, 0); PG8_STAGE(PG8_SA(1, 1), a1 + hstep, voffA);
;             PG8_WAIT_V(8); PG8_WAIT_L(0); PG8_BAR; PG8_MMA(0, 0, At, B0); PG8_MMA(0, 1, At, B1); PG8_BAR; PG8_SCHED;
.LBB0_263:
	s_cmp_gt_i32 s6, -1
	s_cselect_b64 s[4:5], -1, 0
	s_and_b64 s[38:39], s[4:5], exec
	s_cselect_b32 s54, 22, 0x58
	s_add_i32 s55, s54, -2
	s_add_u32 s30, s30, 0x160080
	s_addc_u32 s31, s31, 0
	s_add_u32 s56, s34, 0x100
	s_addc_u32 s57, s35, 0
	s_mov_b32 s34, 0
	ds_read_b128 v[146:149], v167
	ds_read_b128 v[150:153], v167 offset:1024
	ds_read_b128 v[154:157], v167 offset:2048
	ds_read_b128 v[170:173], v167 offset:3072
	ds_read_b128 v[174:177], v168
	ds_read_b128 v[178:181], v168 offset:1024
	ds_read_b128 v[182:185], v168 offset:2048
	ds_read_b128 v[186:189], v168 offset:3072
	s_add_i32 s58, s34, 2
	s_add_u32 s35, s30, 0xffea0080
	s_addc_u32 s38, s31, -1
	s_cmp_eq_u32 s55, s34
	s_cselect_b32 s34, s28, s56
	s_cselect_b32 s39, s27, s38
	s_cselect_b32 s38, s26, s35
	s_cselect_b32 s35, s29, s57
	v_lshl_add_u64 v[222:223], s[30:31], 0, v[136:137]
	s_add_i32 m0, s17, 0xc000
	ds_read_b128 v[190:193], v169
	ds_read_b128 v[194:197], v169 offset:1024
	ds_read_b128 v[198:201], v169 offset:2048
	ds_read_b128 v[202:205], v169 offset:3072
	ds_read_b128 v[206:209], v169 offset:4096
	ds_read_b128 v[210:213], v169 offset:5120
	ds_read_b128 v[214:217], v169 offset:6144
	ds_read_b128 v[218:221], v169 offset:7168
	global_load_lds_dwordx4 v[222:223], off
	v_lshl_add_u64 v[222:223], s[30:31], 0, v[138:139]
	s_add_i32 m0, s17, 0xe000
	s_nop 0
	global_load_lds_dwordx4 v[222:223], off
	s_waitcnt vmcnt(8)
	s_waitcnt lgkmcnt(0)
	s_barrier
	s_waitcnt lgkmcnt(0)
	v_mfma_f32_16x16x32_bf16 v[124:127], v[146:149], v[190:193], 0
	v_mfma_f32_16x16x32_bf16 v[120:123], v[154:157], v[190:193], 0
	v_mfma_f32_16x16x32_bf16 v[116:119], v[146:149], v[198:201], 0
	v_mfma_f32_16x16x32_bf16 v[112:115], v[154:157], v[198:201], 0
	v_mfma_f32_16x16x32_bf16 v[108:111], v[146:149], v[206:209], 0
	v_mfma_f32_16x16x32_bf16 v[104:107], v[154:157], v[206:209], 0
	v_mfma_f32_16x16x32_bf16 v[100:103], v[146:149], v[214:217], 0
	v_mfma_f32_16x16x32_bf16 v[96:99], v[154:157], v[214:217], 0
	v_mfma_f32_16x16x32_bf16 v[124:127], v[150:153], v[194:197], v[124:127]
	v_mfma_f32_16x16x32_bf16 v[120:123], v[170:173], v[194:197], v[120:123]
	v_mfma_f32_16x16x32_bf16 v[116:119], v[150:153], v[202:205], v[116:119]
	v_mfma_f32_16x16x32_bf16 v[112:115], v[170:173], v[202:205], v[112:115]
	v_mfma_f32_16x16x32_bf16 v[108:111], v[150:153], v[210:213], v[108:111]
	v_mfma_f32_16x16x32_bf16 v[104:107], v[170:173], v[210:213], v[104:107]
	v_mfma_f32_16x16x32_bf16 v[100:103], v[150:153], v[218:221], v[100:103]
	v_mfma_f32_16x16x32_bf16 v[96:99], v[170:173], v[218:221], v[96:99]
	v_mfma_f32_16x16x32_bf16 v[68:71], v[174:177], v[190:193], 0
	v_mfma_f32_16x16x32_bf16 v[60:63], v[182:185], v[190:193], 0
	v_mfma_f32_16x16x32_bf16 v[52:55], v[174:177], v[198:201], 0
	v_mfma_f32_16x16x32_bf16 v[48:51], v[182:185], v[198:201], 0
	v_mfma_f32_16x16x32_bf16 v[44:47], v[174:177], v[206:209], 0
	v_mfma_f32_16x16x32_bf16 v[40:43], v[182:185], v[206:209], 0
	v_mfma_f32_16x16x32_bf16 v[36:39], v[174:177], v[214:217], 0
	v_mfma_f32_16x16x32_bf16 v[32:35], v[182:185], v[214:217], 0
	v_mfma_f32_16x16x32_bf16 v[68:71], v[178:181], v[194:197], v[68:71]
	v_mfma_f32_16x16x32_bf16 v[60:63], v[186:189], v[194:197], v[60:63]
	v_mfma_f32_16x16x32_bf16 v[52:55], v[178:181], v[202:205], v[52:55]
	v_mfma_f32_16x16x32_bf16 v[48:51], v[186:189], v[202:205], v[48:51]
	v_mfma_f32_16x16x32_bf16 v[44:47], v[178:181], v[210:213], v[44:47]
	v_mfma_f32_16x16x32_bf16 v[40:43], v[186:189], v[210:213], v[40:43]
	v_mfma_f32_16x16x32_bf16 v[36:39], v[178:181], v[218:221], v[36:39]
	v_mfma_f32_16x16x32_bf16 v[32:35], v[186:189], v[218:221], v[32:35]
	s_barrier
	s_add_i32 s59, s46, s16
	v_lshl_add_u64 v[222:223], s[34:35], 0, v[130:131]
	s_mov_b32 m0, s59
	ds_read_b128 v[190:193], v169 offset:16384
	ds_read_b128 v[194:197], v169 offset:17408
	ds_read_b128 v[198:201], v169 offset:18432
	ds_read_b128 v[202:205], v169 offset:19456
	ds_read_b128 v[206:209], v169 offset:20480
	ds_read_b128 v[210:213], v169 offset:21504
	ds_read_b128 v[214:217], v169 offset:22528
	ds_read_b128 v[218:221], v169 offset:23552
	global_load_lds_dwordx4 v[222:223], off
	s_add_i32 m0, s59, 0x2000
	s_add_u32 s60, s34, 0x160000
	v_lshl_add_u64 v[224:225], s[34:35], 0, v[134:135]
	s_addc_u32 s61, s35, 0
	s_add_i32 s59, s47, s16
	global_load_lds_dwordx4 v[224:225], off
	v_lshl_add_u64 v[226:227], s[60:61], 0, v[130:131]
	s_mov_b32 m0, s59
	v_lshl_add_u64 v[228:229], s[38:39], 0, v[132:133]
	global_load_lds_dwordx4 v[226:227], off
	v_lshl_add_u64 v[226:227], s[60:61], 0, v[134:135]
	s_add_i32 m0, s59, 0x2000
	s_nop 0
	global_load_lds_dwordx4 v[226:227], off
	v_lshl_add_u64 v[226:227], s[38:39], 0, v[128:129]
	s_mov_b32 m0, s17
	s_nop 0
	global_load_lds_dwordx4 v[226:227], off
	s_mov_b32 m0, s18
	s_nop 0
	global_load_lds_dwordx4 v[228:229], off
	s_waitcnt vmcnt(8)
	s_waitcnt lgkmcnt(0)
	s_barrier
; #define PG8_STAGE(bufoff, gbase, voff) do { _Pragma("unroll") for (int _i = 0; _i < 2; ++_i) \
;         __builtin_amdgcn_global_load_lds((const unsigned*)((const char*)(gbase) + (voff)[_i]), (LAS unsigned*)(lds + (bufoff) + ldsw + _i * 8192), 16, 0, 0); } while (0)
; #define PG8_LDA(dst, b, h) do { _Pragma("unroll") for (int m = 0; m < 4; ++m) _Pragma("unroll") for (int k = 0; k < 2; ++k) dst[m][k] = *(const LAS bf16x8*)(lds + PG8_SA(b, h) + aoff + m * 2048 + k * 1024); } while (0)
; #define PG8_LDB(dst, b, h) do { _Pragma("unroll") for (int n = 0; n < 2; ++n) _Pragma("unroll") for (int k = 0; k < 2; ++k) dst[n][k] = *(const LAS bf16x8*)(lds + PG8_SB(b, h) + boff + n * 2048 + k * 1024); } while (0)
; #define PG8_MMA(ai, bj, At, Bt) do { __builtin_amdgcn_s_setprio(1); _Pragma("unroll") for (int m = 0; m < 4; ++m) _Pragma("unroll") for (int n = 0; n < 2; ++n) _Pragma("unroll") for (int k = 0; k < 2; ++k) \
;         acc[ai][bj][m][n] = __builtin_amdgcn_mfma_f32_16x16x32_bf16(Bt[n][k], At[m][k], acc[ai][bj][m][n], 0, 0, 0); __builtin_amdgcn_s_setprio(0); } while (0)
; #define PG8_WAIT_V(n) asm volatile("s_waitcnt vmcnt(" #n ")" ::: "memory")
; #define PG8_WAIT_L(n) asm volatile("s_waitcnt lgkmcnt(" #n ")" ::: "memory")
; #define PG8_BAR __builtin_amdgcn_s_barrier()
; #define PG8_SCHED __builtin_amdgcn_sched_barrier(0)
; __device__ __forceinline__ void gemm_phase(LAS unsigned char* lds, const Params& p, const bf16_t* gA, const bf16_t* gBt, const int gM, const int gN, const int gK, const int epi, const int perm, bf16_t* const Hp, const int goff, const float coef) {
;     ...
;             PG8_WAIT_V(8); PG8_WAIT_L(0); PG8_BAR; PG8_MMA(0, 0, At, B0); PG8_MMA(0, 1, At, B1); PG8_BAR; PG8_SCHED;
;             PG8_LDA(At, 0, 1); PG8_STAGE(PG8_SB(0, 0), b2, voffB); PG8_STAGE(PG8_SB(0, 1), b2 + hstep, voffB); PG8_STAGE(PG8_SA(0, 0), a2, voffA);
;             PG8_WAIT_V(8); PG8_WAIT_L(0); PG8_BAR; PG8_MMA(1, 0, At, B0); PG8_MMA(1, 1, At, B1); PG8_BAR; PG8_SCHED;
;             PG8_LDB(B0, 1, 0); PG8_LDB(B1, 1, 1); PG8_SCHED; PG8_LDA(At, 1, 0); PG8_STAGE(PG8_SA(0, 1), a2 + hstep, voffA);
;             PG8_WAIT_V(8); PG8_WAIT_L(0); PG8_BAR; PG8_MMA(0, 0, At, B0); PG8_MMA(0, 1, At, B1); PG8_BAR; PG8_SCHED;
	s_waitcnt lgkmcnt(0)
	v_mfma_f32_16x16x32_bf16 v[92:95], v[146:149], v[190:193], 0
	v_mfma_f32_16x16x32_bf16 v[88:91], v[154:157], v[190:193], 0
	v_mfma_f32_16x16x32_bf16 v[84:87], v[146:149], v[198:201], 0
	v_mfma_f32_16x16x32_bf16 v[80:83], v[154:157], v[198:201], 0
	v_mfma_f32_16x16x32_bf16 v[76:79], v[146:149], v[206:209], 0
	v_mfma_f32_16x16x32_bf16 v[72:75], v[154:157], v[206:209], 0
	v_mfma_f32_16x16x32_bf16 v[64:67], v[146:149], v[214:217], 0
	v_mfma_f32_16x16x32_bf16 v[56:59], v[154:157], v[214:217], 0
	v_mfma_f32_16x16x32_bf16 v[92:95], v[150:153], v[194:197], v[92:95]
	v_mfma_f32_16x16x32_bf16 v[88:91], v[170:173], v[194:197], v[88:91]
	v_mfma_f32_16x16x32_bf16 v[84:87], v[150:153], v[202:205], v[84:87]
	v_mfma_f32_16x16x32_bf16 v[80:83], v[170:173], v[202:205], v[80:83]
	v_mfma_f32_16x16x32_bf16 v[76:79], v[150:153], v[210:213], v[76:79]
	v_mfma_f32_16x16x32_bf16 v[72:75], v[170:173], v[210:213], v[72:75]
	v_mfma_f32_16x16x32_bf16 v[64:67], v[150:153], v[218:221], v[64:67]
	v_mfma_f32_16x16x32_bf16 v[56:59], v[170:173], v[218:221], v[56:59]
	v_mfma_f32_16x16x32_bf16 v[28:31], v[174:177], v[190:193], 0
	v_mfma_f32_16x16x32_bf16 v[24:27], v[182:185], v[190:193], 0
	v_mfma_f32_16x16x32_bf16 v[20:23], v[174:177], v[198:201], 0
	v_mfma_f32_16x16x32_bf16 v[16:19], v[182:185], v[198:201], 0
	v_mfma_f32_16x16x32_bf16 v[12:15], v[174:177], v[206:209], 0
	v_mfma_f32_16x16x32_bf16 v[8:11], v[182:185], v[206:209], 0
	v_mfma_f32_16x16x32_bf16 v[4:7], v[174:177], v[214:217], 0
	v_mfma_f32_16x16x32_bf16 v[0:3], v[182:185], v[214:217], 0
	v_mfma_f32_16x16x32_bf16 v[28:31], v[178:181], v[194:197], v[28:31]
	v_mfma_f32_16x16x32_bf16 v[24:27], v[186:189], v[194:197], v[24:27]
	v_mfma_f32_16x16x32_bf16 v[20:23], v[178:181], v[202:205], v[20:23]
	v_mfma_f32_16x16x32_bf16 v[16:19], v[186:189], v[202:205], v[16:19]
	v_mfma_f32_16x16x32_bf16 v[12:15], v[178:181], v[210:213], v[12:15]
	v_mfma_f32_16x16x32_bf16 v[8:11], v[186:189], v[210:213], v[8:11]
	v_mfma_f32_16x16x32_bf16 v[4:7], v[178:181], v[218:221], v[4:7]
	v_mfma_f32_16x16x32_bf16 v[0:3], v[186:189], v[218:221], v[0:3]
	s_barrier
	s_add_i32 s59, 0, 0x18000
	s_add_i32 s60, 0, 0x1c000
	v_add_u32_e32 v170, s59, v158
	v_add_u32_e32 v186, s60, v158
	ds_read_b128 v[146:149], v170
	ds_read_b128 v[150:153], v170 offset:1024
	ds_read_b128 v[154:157], v170 offset:2048
	ds_read_b128 v[170:173], v170 offset:3072
	ds_read_b128 v[174:177], v186
	ds_read_b128 v[178:181], v186 offset:1024
	ds_read_b128 v[182:185], v186 offset:2048
	ds_read_b128 v[186:189], v186 offset:3072
	s_add_u32 s38, s38, 0x160000
	s_addc_u32 s39, s39, 0
	s_mov_b32 m0, s19
	v_lshl_add_u64 v[230:231], s[38:39], 0, v[128:129]
	ds_read_b128 v[190:193], v169 offset:32768
	ds_read_b128 v[194:197], v169 offset:33792
	ds_read_b128 v[198:201], v169 offset:34816
	ds_read_b128 v[202:205], v169 offset:35840
	ds_read_b128 v[206:209], v169 offset:36864
	ds_read_b128 v[210:213], v169 offset:37888
	ds_read_b128 v[214:217], v169 offset:38912
	ds_read_b128 v[218:221], v169 offset:39936
	global_load_lds_dwordx4 v[230:231], off
	v_lshl_add_u64 v[230:231], s[38:39], 0, v[132:133]
	s_mov_b32 m0, s20
	s_nop 0
	global_load_lds_dwordx4 v[230:231], off
	s_waitcnt vmcnt(8)
	s_waitcnt lgkmcnt(0)
	s_barrier
	s_waitcnt lgkmcnt(0)
	v_mfma_f32_16x16x32_bf16 v[124:127], v[146:149], v[190:193], v[124:127]
	v_mfma_f32_16x16x32_bf16 v[120:123], v[154:157], v[190:193], v[120:123]
	v_mfma_f32_16x16x32_bf16 v[116:119], v[146:149], v[198:201], v[116:119]
	v_mfma_f32_16x16x32_bf16 v[112:115], v[154:157], v[198:201], v[112:115]
	v_mfma_f32_16x16x32_bf16 v[108:111], v[146:149], v[206:209], v[108:111]
	v_mfma_f32_16x16x32_bf16 v[104:107], v[154:157], v[206:209], v[104:107]
	v_mfma_f32_16x16x32_bf16 v[100:103], v[146:149], v[214:217], v[100:103]
	v_mfma_f32_16x16x32_bf16 v[96:99], v[154:157], v[214:217], v[96:99]
	v_mfma_f32_16x16x32_bf16 v[124:127], v[150:153], v[194:197], v[124:127]
	v_mfma_f32_16x16x32_bf16 v[120:123], v[170:173], v[194:197], v[120:123]
	v_mfma_f32_16x16x32_bf16 v[116:119], v[150:153], v[202:205], v[116:119]
	v_mfma_f32_16x16x32_bf16 v[112:115], v[170:173], v[202:205], v[112:115]
	v_mfma_f32_16x16x32_bf16 v[108:111], v[150:153], v[210:213], v[108:111]
	v_mfma_f32_16x16x32_bf16 v[104:107], v[170:173], v[210:213], v[104:107]
	v_mfma_f32_16x16x32_bf16 v[100:103], v[150:153], v[218:221], v[100:103]
	v_mfma_f32_16x16x32_bf16 v[96:99], v[170:173], v[218:221], v[96:99]
	v_mfma_f32_16x16x32_bf16 v[68:71], v[174:177], v[190:193], v[68:71]
	v_mfma_f32_16x16x32_bf16 v[60:63], v[182:185], v[190:193], v[60:63]
	v_mfma_f32_16x16x32_bf16 v[52:55], v[174:177], v[198:201], v[52:55]
	v_mfma_f32_16x16x32_bf16 v[48:51], v[182:185], v[198:201], v[48:51]
	v_mfma_f32_16x16x32_bf16 v[44:47], v[174:177], v[206:209], v[44:47]
	v_mfma_f32_16x16x32_bf16 v[40:43], v[182:185], v[206:209], v[40:43]
	v_mfma_f32_16x16x32_bf16 v[36:39], v[174:177], v[214:217], v[36:39]
	v_mfma_f32_16x16x32_bf16 v[32:35], v[182:185], v[214:217], v[32:35]
	v_mfma_f32_16x16x32_bf16 v[68:71], v[178:181], v[194:197], v[68:71]
	v_mfma_f32_16x16x32_bf16 v[60:63], v[186:189], v[194:197], v[60:63]
	v_mfma_f32_16x16x32_bf16 v[52:55], v[178:181], v[202:205], v[52:55]
	v_mfma_f32_16x16x32_bf16 v[48:51], v[186:189], v[202:205], v[48:51]
	v_mfma_f32_16x16x32_bf16 v[44:47], v[178:181], v[210:213], v[44:47]
	v_mfma_f32_16x16x32_bf16 v[40:43], v[186:189], v[210:213], v[40:43]
	v_mfma_f32_16x16x32_bf16 v[36:39], v[178:181], v[218:221], v[36:39]
	v_mfma_f32_16x16x32_bf16 v[32:35], v[186:189], v[218:221], v[32:35]
	s_barrier
; #define PG8_STAGE(bufoff, gbase, voff) do { _Pragma("unroll") for (int _i = 0; _i < 2; ++_i) \
;         __builtin_amdgcn_global_load_lds((const unsigned*)((const char*)(gbase) + (voff)[_i]), (LAS unsigned*)(lds + (bufoff) + ldsw + _i * 8192), 16, 0, 0); } while (0)
; #define PG8_LDA(dst, b, h) do { _Pragma("unroll") for (int m = 0; m < 4; ++m) _Pragma("unroll") for (int k = 0; k < 2; ++k) dst[m][k] = *(const LAS bf16x8*)(lds + PG8_SA(b, h) + aoff + m * 2048 + k * 1024); } while (0)
; #define PG8_LDB(dst, b, h) do { _Pragma("unroll") for (int n = 0; n < 2; ++n) _Pragma("unroll") for (int k = 0; k < 2; ++k) dst[n][k] = *(const LAS bf16x8*)(lds + PG8_SB(b, h) + boff + n * 2048 + k * 1024); } while (0)
; #define PG8_MMA(ai, bj, At, Bt) do { __builtin_amdgcn_s_setprio(1); _Pragma("unroll") for (int m = 0; m < 4; ++m) _Pragma("unroll") for (int n = 0; n < 2; ++n) _Pragma("unroll") for (int k = 0; k < 2; ++k) \
;         acc[ai][bj][m][n] = __builtin_amdgcn_mfma_f32_16x16x32_bf16(Bt[n][k], At[m][k], acc[ai][bj][m][n], 0, 0, 0); __builtin_amdgcn_s_setprio(0); } while (0)
; #define PG8_WAIT_V(n) asm volatile("s_waitcnt vmcnt(" #n ")" ::: "memory")
; #define PG8_WAIT_L(n) asm volatile("s_waitcnt lgkmcnt(" #n ")" ::: "memory")
; __device__ __forceinline__ void gemm_phase(LAS unsigned char* lds, const Params& p, const bf16_t* gA, const bf16_t* gBt, const int gM, const int gN, const int gK, const int epi, const int perm, bf16_t* const Hp, const int goff, const float coef) {
;     ...
;         for (int t = 0; t < nt; t += 2) {
;             const bool last = (t == nt - 2);
;             const char* a1 = cA + (size_t)(t + 1) * kstep;
;             const char* a2 = last ? nA : cA + (size_t)(t + 2) * kstep; const char* b2 = last ? nB : cB + (size_t)(t + 2) * kstep;
;             const char* a3 = a2 + kstep; const char* b3 = b2 + kstep;
;             PG8_LDB(B0, 0, 0); PG8_LDB(B1, 0, 1); PG8_SCHED; PG8_LDA(At, 0, 0); PG8_STAGE(PG8_SA(1, 1), a1 + hstep, voffA);
;             PG8_WAIT_V(8); PG8_WAIT_L(0); PG8_BAR; PG8_MMA(0, 0, At, B0); PG8_MMA(0, 1, At, B1); PG8_BAR; PG8_SCHED;
;     ...
;             PG8_LDA(At, 1, 1); PG8_STAGE(PG8_SB(1, 0), b3, voffB); PG8_STAGE(PG8_SB(1, 1), b3 + hstep, voffB); PG8_STAGE(PG8_SA(1, 0), a3, voffA);
;             PG8_WAIT_V(8); PG8_WAIT_L(0); PG8_BAR; PG8_MMA(1, 0, At, B0); PG8_MMA(1, 1, At, B1); PG8_BAR; PG8_SCHED;
	s_add_i32 s38, s59, s16
	v_lshl_add_u64 v[222:223], v[222:223], 0, s[12:13]
	s_mov_b32 m0, s38
	ds_read_b128 v[190:193], v169 offset:49152
	ds_read_b128 v[194:197], v169 offset:50176
	ds_read_b128 v[198:201], v169 offset:51200
	ds_read_b128 v[202:205], v169 offset:52224
	ds_read_b128 v[206:209], v169 offset:53248
	ds_read_b128 v[210:213], v169 offset:54272
	ds_read_b128 v[214:217], v169 offset:55296
	ds_read_b128 v[218:221], v169 offset:56320
	global_load_lds_dwordx4 v[222:223], off
	s_add_i32 m0, s38, 0x2000
	s_add_u32 s34, s34, 0x160080
	v_lshl_add_u64 v[222:223], v[224:225], 0, s[12:13]
	s_addc_u32 s35, s35, 0
	s_add_i32 s38, s60, s16
	global_load_lds_dwordx4 v[222:223], off
	v_lshl_add_u64 v[222:223], s[34:35], 0, v[130:131]
	s_mov_b32 m0, s38
	s_nop 0
	global_load_lds_dwordx4 v[222:223], off
	v_lshl_add_u64 v[222:223], s[34:35], 0, v[134:135]
	s_add_i32 m0, s38, 0x2000
	s_nop 0
	global_load_lds_dwordx4 v[222:223], off
	v_lshl_add_u64 v[222:223], v[226:227], 0, s[12:13]
	s_mov_b32 m0, s23
	s_nop 0
	global_load_lds_dwordx4 v[222:223], off
	v_lshl_add_u64 v[222:223], v[228:229], 0, s[12:13]
	s_mov_b32 m0, s33
	s_nop 0
	global_load_lds_dwordx4 v[222:223], off
	s_waitcnt vmcnt(8)
	s_waitcnt lgkmcnt(0)
	s_barrier
	s_waitcnt lgkmcnt(0)
	v_mfma_f32_16x16x32_bf16 v[92:95], v[146:149], v[190:193], v[92:95]
	v_mfma_f32_16x16x32_bf16 v[88:91], v[154:157], v[190:193], v[88:91]
	v_mfma_f32_16x16x32_bf16 v[84:87], v[146:149], v[198:201], v[84:87]
	v_mfma_f32_16x16x32_bf16 v[80:83], v[154:157], v[198:201], v[80:83]
	v_mfma_f32_16x16x32_bf16 v[76:79], v[146:149], v[206:209], v[76:79]
	v_mfma_f32_16x16x32_bf16 v[72:75], v[154:157], v[206:209], v[72:75]
	v_mfma_f32_16x16x32_bf16 v[64:67], v[146:149], v[214:217], v[64:67]
	v_mfma_f32_16x16x32_bf16 v[56:59], v[154:157], v[214:217], v[56:59]
	v_mfma_f32_16x16x32_bf16 v[92:95], v[150:153], v[194:197], v[92:95]
	v_mfma_f32_16x16x32_bf16 v[88:91], v[170:173], v[194:197], v[88:91]
	v_mfma_f32_16x16x32_bf16 v[84:87], v[150:153], v[202:205], v[84:87]
	v_mfma_f32_16x16x32_bf16 v[80:83], v[170:173], v[202:205], v[80:83]
	v_mfma_f32_16x16x32_bf16 v[76:79], v[150:153], v[210:213], v[76:79]
	v_mfma_f32_16x16x32_bf16 v[72:75], v[170:173], v[210:213], v[72:75]
	v_mfma_f32_16x16x32_bf16 v[64:67], v[150:153], v[218:221], v[64:67]
	v_mfma_f32_16x16x32_bf16 v[56:59], v[170:173], v[218:221], v[56:59]
	v_mfma_f32_16x16x32_bf16 v[28:31], v[174:177], v[190:193], v[28:31]
	v_mfma_f32_16x16x32_bf16 v[24:27], v[182:185], v[190:193], v[24:27]
	v_mfma_f32_16x16x32_bf16 v[20:23], v[174:177], v[198:201], v[20:23]
	v_mfma_f32_16x16x32_bf16 v[16:19], v[182:185], v[198:201], v[16:19]
	v_mfma_f32_16x16x32_bf16 v[12:15], v[174:177], v[206:209], v[12:15]
	v_mfma_f32_16x16x32_bf16 v[8:11], v[182:185], v[206:209], v[8:11]
	v_mfma_f32_16x16x32_bf16 v[4:7], v[174:177], v[214:217], v[4:7]
	v_mfma_f32_16x16x32_bf16 v[0:3], v[182:185], v[214:217], v[0:3]
	v_mfma_f32_16x16x32_bf16 v[28:31], v[178:181], v[194:197], v[28:31]
	v_mfma_f32_16x16x32_bf16 v[24:27], v[186:189], v[194:197], v[24:27]
	v_mfma_f32_16x16x32_bf16 v[20:23], v[178:181], v[202:205], v[20:23]
	v_mfma_f32_16x16x32_bf16 v[16:19], v[186:189], v[202:205], v[16:19]
	v_mfma_f32_16x16x32_bf16 v[12:15], v[178:181], v[210:213], v[12:15]
	v_mfma_f32_16x16x32_bf16 v[8:11], v[186:189], v[210:213], v[8:11]
	v_mfma_f32_16x16x32_bf16 v[4:7], v[178:181], v[218:221], v[4:7]
	v_mfma_f32_16x16x32_bf16 v[0:3], v[186:189], v[218:221], v[0:3]
	s_barrier
	s_add_u32 s30, s30, 0x100
	s_addc_u32 s31, s31, 0
	s_add_u32 s56, s56, 0x100
	s_addc_u32 s57, s57, 0
	s_cmp_ge_u32 s58, s54
	s_mov_b32 s34, s58
	s_cbranch_scc1 .Lpeel_exit_1
.LBB0_264:
	ds_read_b128 v[146:149], v167
	ds_read_b128 v[150:153], v167 offset:1024
	ds_read_b128 v[154:157], v167 offset:2048
	ds_read_b128 v[170:173], v167 offset:3072
	ds_read_b128 v[174:177], v168
	ds_read_b128 v[178:181], v168 offset:1024
	ds_read_b128 v[182:185], v168 offset:2048
	ds_read_b128 v[186:189], v168 offset:3072
	s_add_i32 s58, s34, 2
	s_add_u32 s35, s30, 0xffea0080
	s_addc_u32 s38, s31, -1
	s_cmp_eq_u32 s55, s34
	s_cselect_b32 s34, s28, s56
	s_cselect_b32 s39, s27, s38
	s_cselect_b32 s38, s26, s35
	s_cselect_b32 s35, s29, s57
	v_lshl_add_u64 v[222:223], s[30:31], 0, v[136:137]
	s_add_i32 m0, s17, 0xc000
	ds_read_b128 v[190:193], v169
	ds_read_b128 v[194:197], v169 offset:1024
	ds_read_b128 v[198:201], v169 offset:2048
	ds_read_b128 v[202:205], v169 offset:3072
	ds_read_b128 v[206:209], v169 offset:4096
	ds_read_b128 v[210:213], v169 offset:5120
	ds_read_b128 v[214:217], v169 offset:6144
	ds_read_b128 v[218:221], v169 offset:7168
	global_load_lds_dwordx4 v[222:223], off
	v_lshl_add_u64 v[222:223], s[30:31], 0, v[138:139]
	s_add_i32 m0, s17, 0xe000
	s_nop 0
	global_load_lds_dwordx4 v[222:223], off
	s_waitcnt vmcnt(8)
	s_waitcnt lgkmcnt(0)
	s_barrier
; #define PG8_STAGE(bufoff, gbase, voff) do { _Pragma("unroll") for (int _i = 0; _i < 2; ++_i) \
;         __builtin_amdgcn_global_load_lds((const unsigned*)((const char*)(gbase) + (voff)[_i]), (LAS unsigned*)(lds + (bufoff) + ldsw + _i * 8192), 16, 0, 0); } while (0)
; #define PG8_LDA(dst, b, h) do { _Pragma("unroll") for (int m = 0; m < 4; ++m) _Pragma("unroll") for (int k = 0; k < 2; ++k) dst[m][k] = *(const LAS bf16x8*)(lds + PG8_SA(b, h) + aoff + m * 2048 + k * 1024); } while (0)
; #define PG8_LDB(dst, b, h) do { _Pragma("unroll") for (int n = 0; n < 2; ++n) _Pragma("unroll") for (int k = 0; k < 2; ++k) dst[n][k] = *(const LAS bf16x8*)(lds + PG8_SB(b, h) + boff + n * 2048 + k * 1024); } while (0)
; #define PG8_MMA(ai, bj, At, Bt) do { __builtin_amdgcn_s_setprio(1); _Pragma("unroll") for (int m = 0; m < 4; ++m) _Pragma("unroll") for (int n = 0; n < 2; ++n) _Pragma("unroll") for (int k = 0; k < 2; ++k) \
;         acc[ai][bj][m][n] = __builtin_amdgcn_mfma_f32_16x16x32_bf16(Bt[n][k], At[m][k], acc[ai][bj][m][n], 0, 0, 0); __builtin_amdgcn_s_setprio(0); } while (0)
; #define PG8_WAIT_V(n) asm volatile("s_waitcnt vmcnt(" #n ")" ::: "memory")
; #define PG8_WAIT_L(n) asm volatile("s_waitcnt lgkmcnt(" #n ")" ::: "memory")
; #define PG8_BAR __builtin_amdgcn_s_barrier()
; #define PG8_SCHED __builtin_amdgcn_sched_barrier(0)
; __device__ __forceinline__ void gemm_phase(LAS unsigned char* lds, const Params& p, const bf16_t* gA, const bf16_t* gBt, const int gM, const int gN, const int gK, const int epi, const int perm, bf16_t* const Hp, const int goff, const float coef) {
;     ...
;             PG8_WAIT_V(8); PG8_WAIT_L(0); PG8_BAR; PG8_MMA(0, 0, At, B0); PG8_MMA(0, 1, At, B1); PG8_BAR; PG8_SCHED;
;             PG8_LDA(At, 0, 1); PG8_STAGE(PG8_SB(0, 0), b2, voffB); PG8_STAGE(PG8_SB(0, 1), b2 + hstep, voffB); PG8_STAGE(PG8_SA(0, 0), a2, voffA);
;             PG8_WAIT_V(8); PG8_WAIT_L(0); PG8_BAR; PG8_MMA(1, 0, At, B0); PG8_MMA(1, 1, At, B1); PG8_BAR; PG8_SCHED;
;             PG8_LDB(B0, 1, 0); PG8_LDB(B1, 1, 1); PG8_SCHED; PG8_LDA(At, 1, 0); PG8_STAGE(PG8_SA(0, 1), a2 + hstep, voffA);
;             PG8_WAIT_V(8); PG8_WAIT_L(0); PG8_BAR; PG8_MMA(0, 0, At, B0); PG8_MMA(0, 1, At, B1); PG8_BAR; PG8_SCHED;
	s_waitcnt lgkmcnt(0)
	v_mfma_f32_16x16x32_bf16 v[124:127], v[146:149], v[190:193], v[124:127]
	v_mfma_f32_16x16x32_bf16 v[120:123], v[154:157], v[190:193], v[120:123]
	v_mfma_f32_16x16x32_bf16 v[116:119], v[146:149], v[198:201], v[116:119]
	v_mfma_f32_16x16x32_bf16 v[112:115], v[154:157], v[198:201], v[112:115]
	v_mfma_f32_16x16x32_bf16 v[108:111], v[146:149], v[206:209], v[108:111]
	v_mfma_f32_16x16x32_bf16 v[104:107], v[154:157], v[206:209], v[104:107]
	v_mfma_f32_16x16x32_bf16 v[100:103], v[146:149], v[214:217], v[100:103]
	v_mfma_f32_16x16x32_bf16 v[96:99], v[154:157], v[214:217], v[96:99]
	v_mfma_f32_16x16x32_bf16 v[124:127], v[150:153], v[194:197], v[124:127]
	v_mfma_f32_16x16x32_bf16 v[120:123], v[170:173], v[194:197], v[120:123]
	v_mfma_f32_16x16x32_bf16 v[116:119], v[150:153], v[202:205], v[116:119]
	v_mfma_f32_16x16x32_bf16 v[112:115], v[170:173], v[202:205], v[112:115]
	v_mfma_f32_16x16x32_bf16 v[108:111], v[150:153], v[210:213], v[108:111]
	v_mfma_f32_16x16x32_bf16 v[104:107], v[170:173], v[210:213], v[104:107]
	v_mfma_f32_16x16x32_bf16 v[100:103], v[150:153], v[218:221], v[100:103]
	v_mfma_f32_16x16x32_bf16 v[96:99], v[170:173], v[218:221], v[96:99]
	v_mfma_f32_16x16x32_bf16 v[68:71], v[174:177], v[190:193], v[68:71]
	v_mfma_f32_16x16x32_bf16 v[60:63], v[182:185], v[190:193], v[60:63]
	v_mfma_f32_16x16x32_bf16 v[52:55], v[174:177], v[198:201], v[52:55]
	v_mfma_f32_16x16x32_bf16 v[48:51], v[182:185], v[198:201], v[48:51]
	v_mfma_f32_16x16x32_bf16 v[44:47], v[174:177], v[206:209], v[44:47]
	v_mfma_f32_16x16x32_bf16 v[40:43], v[182:185], v[206:209], v[40:43]
	v_mfma_f32_16x16x32_bf16 v[36:39], v[174:177], v[214:217], v[36:39]
	v_mfma_f32_16x16x32_bf16 v[32:35], v[182:185], v[214:217], v[32:35]
	v_mfma_f32_16x16x32_bf16 v[68:71], v[178:181], v[194:197], v[68:71]
	v_mfma_f32_16x16x32_bf16 v[60:63], v[186:189], v[194:197], v[60:63]
	v_mfma_f32_16x16x32_bf16 v[52:55], v[178:181], v[202:205], v[52:55]
	v_mfma_f32_16x16x32_bf16 v[48:51], v[186:189], v[202:205], v[48:51]
	v_mfma_f32_16x16x32_bf16 v[44:47], v[178:181], v[210:213], v[44:47]
	v_mfma_f32_16x16x32_bf16 v[40:43], v[186:189], v[210:213], v[40:43]
	v_mfma_f32_16x16x32_bf16 v[36:39], v[178:181], v[218:221], v[36:39]
	v_mfma_f32_16x16x32_bf16 v[32:35], v[186:189], v[218:221], v[32:35]
	s_barrier
	s_add_i32 s59, s46, s16
	v_lshl_add_u64 v[222:223], s[34:35], 0, v[130:131]
	s_mov_b32 m0, s59
	ds_read_b128 v[190:193], v169 offset:16384
	ds_read_b128 v[194:197], v169 offset:17408
	ds_read_b128 v[198:201], v169 offset:18432
	ds_read_b128 v[202:205], v169 offset:19456
	ds_read_b128 v[206:209], v169 offset:20480
	ds_read_b128 v[210:213], v169 offset:21504
	ds_read_b128 v[214:217], v169 offset:22528
	ds_read_b128 v[218:221], v169 offset:23552
	global_load_lds_dwordx4 v[222:223], off
	s_add_i32 m0, s59, 0x2000
	s_add_u32 s60, s34, 0x160000
	v_lshl_add_u64 v[224:225], s[34:35], 0, v[134:135]
	s_addc_u32 s61, s35, 0
	s_add_i32 s59, s47, s16
	global_load_lds_dwordx4 v[224:225], off
	v_lshl_add_u64 v[226:227], s[60:61], 0, v[130:131]
	s_mov_b32 m0, s59
	v_lshl_add_u64 v[228:229], s[38:39], 0, v[132:133]
	global_load_lds_dwordx4 v[226:227], off
	v_lshl_add_u64 v[226:227], s[60:61], 0, v[134:135]
	s_add_i32 m0, s59, 0x2000
	s_nop 0
	global_load_lds_dwordx4 v[226:227], off
	v_lshl_add_u64 v[226:227], s[38:39], 0, v[128:129]
	s_mov_b32 m0, s17
	s_nop 0
	global_load_lds_dwordx4 v[226:227], off
	s_mov_b32 m0, s18
	s_nop 0
	global_load_lds_dwordx4 v[228:229], off
	s_waitcnt vmcnt(8)
	s_waitcnt lgkmcnt(0)
	s_barrier
	s_waitcnt lgkmcnt(0)
	v_mfma_f32_16x16x32_bf16 v[92:95], v[146:149], v[190:193], v[92:95]
	v_mfma_f32_16x16x32_bf16 v[88:91], v[154:157], v[190:193], v[88:91]
	v_mfma_f32_16x16x32_bf16 v[84:87], v[146:149], v[198:201], v[84:87]
	v_mfma_f32_16x16x32_bf16 v[80:83], v[154:157], v[198:201], v[80:83]
	v_mfma_f32_16x16x32_bf16 v[76:79], v[146:149], v[206:209], v[76:79]
	v_mfma_f32_16x16x32_bf16 v[72:75], v[154:157], v[206:209], v[72:75]
	v_mfma_f32_16x16x32_bf16 v[64:67], v[146:149], v[214:217], v[64:67]
	v_mfma_f32_16x16x32_bf16 v[56:59], v[154:157], v[214:217], v[56:59]
	v_mfma_f32_16x16x32_bf16 v[92:95], v[150:153], v[194:197], v[92:95]
	v_mfma_f32_16x16x32_bf16 v[88:91], v[170:173], v[194:197], v[88:91]
	v_mfma_f32_16x16x32_bf16 v[84:87], v[150:153], v[202:205], v[84:87]
	v_mfma_f32_16x16x32_bf16 v[80:83], v[170:173], v[202:205], v[80:83]
	v_mfma_f32_16x16x32_bf16 v[76:79], v[150:153], v[210:213], v[76:79]
	v_mfma_f32_16x16x32_bf16 v[72:75], v[170:173], v[210:213], v[72:75]
	v_mfma_f32_16x16x32_bf16 v[64:67], v[150:153], v[218:221], v[64:67]
	v_mfma_f32_16x16x32_bf16 v[56:59], v[170:173], v[218:221], v[56:59]
	v_mfma_f32_16x16x32_bf16 v[28:31], v[174:177], v[190:193], v[28:31]
	v_mfma_f32_16x16x32_bf16 v[24:27], v[182:185], v[190:193], v[24:27]
	v_mfma_f32_16x16x32_bf16 v[20:23], v[174:177], v[198:201], v[20:23]
	v_mfma_f32_16x16x32_bf16 v[16:19], v[182:185], v[198:201], v[16:19]
	v_mfma_f32_16x16x32_bf16 v[12:15], v[174:177], v[206:209], v[12:15]
	v_mfma_f32_16x16x32_bf16 v[8:11], v[182:185], v[206:209], v[8:11]
	v_mfma_f32_16x16x32_bf16 v[4:7], v[174:177], v[214:217], v[4:7]
	v_mfma_f32_16x16x32_bf16 v[0:3], v[182:185], v[214:217], v[0:3]
	v_mfma_f32_16x16x32_bf16 v[28:31], v[178:181], v[194:197], v[28:31]
	v_mfma_f32_16x16x32_bf16 v[24:27], v[186:189], v[194:197], v[24:27]
	v_mfma_f32_16x16x32_bf16 v[20:23], v[178:181], v[202:205], v[20:23]
	v_mfma_f32_16x16x32_bf16 v[16:19], v[186:189], v[202:205], v[16:19]
	v_mfma_f32_16x16x32_bf16 v[12:15], v[178:181], v[210:213], v[12:15]
	v_mfma_f32_16x16x32_bf16 v[8:11], v[186:189], v[210:213], v[8:11]
	v_mfma_f32_16x16x32_bf16 v[4:7], v[178:181], v[218:221], v[4:7]
	v_mfma_f32_16x16x32_bf16 v[0:3], v[186:189], v[218:221], v[0:3]
	s_barrier
; #define PG8_STAGE(bufoff, gbase, voff) do { _Pragma("unroll") for (int _i = 0; _i < 2; ++_i) \
;         __builtin_amdgcn_global_load_lds((const unsigned*)((const char*)(gbase) + (voff)[_i]), (LAS unsigned*)(lds + (bufoff) + ldsw + _i * 8192), 16, 0, 0); } while (0)
; #define PG8_LDA(dst, b, h) do { _Pragma("unroll") for (int m = 0; m < 4; ++m) _Pragma("unroll") for (int k = 0; k < 2; ++k) dst[m][k] = *(const LAS bf16x8*)(lds + PG8_SA(b, h) + aoff + m * 2048 + k * 1024); } while (0)
; #define PG8_MMA(ai, bj, At, Bt) do { __builtin_amdgcn_s_setprio(1); _Pragma("unroll") for (int m = 0; m < 4; ++m) _Pragma("unroll") for (int n = 0; n < 2; ++n) _Pragma("unroll") for (int k = 0; k < 2; ++k) \
;         acc[ai][bj][m][n] = __builtin_amdgcn_mfma_f32_16x16x32_bf16(Bt[n][k], At[m][k], acc[ai][bj][m][n], 0, 0, 0); __builtin_amdgcn_s_setprio(0); } while (0)
; #define PG8_WAIT_V(n) asm volatile("s_waitcnt vmcnt(" #n ")" ::: "memory")
; #define PG8_WAIT_L(n) asm volatile("s_waitcnt lgkmcnt(" #n ")" ::: "memory")
; #define PG8_BAR __builtin_amdgcn_s_barrier()
; #define PG8_SCHED __builtin_amdgcn_sched_barrier(0)
; __device__ __forceinline__ void gemm_phase(LAS unsigned char* lds, const Params& p, const bf16_t* gA, const bf16_t* gBt, const int gM, const int gN, const int gK, const int epi, const int perm, bf16_t* const Hp, const int goff, const float coef) {
;     ...
;             PG8_LDA(At, 1, 1); PG8_STAGE(PG8_SB(1, 0), b3, voffB); PG8_STAGE(PG8_SB(1, 1), b3 + hstep, voffB); PG8_STAGE(PG8_SA(1, 0), a3, voffA);
;             PG8_WAIT_V(8); PG8_WAIT_L(0); PG8_BAR; PG8_MMA(1, 0, At, B0); PG8_MMA(1, 1, At, B1); PG8_BAR; PG8_SCHED;
;         }
;         if (wr == 0) PG8_BAR;
	s_add_i32 s59, 0, 0x18000
	s_add_i32 s60, 0, 0x1c000
	v_add_u32_e32 v170, s59, v158
	v_add_u32_e32 v186, s60, v158
	ds_read_b128 v[146:149], v170
	ds_read_b128 v[150:153], v170 offset:1024
	ds_read_b128 v[154:157], v170 offset:2048
	ds_read_b128 v[170:173], v170 offset:3072
	ds_read_b128 v[174:177], v186
	ds_read_b128 v[178:181], v186 offset:1024
	ds_read_b128 v[182:185], v186 offset:2048
	ds_read_b128 v[186:189], v186 offset:3072
	s_add_u32 s38, s38, 0x160000
	s_addc_u32 s39, s39, 0
	s_mov_b32 m0, s19
	v_lshl_add_u64 v[230:231], s[38:39], 0, v[128:129]
	ds_read_b128 v[190:193], v169 offset:32768
	ds_read_b128 v[194:197], v169 offset:33792
	ds_read_b128 v[198:201], v169 offset:34816
	ds_read_b128 v[202:205], v169 offset:35840
	ds_read_b128 v[206:209], v169 offset:36864
	ds_read_b128 v[210:213], v169 offset:37888
	ds_read_b128 v[214:217], v169 offset:38912
	ds_read_b128 v[218:221], v169 offset:39936
	global_load_lds_dwordx4 v[230:231], off
	v_lshl_add_u64 v[230:231], s[38:39], 0, v[132:133]
	s_mov_b32 m0, s20
	s_nop 0
	global_load_lds_dwordx4 v[230:231], off
	s_waitcnt vmcnt(8)
	s_waitcnt lgkmcnt(0)
	s_barrier
	s_waitcnt lgkmcnt(0)
	v_mfma_f32_16x16x32_bf16 v[124:127], v[146:149], v[190:193], v[124:127]
	v_mfma_f32_16x16x32_bf16 v[120:123], v[154:157], v[190:193], v[120:123]
	v_mfma_f32_16x16x32_bf16 v[116:119], v[146:149], v[198:201], v[116:119]
	v_mfma_f32_16x16x32_bf16 v[112:115], v[154:157], v[198:201], v[112:115]
	v_mfma_f32_16x16x32_bf16 v[108:111], v[146:149], v[206:209], v[108:111]
	v_mfma_f32_16x16x32_bf16 v[104:107], v[154:157], v[206:209], v[104:107]
	v_mfma_f32_16x16x32_bf16 v[100:103], v[146:149], v[214:217], v[100:103]
	v_mfma_f32_16x16x32_bf16 v[96:99], v[154:157], v[214:217], v[96:99]
	v_mfma_f32_16x16x32_bf16 v[124:127], v[150:153], v[194:197], v[124:127]
	v_mfma_f32_16x16x32_bf16 v[120:123], v[170:173], v[194:197], v[120:123]
	v_mfma_f32_16x16x32_bf16 v[116:119], v[150:153], v[202:205], v[116:119]
	v_mfma_f32_16x16x32_bf16 v[112:115], v[170:173], v[202:205], v[112:115]
	v_mfma_f32_16x16x32_bf16 v[108:111], v[150:153], v[210:213], v[108:111]
	v_mfma_f32_16x16x32_bf16 v[104:107], v[170:173], v[210:213], v[104:107]
	v_mfma_f32_16x16x32_bf16 v[100:103], v[150:153], v[218:221], v[100:103]
	v_mfma_f32_16x16x32_bf16 v[96:99], v[170:173], v[218:221], v[96:99]
	v_mfma_f32_16x16x32_bf16 v[68:71], v[174:177], v[190:193], v[68:71]
	v_mfma_f32_16x16x32_bf16 v[60:63], v[182:185], v[190:193], v[60:63]
	v_mfma_f32_16x16x32_bf16 v[52:55], v[174:177], v[198:201], v[52:55]
	v_mfma_f32_16x16x32_bf16 v[48:51], v[182:185], v[198:201], v[48:51]
	v_mfma_f32_16x16x32_bf16 v[44:47], v[174:177], v[206:209], v[44:47]
	v_mfma_f32_16x16x32_bf16 v[40:43], v[182:185], v[206:209], v[40:43]
	v_mfma_f32_16x16x32_bf16 v[36:39], v[174:177], v[214:217], v[36:39]
	v_mfma_f32_16x16x32_bf16 v[32:35], v[182:185], v[214:217], v[32:35]
	v_mfma_f32_16x16x32_bf16 v[68:71], v[178:181], v[194:197], v[68:71]
	v_mfma_f32_16x16x32_bf16 v[60:63], v[186:189], v[194:197], v[60:63]
	v_mfma_f32_16x16x32_bf16 v[52:55], v[178:181], v[202:205], v[52:55]
	v_mfma_f32_16x16x32_bf16 v[48:51], v[186:189], v[202:205], v[48:51]
	v_mfma_f32_16x16x32_bf16 v[44:47], v[178:181], v[210:213], v[44:47]
	v_mfma_f32_16x16x32_bf16 v[40:43], v[186:189], v[210:213], v[40:43]
	v_mfma_f32_16x16x32_bf16 v[36:39], v[178:181], v[218:221], v[36:39]
	v_mfma_f32_16x16x32_bf16 v[32:35], v[186:189], v[218:221], v[32:35]
	s_barrier
	s_add_i32 s38, s59, s16
	v_lshl_add_u64 v[222:223], v[222:223], 0, s[12:13]
	s_mov_b32 m0, s38
	ds_read_b128 v[190:193], v169 offset:49152
	ds_read_b128 v[194:197], v169 offset:50176
	ds_read_b128 v[198:201], v169 offset:51200
	ds_read_b128 v[202:205], v169 offset:52224
	ds_read_b128 v[206:209], v169 offset:53248
	ds_read_b128 v[210:213], v169 offset:54272
	ds_read_b128 v[214:217], v169 offset:55296
	ds_read_b128 v[218:221], v169 offset:56320
	global_load_lds_dwordx4 v[222:223], off
	s_add_i32 m0, s38, 0x2000
	s_add_u32 s34, s34, 0x160080
	v_lshl_add_u64 v[222:223], v[224:225], 0, s[12:13]
	s_addc_u32 s35, s35, 0
	s_add_i32 s38, s60, s16
	global_load_lds_dwordx4 v[222:223], off
	v_lshl_add_u64 v[222:223], s[34:35], 0, v[130:131]
	s_mov_b32 m0, s38
	s_nop 0
	global_load_lds_dwordx4 v[222:223], off
	v_lshl_add_u64 v[222:223], s[34:35], 0, v[134:135]
	s_add_i32 m0, s38, 0x2000
	s_nop 0
	global_load_lds_dwordx4 v[222:223], off
	v_lshl_add_u64 v[222:223], v[226:227], 0, s[12:13]
	s_mov_b32 m0, s23
	s_nop 0
	global_load_lds_dwordx4 v[222:223], off
	v_lshl_add_u64 v[222:223], v[228:229], 0, s[12:13]
	s_mov_b32 m0, s33
	s_nop 0
	global_load_lds_dwordx4 v[222:223], off
	s_waitcnt vmcnt(8)
	s_waitcnt lgkmcnt(0)
	s_barrier
	s_waitcnt lgkmcnt(0)
	v_mfma_f32_16x16x32_bf16 v[92:95], v[146:149], v[190:193], v[92:95]
	v_mfma_f32_16x16x32_bf16 v[88:91], v[154:157], v[190:193], v[88:91]
	v_mfma_f32_16x16x32_bf16 v[84:87], v[146:149], v[198:201], v[84:87]
	v_mfma_f32_16x16x32_bf16 v[80:83], v[154:157], v[198:201], v[80:83]
	v_mfma_f32_16x16x32_bf16 v[76:79], v[146:149], v[206:209], v[76:79]
	v_mfma_f32_16x16x32_bf16 v[72:75], v[154:157], v[206:209], v[72:75]
	v_mfma_f32_16x16x32_bf16 v[64:67], v[146:149], v[214:217], v[64:67]
	v_mfma_f32_16x16x32_bf16 v[56:59], v[154:157], v[214:217], v[56:59]
	v_mfma_f32_16x16x32_bf16 v[92:95], v[150:153], v[194:197], v[92:95]
	v_mfma_f32_16x16x32_bf16 v[88:91], v[170:173], v[194:197], v[88:91]
	v_mfma_f32_16x16x32_bf16 v[84:87], v[150:153], v[202:205], v[84:87]
	v_mfma_f32_16x16x32_bf16 v[80:83], v[170:173], v[202:205], v[80:83]
	v_mfma_f32_16x16x32_bf16 v[76:79], v[150:153], v[210:213], v[76:79]
	v_mfma_f32_16x16x32_bf16 v[72:75], v[170:173], v[210:213], v[72:75]
	v_mfma_f32_16x16x32_bf16 v[64:67], v[150:153], v[218:221], v[64:67]
	v_mfma_f32_16x16x32_bf16 v[56:59], v[170:173], v[218:221], v[56:59]
	v_mfma_f32_16x16x32_bf16 v[28:31], v[174:177], v[190:193], v[28:31]
	v_mfma_f32_16x16x32_bf16 v[24:27], v[182:185], v[190:193], v[24:27]
	v_mfma_f32_16x16x32_bf16 v[20:23], v[174:177], v[198:201], v[20:23]
	v_mfma_f32_16x16x32_bf16 v[16:19], v[182:185], v[198:201], v[16:19]
	v_mfma_f32_16x16x32_bf16 v[12:15], v[174:177], v[206:209], v[12:15]
	v_mfma_f32_16x16x32_bf16 v[8:11], v[182:185], v[206:209], v[8:11]
	v_mfma_f32_16x16x32_bf16 v[4:7], v[174:177], v[214:217], v[4:7]
	v_mfma_f32_16x16x32_bf16 v[0:3], v[182:185], v[214:217], v[0:3]
	v_mfma_f32_16x16x32_bf16 v[28:31], v[178:181], v[194:197], v[28:31]
	v_mfma_f32_16x16x32_bf16 v[24:27], v[186:189], v[194:197], v[24:27]
	v_mfma_f32_16x16x32_bf16 v[20:23], v[178:181], v[202:205], v[20:23]
	v_mfma_f32_16x16x32_bf16 v[16:19], v[186:189], v[202:205], v[16:19]
	v_mfma_f32_16x16x32_bf16 v[12:15], v[178:181], v[210:213], v[12:15]
	v_mfma_f32_16x16x32_bf16 v[8:11], v[186:189], v[210:213], v[8:11]
	v_mfma_f32_16x16x32_bf16 v[4:7], v[178:181], v[218:221], v[4:7]
	v_mfma_f32_16x16x32_bf16 v[0:3], v[186:189], v[218:221], v[0:3]
	s_barrier
	s_add_u32 s30, s30, 0x100
	s_addc_u32 s31, s31, 0
	s_add_u32 s56, s56, 0x100
	s_addc_u32 s57, s57, 0
	s_cmp_ge_u32 s58, s54
	s_mov_b32 s34, s58
	s_cbranch_scc0 .LBB0_264
; #define PG8_BAR __builtin_amdgcn_s_barrier()
; __device__ __forceinline__ void gemm_phase(LAS unsigned char* lds, const Params& p, const bf16_t* gA, const bf16_t* gBt, const int gM, const int gN, const int gK, const int epi, const int perm, bf16_t* const Hp, const int goff, const float coef) {
;     ...
;         if (wr == 0) PG8_BAR;
;         gemm_epilogue(p, epi, Hp, goff, coef, acc, cur, wr, wc, fr, fq);
.Lpeel_exit_1:
	s_and_b64 vcc, exec, s[24:25]
	s_cbranch_vccz .LBB0_267
	s_barrier

; #define PG8_STAGE(bufoff, gbase, voff) do { _Pragma("unroll") for (int _i = 0; _i < 2; ++_i) \
;         __builtin_amdgcn_global_load_lds((const unsigned*)((const char*)(gbase) + (voff)[_i]), (LAS unsigned*)(lds + (bufoff) + ldsw + _i * 8192), 16, 0, 0); } while (0)
; #define PG8_LDA(dst, b, h) do { _Pragma("unroll") for (int m = 0; m < 4; ++m) _Pragma("unroll") for (int k = 0; k < 2; ++k) dst[m][k] = *(const LAS bf16x8*)(lds + PG8_SA(b, h) + aoff + m * 2048 + k * 1024); } while (0)
; #define PG8_LDB(dst, b, h) do { _Pragma("unroll") for (int n = 0; n < 2; ++n) _Pragma("unroll") for (int k = 0; k < 2; ++k) dst[n][k] = *(const LAS bf16x8*)(lds + PG8_SB(b, h) + boff + n * 2048 + k * 1024); } while (0)
; #define PG8_MMA(ai, bj, At, Bt) do { __builtin_amdgcn_s_setprio(1); _Pragma("unroll") for (int m = 0; m < 4; ++m) _Pragma("unroll") for (int n = 0; n < 2; ++n) _Pragma("unroll") for (int k = 0; k < 2; ++k) \
;         acc[ai][bj][m][n] = __builtin_amdgcn_mfma_f32_16x16x32_bf16(Bt[n][k], At[m][k], acc[ai][bj][m][n], 0, 0, 0); __builtin_amdgcn_s_setprio(0); } while (0)
; #define PG8_WAIT_V(n) asm volatile("s_waitcnt vmcnt(" #n ")" ::: "memory")
; #define PG8_WAIT_L(n) asm volatile("s_waitcnt lgkmcnt(" #n ")" ::: "memory")
; __device__ __forceinline__ void gemm_phase(LAS unsigned char* lds, const Params& p, const bf16_t* gA, const bf16_t* gBt, const int gM, const int gN, const int gK, const int epi, const int perm, bf16_t* const Hp, const int goff, const float coef) {
;     ...
;         const char* nA = has_next ? (const char*)gA + (size_t)nxt.pm * tstep + (nxt.ks > 0 ? nxt.ks * ksl : 0) : cA; const char* nB = has_next ? (const char*)gBt + (size_t)nxt.pn * tstep + (nxt.ks > 0 ? nxt.ks * ksl : 0) : cB;
;         const int nt = cur.ks >= 0 ? ntf / 4 : ntf;
;         for (int t = 0; t < nt; t += 2) {
;             const bool last = (t == nt - 2);
;             const char* a1 = cA + (size_t)(t + 1) * kstep;
;             const char* a2 = last ? nA : cA + (size_t)(t + 2) * kstep; const char* b2 = last ? nB : cB + (size_t)(t + 2) * kstep;
;             const char* a3 = a2 + kstep; const char* b3 = b2 + kstep;
;             PG8_LDB(B0, 0, 0); PG8_LDB(B1, 0, 1); PG8_SCHED; PG8_LDA(At, 0, 0); PG8_STAGE(PG8_SA(1, 1), a1 + hstep, voffA);
;             PG8_WAIT_V(8); PG8_WAIT_L(0); PG8_BAR; PG8_MMA(0, 0, At, B0); PG8_MMA(0, 1, At, B1); PG8_BAR; PG8_SCHED;
.LBB0_435:
	s_ashr_i32 s35, s34, 31
	s_lshl_b64 s[14:15], s[34:35], 20
	s_add_u32 s16, s3, s14
	s_addc_u32 s17, s27, s15
	s_lshl_b64 s[14:15], s[6:7], 10
	s_cmp_gt_i32 s6, 0
	s_cselect_b32 s33, s14, 0
	s_cselect_b32 s23, s15, 0
	s_add_u32 s40, s16, s33
	s_addc_u32 s41, s17, s23
	s_and_b64 s[14:15], s[38:39], exec
	s_cselect_b32 s14, s41, s1
	s_cselect_b32 s15, s40, s0
	s_ashr_i32 s37, s36, 31
	s_lshl_b64 s[16:17], s[36:37], 20
	s_add_u32 s16, s29, s16
	s_addc_u32 s17, s31, s17
	s_add_u32 s42, s16, s33
	s_addc_u32 s43, s17, s23
	s_and_b64 s[16:17], s[38:39], exec
	s_cselect_b32 s16, s43, s5
	s_cselect_b32 s17, s42, s4
	s_cmp_gt_i32 s22, -1
	s_cselect_b32 s22, 8, 32
	s_add_i32 s23, s22, -2
	s_add_u32 s0, s0, 0x80080
	s_addc_u32 s1, s1, 0
	s_add_u32 s33, s4, 0x100
	s_mov_b32 s45, 0
	s_addc_u32 s35, s5, 0
	ds_read_b128 v[128:131], v180
	ds_read_b128 v[132:135], v180 offset:1024
	ds_read_b128 v[136:139], v180 offset:2048
	ds_read_b128 v[184:187], v180 offset:3072
	ds_read_b128 v[188:191], v181
	ds_read_b128 v[192:195], v181 offset:1024
	ds_read_b128 v[196:199], v181 offset:2048
	ds_read_b128 v[200:203], v181 offset:3072
	s_add_i32 s37, s45, 2
	s_add_u32 s4, s0, 0xfff80080
	s_addc_u32 s5, s1, -1
	s_cmp_eq_u32 s23, s45
	s_cselect_b32 s49, s14, s5
	s_cselect_b32 s48, s15, s4
	s_cselect_b32 s5, s16, s35
	s_cselect_b32 s4, s17, s33
	v_lshl_add_u64 v[168:169], s[0:1], 0, v[160:161]
	s_add_i32 m0, s47, 0xc000
	ds_read_b128 v[204:207], v182
	ds_read_b128 v[208:211], v182 offset:1024
	ds_read_b128 v[212:215], v182 offset:2048
	ds_read_b128 v[216:219], v182 offset:3072
	ds_read_b128 v[220:223], v182 offset:4096
	ds_read_b128 v[224:227], v182 offset:5120
	ds_read_b128 v[228:231], v182 offset:6144
	ds_read_b128 v[232:235], v182 offset:7168
	global_load_lds_dwordx4 v[168:169], off
	v_lshl_add_u64 v[168:169], s[0:1], 0, v[162:163]
	s_add_i32 m0, s47, 0xe000
	s_nop 0
	global_load_lds_dwordx4 v[168:169], off
	s_waitcnt vmcnt(8)
	s_waitcnt lgkmcnt(0)
	s_barrier
	s_waitcnt lgkmcnt(0)
	v_mfma_f32_16x16x32_bf16 v[124:127], v[128:131], v[204:207], 0
	v_mfma_f32_16x16x32_bf16 v[120:123], v[136:139], v[204:207], 0
	v_mfma_f32_16x16x32_bf16 v[108:111], v[128:131], v[212:215], 0
	v_mfma_f32_16x16x32_bf16 v[104:107], v[136:139], v[212:215], 0
	v_mfma_f32_16x16x32_bf16 v[92:95], v[128:131], v[220:223], 0
	v_mfma_f32_16x16x32_bf16 v[88:91], v[136:139], v[220:223], 0
	v_mfma_f32_16x16x32_bf16 v[76:79], v[128:131], v[228:231], 0
	v_mfma_f32_16x16x32_bf16 v[72:75], v[136:139], v[228:231], 0
	v_mfma_f32_16x16x32_bf16 v[124:127], v[132:135], v[208:211], v[124:127]
	v_mfma_f32_16x16x32_bf16 v[120:123], v[184:187], v[208:211], v[120:123]
	v_mfma_f32_16x16x32_bf16 v[108:111], v[132:135], v[216:219], v[108:111]
	v_mfma_f32_16x16x32_bf16 v[104:107], v[184:187], v[216:219], v[104:107]
	v_mfma_f32_16x16x32_bf16 v[92:95], v[132:135], v[224:227], v[92:95]
	v_mfma_f32_16x16x32_bf16 v[88:91], v[184:187], v[224:227], v[88:91]
	v_mfma_f32_16x16x32_bf16 v[76:79], v[132:135], v[232:235], v[76:79]
	v_mfma_f32_16x16x32_bf16 v[72:75], v[184:187], v[232:235], v[72:75]
	v_mfma_f32_16x16x32_bf16 v[116:119], v[188:191], v[204:207], 0
	v_mfma_f32_16x16x32_bf16 v[112:115], v[196:199], v[204:207], 0
	v_mfma_f32_16x16x32_bf16 v[100:103], v[188:191], v[212:215], 0
	v_mfma_f32_16x16x32_bf16 v[96:99], v[196:199], v[212:215], 0
	v_mfma_f32_16x16x32_bf16 v[84:87], v[188:191], v[220:223], 0
	v_mfma_f32_16x16x32_bf16 v[80:83], v[196:199], v[220:223], 0
	v_mfma_f32_16x16x32_bf16 v[68:71], v[188:191], v[228:231], 0
	v_mfma_f32_16x16x32_bf16 v[64:67], v[196:199], v[228:231], 0
	v_mfma_f32_16x16x32_bf16 v[116:119], v[192:195], v[208:211], v[116:119]
	v_mfma_f32_16x16x32_bf16 v[112:115], v[200:203], v[208:211], v[112:115]
	v_mfma_f32_16x16x32_bf16 v[100:103], v[192:195], v[216:219], v[100:103]
	v_mfma_f32_16x16x32_bf16 v[96:99], v[200:203], v[216:219], v[96:99]
	v_mfma_f32_16x16x32_bf16 v[84:87], v[192:195], v[224:227], v[84:87]
	v_mfma_f32_16x16x32_bf16 v[80:83], v[200:203], v[224:227], v[80:83]
	v_mfma_f32_16x16x32_bf16 v[68:71], v[192:195], v[232:235], v[68:71]
	v_mfma_f32_16x16x32_bf16 v[64:67], v[200:203], v[232:235], v[64:67]
	s_barrier
	s_add_i32 s45, s19, s52
	v_lshl_add_u64 v[168:169], s[4:5], 0, v[144:145]
	s_mov_b32 m0, s45
	ds_read_b128 v[204:207], v182 offset:16384
	ds_read_b128 v[208:211], v182 offset:17408
	ds_read_b128 v[212:215], v182 offset:18432
	ds_read_b128 v[216:219], v182 offset:19456
	ds_read_b128 v[220:223], v182 offset:20480
	ds_read_b128 v[224:227], v182 offset:21504
	ds_read_b128 v[228:231], v182 offset:22528
	ds_read_b128 v[232:235], v182 offset:23552
	global_load_lds_dwordx4 v[168:169], off
	s_add_i32 m0, s45, 0x2000
	s_add_u32 s50, s4, 0x80000
	v_lshl_add_u64 v[236:237], s[4:5], 0, v[148:149]
	s_addc_u32 s51, s5, 0
	s_add_i32 s45, s21, s52
	global_load_lds_dwordx4 v[236:237], off
	v_lshl_add_u64 v[238:239], s[50:51], 0, v[144:145]
	s_mov_b32 m0, s45
	v_lshl_add_u64 v[240:241], s[48:49], 0, v[146:147]
	global_load_lds_dwordx4 v[238:239], off
	v_lshl_add_u64 v[238:239], s[50:51], 0, v[148:149]
	s_add_i32 m0, s45, 0x2000
	s_nop 0
	global_load_lds_dwordx4 v[238:239], off
	v_lshl_add_u64 v[238:239], s[48:49], 0, v[142:143]
	s_mov_b32 m0, s47
	s_nop 0
	global_load_lds_dwordx4 v[238:239], off
	s_mov_b32 m0, s53
	s_nop 0
	global_load_lds_dwordx4 v[240:241], off
	s_waitcnt vmcnt(8)
	s_waitcnt lgkmcnt(0)
	s_barrier
; #define PG8_STAGE(bufoff, gbase, voff) do { _Pragma("unroll") for (int _i = 0; _i < 2; ++_i) \
;         __builtin_amdgcn_global_load_lds((const unsigned*)((const char*)(gbase) + (voff)[_i]), (LAS unsigned*)(lds + (bufoff) + ldsw + _i * 8192), 16, 0, 0); } while (0)
; #define PG8_LDA(dst, b, h) do { _Pragma("unroll") for (int m = 0; m < 4; ++m) _Pragma("unroll") for (int k = 0; k < 2; ++k) dst[m][k] = *(const LAS bf16x8*)(lds + PG8_SA(b, h) + aoff + m * 2048 + k * 1024); } while (0)
; #define PG8_LDB(dst, b, h) do { _Pragma("unroll") for (int n = 0; n < 2; ++n) _Pragma("unroll") for (int k = 0; k < 2; ++k) dst[n][k] = *(const LAS bf16x8*)(lds + PG8_SB(b, h) + boff + n * 2048 + k * 1024); } while (0)
; #define PG8_MMA(ai, bj, At, Bt) do { __builtin_amdgcn_s_setprio(1); _Pragma("unroll") for (int m = 0; m < 4; ++m) _Pragma("unroll") for (int n = 0; n < 2; ++n) _Pragma("unroll") for (int k = 0; k < 2; ++k) \
;         acc[ai][bj][m][n] = __builtin_amdgcn_mfma_f32_16x16x32_bf16(Bt[n][k], At[m][k], acc[ai][bj][m][n], 0, 0, 0); __builtin_amdgcn_s_setprio(0); } while (0)
; #define PG8_WAIT_V(n) asm volatile("s_waitcnt vmcnt(" #n ")" ::: "memory")
; #define PG8_WAIT_L(n) asm volatile("s_waitcnt lgkmcnt(" #n ")" ::: "memory")
; #define PG8_BAR __builtin_amdgcn_s_barrier()
; #define PG8_SCHED __builtin_amdgcn_sched_barrier(0)
; __device__ __forceinline__ void gemm_phase(LAS unsigned char* lds, const Params& p, const bf16_t* gA, const bf16_t* gBt, const int gM, const int gN, const int gK, const int epi, const int perm, bf16_t* const Hp, const int goff, const float coef) {
;     ...
;             PG8_WAIT_V(8); PG8_WAIT_L(0); PG8_BAR; PG8_MMA(0, 0, At, B0); PG8_MMA(0, 1, At, B1); PG8_BAR; PG8_SCHED;
;             PG8_LDA(At, 0, 1); PG8_STAGE(PG8_SB(0, 0), b2, voffB); PG8_STAGE(PG8_SB(0, 1), b2 + hstep, voffB); PG8_STAGE(PG8_SA(0, 0), a2, voffA);
;             PG8_WAIT_V(8); PG8_WAIT_L(0); PG8_BAR; PG8_MMA(1, 0, At, B0); PG8_MMA(1, 1, At, B1); PG8_BAR; PG8_SCHED;
;             PG8_LDB(B0, 1, 0); PG8_LDB(B1, 1, 1); PG8_SCHED; PG8_LDA(At, 1, 0); PG8_STAGE(PG8_SA(0, 1), a2 + hstep, voffA);
;             PG8_WAIT_V(8); PG8_WAIT_L(0); PG8_BAR; PG8_MMA(0, 0, At, B0); PG8_MMA(0, 1, At, B1); PG8_BAR; PG8_SCHED;
	s_waitcnt lgkmcnt(0)
	v_mfma_f32_16x16x32_bf16 v[60:63], v[128:131], v[204:207], 0
	v_mfma_f32_16x16x32_bf16 v[56:59], v[136:139], v[204:207], 0
	v_mfma_f32_16x16x32_bf16 v[44:47], v[128:131], v[212:215], 0
	v_mfma_f32_16x16x32_bf16 v[40:43], v[136:139], v[212:215], 0
	v_mfma_f32_16x16x32_bf16 v[28:31], v[128:131], v[220:223], 0
	v_mfma_f32_16x16x32_bf16 v[24:27], v[136:139], v[220:223], 0
	v_mfma_f32_16x16x32_bf16 v[12:15], v[128:131], v[228:231], 0
	v_mfma_f32_16x16x32_bf16 v[8:11], v[136:139], v[228:231], 0
	v_mfma_f32_16x16x32_bf16 v[60:63], v[132:135], v[208:211], v[60:63]
	v_mfma_f32_16x16x32_bf16 v[56:59], v[184:187], v[208:211], v[56:59]
	v_mfma_f32_16x16x32_bf16 v[44:47], v[132:135], v[216:219], v[44:47]
	v_mfma_f32_16x16x32_bf16 v[40:43], v[184:187], v[216:219], v[40:43]
	v_mfma_f32_16x16x32_bf16 v[28:31], v[132:135], v[224:227], v[28:31]
	v_mfma_f32_16x16x32_bf16 v[24:27], v[184:187], v[224:227], v[24:27]
	v_mfma_f32_16x16x32_bf16 v[12:15], v[132:135], v[232:235], v[12:15]
	v_mfma_f32_16x16x32_bf16 v[8:11], v[184:187], v[232:235], v[8:11]
	v_mfma_f32_16x16x32_bf16 v[52:55], v[188:191], v[204:207], 0
	v_mfma_f32_16x16x32_bf16 v[48:51], v[196:199], v[204:207], 0
	v_mfma_f32_16x16x32_bf16 v[36:39], v[188:191], v[212:215], 0
	v_mfma_f32_16x16x32_bf16 v[32:35], v[196:199], v[212:215], 0
	v_mfma_f32_16x16x32_bf16 v[20:23], v[188:191], v[220:223], 0
	v_mfma_f32_16x16x32_bf16 v[16:19], v[196:199], v[220:223], 0
	v_mfma_f32_16x16x32_bf16 v[4:7], v[188:191], v[228:231], 0
	v_mfma_f32_16x16x32_bf16 v[0:3], v[196:199], v[228:231], 0
	v_mfma_f32_16x16x32_bf16 v[52:55], v[192:195], v[208:211], v[52:55]
	v_mfma_f32_16x16x32_bf16 v[48:51], v[200:203], v[208:211], v[48:51]
	v_mfma_f32_16x16x32_bf16 v[36:39], v[192:195], v[216:219], v[36:39]
	v_mfma_f32_16x16x32_bf16 v[32:35], v[200:203], v[216:219], v[32:35]
	v_mfma_f32_16x16x32_bf16 v[20:23], v[192:195], v[224:227], v[20:23]
	v_mfma_f32_16x16x32_bf16 v[16:19], v[200:203], v[224:227], v[16:19]
	v_mfma_f32_16x16x32_bf16 v[4:7], v[192:195], v[232:235], v[4:7]
	v_mfma_f32_16x16x32_bf16 v[0:3], v[200:203], v[232:235], v[0:3]
	s_barrier
	s_add_i32 s45, 0, 0x18000
	v_add_u32_e32 v150, s45, v171
	s_add_i32 s50, 0, 0x1c000
	ds_read_b128 v[128:131], v150
	ds_read_b128 v[132:135], v150 offset:1024
	ds_read_b128 v[136:139], v150 offset:2048
	ds_read_b128 v[184:187], v150 offset:3072
	v_add_u32_e32 v150, s50, v171
	ds_read_b128 v[188:191], v150
	ds_read_b128 v[192:195], v150 offset:1024
	ds_read_b128 v[196:199], v150 offset:2048
	ds_read_b128 v[200:203], v150 offset:3072
	s_add_u32 s48, s48, 0x80000
	s_addc_u32 s49, s49, 0
	s_mov_b32 m0, s54
	v_lshl_add_u64 v[242:243], s[48:49], 0, v[142:143]
	ds_read_b128 v[204:207], v182 offset:32768
	ds_read_b128 v[208:211], v182 offset:33792
	ds_read_b128 v[212:215], v182 offset:34816
	ds_read_b128 v[216:219], v182 offset:35840
	ds_read_b128 v[220:223], v182 offset:36864
	ds_read_b128 v[224:227], v182 offset:37888
	ds_read_b128 v[228:231], v182 offset:38912
	ds_read_b128 v[232:235], v182 offset:39936
	global_load_lds_dwordx4 v[242:243], off
	v_lshl_add_u64 v[242:243], s[48:49], 0, v[146:147]
	s_mov_b32 m0, s55
	s_nop 0
	global_load_lds_dwordx4 v[242:243], off
	s_waitcnt vmcnt(8)
	s_waitcnt lgkmcnt(0)
	s_barrier
	s_waitcnt lgkmcnt(0)
	v_mfma_f32_16x16x32_bf16 v[124:127], v[128:131], v[204:207], v[124:127]
	v_mfma_f32_16x16x32_bf16 v[120:123], v[136:139], v[204:207], v[120:123]
	v_mfma_f32_16x16x32_bf16 v[108:111], v[128:131], v[212:215], v[108:111]
	v_mfma_f32_16x16x32_bf16 v[104:107], v[136:139], v[212:215], v[104:107]
	v_mfma_f32_16x16x32_bf16 v[92:95], v[128:131], v[220:223], v[92:95]
	v_mfma_f32_16x16x32_bf16 v[88:91], v[136:139], v[220:223], v[88:91]
	v_mfma_f32_16x16x32_bf16 v[76:79], v[128:131], v[228:231], v[76:79]
	v_mfma_f32_16x16x32_bf16 v[72:75], v[136:139], v[228:231], v[72:75]
	v_mfma_f32_16x16x32_bf16 v[124:127], v[132:135], v[208:211], v[124:127]
	v_mfma_f32_16x16x32_bf16 v[120:123], v[184:187], v[208:211], v[120:123]
	v_mfma_f32_16x16x32_bf16 v[108:111], v[132:135], v[216:219], v[108:111]
	v_mfma_f32_16x16x32_bf16 v[104:107], v[184:187], v[216:219], v[104:107]
	v_mfma_f32_16x16x32_bf16 v[92:95], v[132:135], v[224:227], v[92:95]
	v_mfma_f32_16x16x32_bf16 v[88:91], v[184:187], v[224:227], v[88:91]
	v_mfma_f32_16x16x32_bf16 v[76:79], v[132:135], v[232:235], v[76:79]
	v_mfma_f32_16x16x32_bf16 v[72:75], v[184:187], v[232:235], v[72:75]
	v_mfma_f32_16x16x32_bf16 v[116:119], v[188:191], v[204:207], v[116:119]
	v_mfma_f32_16x16x32_bf16 v[112:115], v[196:199], v[204:207], v[112:115]
	v_mfma_f32_16x16x32_bf16 v[100:103], v[188:191], v[212:215], v[100:103]
	v_mfma_f32_16x16x32_bf16 v[96:99], v[196:199], v[212:215], v[96:99]
	v_mfma_f32_16x16x32_bf16 v[84:87], v[188:191], v[220:223], v[84:87]
	v_mfma_f32_16x16x32_bf16 v[80:83], v[196:199], v[220:223], v[80:83]
	v_mfma_f32_16x16x32_bf16 v[68:71], v[188:191], v[228:231], v[68:71]
	v_mfma_f32_16x16x32_bf16 v[64:67], v[196:199], v[228:231], v[64:67]
	v_mfma_f32_16x16x32_bf16 v[116:119], v[192:195], v[208:211], v[116:119]
	v_mfma_f32_16x16x32_bf16 v[112:115], v[200:203], v[208:211], v[112:115]
	v_mfma_f32_16x16x32_bf16 v[100:103], v[192:195], v[216:219], v[100:103]
	v_mfma_f32_16x16x32_bf16 v[96:99], v[200:203], v[216:219], v[96:99]
	v_mfma_f32_16x16x32_bf16 v[84:87], v[192:195], v[224:227], v[84:87]
	v_mfma_f32_16x16x32_bf16 v[80:83], v[200:203], v[224:227], v[80:83]
	v_mfma_f32_16x16x32_bf16 v[68:71], v[192:195], v[232:235], v[68:71]
	v_mfma_f32_16x16x32_bf16 v[64:67], v[200:203], v[232:235], v[64:67]
	s_barrier
; #define PG8_STAGE(bufoff, gbase, voff) do { _Pragma("unroll") for (int _i = 0; _i < 2; ++_i) \
;         __builtin_amdgcn_global_load_lds((const unsigned*)((const char*)(gbase) + (voff)[_i]), (LAS unsigned*)(lds + (bufoff) + ldsw + _i * 8192), 16, 0, 0); } while (0)
; #define PG8_LDA(dst, b, h) do { _Pragma("unroll") for (int m = 0; m < 4; ++m) _Pragma("unroll") for (int k = 0; k < 2; ++k) dst[m][k] = *(const LAS bf16x8*)(lds + PG8_SA(b, h) + aoff + m * 2048 + k * 1024); } while (0)
; #define PG8_LDB(dst, b, h) do { _Pragma("unroll") for (int n = 0; n < 2; ++n) _Pragma("unroll") for (int k = 0; k < 2; ++k) dst[n][k] = *(const LAS bf16x8*)(lds + PG8_SB(b, h) + boff + n * 2048 + k * 1024); } while (0)
; #define PG8_MMA(ai, bj, At, Bt) do { __builtin_amdgcn_s_setprio(1); _Pragma("unroll") for (int m = 0; m < 4; ++m) _Pragma("unroll") for (int n = 0; n < 2; ++n) _Pragma("unroll") for (int k = 0; k < 2; ++k) \
;         acc[ai][bj][m][n] = __builtin_amdgcn_mfma_f32_16x16x32_bf16(Bt[n][k], At[m][k], acc[ai][bj][m][n], 0, 0, 0); __builtin_amdgcn_s_setprio(0); } while (0)
; #define PG8_WAIT_V(n) asm volatile("s_waitcnt vmcnt(" #n ")" ::: "memory")
; #define PG8_WAIT_L(n) asm volatile("s_waitcnt lgkmcnt(" #n ")" ::: "memory")
; __device__ __forceinline__ void gemm_phase(LAS unsigned char* lds, const Params& p, const bf16_t* gA, const bf16_t* gBt, const int gM, const int gN, const int gK, const int epi, const int perm, bf16_t* const Hp, const int goff, const float coef) {
;     ...
;         for (int t = 0; t < nt; t += 2) {
;             const bool last = (t == nt - 2);
;             const char* a1 = cA + (size_t)(t + 1) * kstep;
;             const char* a2 = last ? nA : cA + (size_t)(t + 2) * kstep; const char* b2 = last ? nB : cB + (size_t)(t + 2) * kstep;
;             const char* a3 = a2 + kstep; const char* b3 = b2 + kstep;
;             PG8_LDB(B0, 0, 0); PG8_LDB(B1, 0, 1); PG8_SCHED; PG8_LDA(At, 0, 0); PG8_STAGE(PG8_SA(1, 1), a1 + hstep, voffA);
;             PG8_WAIT_V(8); PG8_WAIT_L(0); PG8_BAR; PG8_MMA(0, 0, At, B0); PG8_MMA(0, 1, At, B1); PG8_BAR; PG8_SCHED;
;     ...
;             PG8_LDA(At, 1, 1); PG8_STAGE(PG8_SB(1, 0), b3, voffB); PG8_STAGE(PG8_SB(1, 1), b3 + hstep, voffB); PG8_STAGE(PG8_SA(1, 0), a3, voffA);
;             PG8_WAIT_V(8); PG8_WAIT_L(0); PG8_BAR; PG8_MMA(1, 0, At, B0); PG8_MMA(1, 1, At, B1); PG8_BAR; PG8_SCHED;
	s_add_i32 s45, s45, s52
	v_lshl_add_u64 v[168:169], v[168:169], 0, s[10:11]
	s_mov_b32 m0, s45
	ds_read_b128 v[204:207], v182 offset:49152
	ds_read_b128 v[208:211], v182 offset:50176
	ds_read_b128 v[212:215], v182 offset:51200
	ds_read_b128 v[216:219], v182 offset:52224
	ds_read_b128 v[220:223], v182 offset:53248
	ds_read_b128 v[224:227], v182 offset:54272
	ds_read_b128 v[228:231], v182 offset:55296
	ds_read_b128 v[232:235], v182 offset:56320
	global_load_lds_dwordx4 v[168:169], off
	s_add_i32 m0, s45, 0x2000
	s_add_u32 s4, s4, 0x80080
	v_lshl_add_u64 v[168:169], v[236:237], 0, s[10:11]
	s_addc_u32 s5, s5, 0
	s_add_i32 s45, s50, s52
	global_load_lds_dwordx4 v[168:169], off
	v_lshl_add_u64 v[168:169], s[4:5], 0, v[144:145]
	s_mov_b32 m0, s45
	s_nop 0
	global_load_lds_dwordx4 v[168:169], off
	v_lshl_add_u64 v[168:169], s[4:5], 0, v[148:149]
	s_add_i32 m0, s45, 0x2000
	s_nop 0
	global_load_lds_dwordx4 v[168:169], off
	v_lshl_add_u64 v[168:169], v[238:239], 0, s[10:11]
	s_mov_b32 m0, s57
	s_nop 0
	global_load_lds_dwordx4 v[168:169], off
	v_lshl_add_u64 v[168:169], v[240:241], 0, s[10:11]
	s_mov_b32 m0, s58
	s_nop 0
	global_load_lds_dwordx4 v[168:169], off
	s_waitcnt vmcnt(8)
	s_waitcnt lgkmcnt(0)
	s_barrier
	s_waitcnt lgkmcnt(0)
	v_mfma_f32_16x16x32_bf16 v[60:63], v[128:131], v[204:207], v[60:63]
	v_mfma_f32_16x16x32_bf16 v[56:59], v[136:139], v[204:207], v[56:59]
	v_mfma_f32_16x16x32_bf16 v[44:47], v[128:131], v[212:215], v[44:47]
	v_mfma_f32_16x16x32_bf16 v[40:43], v[136:139], v[212:215], v[40:43]
	v_mfma_f32_16x16x32_bf16 v[28:31], v[128:131], v[220:223], v[28:31]
	v_mfma_f32_16x16x32_bf16 v[24:27], v[136:139], v[220:223], v[24:27]
	v_mfma_f32_16x16x32_bf16 v[12:15], v[128:131], v[228:231], v[12:15]
	v_mfma_f32_16x16x32_bf16 v[8:11], v[136:139], v[228:231], v[8:11]
	v_mfma_f32_16x16x32_bf16 v[60:63], v[132:135], v[208:211], v[60:63]
	v_mfma_f32_16x16x32_bf16 v[56:59], v[184:187], v[208:211], v[56:59]
	v_mfma_f32_16x16x32_bf16 v[44:47], v[132:135], v[216:219], v[44:47]
	v_mfma_f32_16x16x32_bf16 v[40:43], v[184:187], v[216:219], v[40:43]
	v_mfma_f32_16x16x32_bf16 v[28:31], v[132:135], v[224:227], v[28:31]
	v_mfma_f32_16x16x32_bf16 v[24:27], v[184:187], v[224:227], v[24:27]
	v_mfma_f32_16x16x32_bf16 v[12:15], v[132:135], v[232:235], v[12:15]
	v_mfma_f32_16x16x32_bf16 v[8:11], v[184:187], v[232:235], v[8:11]
	v_mfma_f32_16x16x32_bf16 v[52:55], v[188:191], v[204:207], v[52:55]
	v_mfma_f32_16x16x32_bf16 v[48:51], v[196:199], v[204:207], v[48:51]
	v_mfma_f32_16x16x32_bf16 v[36:39], v[188:191], v[212:215], v[36:39]
	v_mfma_f32_16x16x32_bf16 v[32:35], v[196:199], v[212:215], v[32:35]
	v_mfma_f32_16x16x32_bf16 v[20:23], v[188:191], v[220:223], v[20:23]
	v_mfma_f32_16x16x32_bf16 v[16:19], v[196:199], v[220:223], v[16:19]
	v_mfma_f32_16x16x32_bf16 v[4:7], v[188:191], v[228:231], v[4:7]
	v_mfma_f32_16x16x32_bf16 v[0:3], v[196:199], v[228:231], v[0:3]
	v_mfma_f32_16x16x32_bf16 v[52:55], v[192:195], v[208:211], v[52:55]
	v_mfma_f32_16x16x32_bf16 v[48:51], v[200:203], v[208:211], v[48:51]
	v_mfma_f32_16x16x32_bf16 v[36:39], v[192:195], v[216:219], v[36:39]
	v_mfma_f32_16x16x32_bf16 v[32:35], v[200:203], v[216:219], v[32:35]
	v_mfma_f32_16x16x32_bf16 v[20:23], v[192:195], v[224:227], v[20:23]
	v_mfma_f32_16x16x32_bf16 v[16:19], v[200:203], v[224:227], v[16:19]
	v_mfma_f32_16x16x32_bf16 v[4:7], v[192:195], v[232:235], v[4:7]
	v_mfma_f32_16x16x32_bf16 v[0:3], v[200:203], v[232:235], v[0:3]
	s_barrier
	s_add_u32 s0, s0, 0x100
	s_addc_u32 s1, s1, 0
	s_add_u32 s33, s33, 0x100
	s_addc_u32 s35, s35, 0
	s_cmp_ge_u32 s37, s22
	s_mov_b32 s45, s37
	s_cbranch_scc1 .Lpeel_exit_2
.LBB0_436:
	ds_read_b128 v[128:131], v180
	ds_read_b128 v[132:135], v180 offset:1024
	ds_read_b128 v[136:139], v180 offset:2048
	ds_read_b128 v[184:187], v180 offset:3072
	ds_read_b128 v[188:191], v181
	ds_read_b128 v[192:195], v181 offset:1024
	ds_read_b128 v[196:199], v181 offset:2048
	ds_read_b128 v[200:203], v181 offset:3072
	s_add_i32 s37, s45, 2
	s_add_u32 s4, s0, 0xfff80080
	s_addc_u32 s5, s1, -1
	s_cmp_eq_u32 s23, s45
	s_cselect_b32 s49, s14, s5
	s_cselect_b32 s48, s15, s4
	s_cselect_b32 s5, s16, s35
	s_cselect_b32 s4, s17, s33
	v_lshl_add_u64 v[168:169], s[0:1], 0, v[160:161]
	s_add_i32 m0, s47, 0xc000
	ds_read_b128 v[204:207], v182
	ds_read_b128 v[208:211], v182 offset:1024
	ds_read_b128 v[212:215], v182 offset:2048
	ds_read_b128 v[216:219], v182 offset:3072
	ds_read_b128 v[220:223], v182 offset:4096
	ds_read_b128 v[224:227], v182 offset:5120
	ds_read_b128 v[228:231], v182 offset:6144
	ds_read_b128 v[232:235], v182 offset:7168
	global_load_lds_dwordx4 v[168:169], off
	v_lshl_add_u64 v[168:169], s[0:1], 0, v[162:163]
	s_add_i32 m0, s47, 0xe000
	s_nop 0
	global_load_lds_dwordx4 v[168:169], off
	s_waitcnt vmcnt(8)
	s_waitcnt lgkmcnt(0)
	s_barrier
; #define PG8_STAGE(bufoff, gbase, voff) do { _Pragma("unroll") for (int _i = 0; _i < 2; ++_i) \
;         __builtin_amdgcn_global_load_lds((const unsigned*)((const char*)(gbase) + (voff)[_i]), (LAS unsigned*)(lds + (bufoff) + ldsw + _i * 8192), 16, 0, 0); } while (0)
; #define PG8_LDA(dst, b, h) do { _Pragma("unroll") for (int m = 0; m < 4; ++m) _Pragma("unroll") for (int k = 0; k < 2; ++k) dst[m][k] = *(const LAS bf16x8*)(lds + PG8_SA(b, h) + aoff + m * 2048 + k * 1024); } while (0)
; #define PG8_MMA(ai, bj, At, Bt) do { __builtin_amdgcn_s_setprio(1); _Pragma("unroll") for (int m = 0; m < 4; ++m) _Pragma("unroll") for (int n = 0; n < 2; ++n) _Pragma("unroll") for (int k = 0; k < 2; ++k) \
;         acc[ai][bj][m][n] = __builtin_amdgcn_mfma_f32_16x16x32_bf16(Bt[n][k], At[m][k], acc[ai][bj][m][n], 0, 0, 0); __builtin_amdgcn_s_setprio(0); } while (0)
; #define PG8_WAIT_V(n) asm volatile("s_waitcnt vmcnt(" #n ")" ::: "memory")
; #define PG8_WAIT_L(n) asm volatile("s_waitcnt lgkmcnt(" #n ")" ::: "memory")
; #define PG8_BAR __builtin_amdgcn_s_barrier()
; #define PG8_SCHED __builtin_amdgcn_sched_barrier(0)
; __device__ __forceinline__ void gemm_phase(LAS unsigned char* lds, const Params& p, const bf16_t* gA, const bf16_t* gBt, const int gM, const int gN, const int gK, const int epi, const int perm, bf16_t* const Hp, const int goff, const float coef) {
;     ...
;             PG8_WAIT_V(8); PG8_WAIT_L(0); PG8_BAR; PG8_MMA(0, 0, At, B0); PG8_MMA(0, 1, At, B1); PG8_BAR; PG8_SCHED;
;             PG8_LDA(At, 0, 1); PG8_STAGE(PG8_SB(0, 0), b2, voffB); PG8_STAGE(PG8_SB(0, 1), b2 + hstep, voffB); PG8_STAGE(PG8_SA(0, 0), a2, voffA);
;             PG8_WAIT_V(8); PG8_WAIT_L(0); PG8_BAR; PG8_MMA(1, 0, At, B0); PG8_MMA(1, 1, At, B1); PG8_BAR; PG8_SCHED;
	s_waitcnt lgkmcnt(0)
	v_mfma_f32_16x16x32_bf16 v[124:127], v[128:131], v[204:207], v[124:127]
	v_mfma_f32_16x16x32_bf16 v[120:123], v[136:139], v[204:207], v[120:123]
	v_mfma_f32_16x16x32_bf16 v[108:111], v[128:131], v[212:215], v[108:111]
	v_mfma_f32_16x16x32_bf16 v[104:107], v[136:139], v[212:215], v[104:107]
	v_mfma_f32_16x16x32_bf16 v[92:95], v[128:131], v[220:223], v[92:95]
	v_mfma_f32_16x16x32_bf16 v[88:91], v[136:139], v[220:223], v[88:91]
	v_mfma_f32_16x16x32_bf16 v[76:79], v[128:131], v[228:231], v[76:79]
	v_mfma_f32_16x16x32_bf16 v[72:75], v[136:139], v[228:231], v[72:75]
	v_mfma_f32_16x16x32_bf16 v[124:127], v[132:135], v[208:211], v[124:127]
	v_mfma_f32_16x16x32_bf16 v[120:123], v[184:187], v[208:211], v[120:123]
	v_mfma_f32_16x16x32_bf16 v[108:111], v[132:135], v[216:219], v[108:111]
	v_mfma_f32_16x16x32_bf16 v[104:107], v[184:187], v[216:219], v[104:107]
	v_mfma_f32_16x16x32_bf16 v[92:95], v[132:135], v[224:227], v[92:95]
	v_mfma_f32_16x16x32_bf16 v[88:91], v[184:187], v[224:227], v[88:91]
	v_mfma_f32_16x16x32_bf16 v[76:79], v[132:135], v[232:235], v[76:79]
	v_mfma_f32_16x16x32_bf16 v[72:75], v[184:187], v[232:235], v[72:75]
	v_mfma_f32_16x16x32_bf16 v[116:119], v[188:191], v[204:207], v[116:119]
	v_mfma_f32_16x16x32_bf16 v[112:115], v[196:199], v[204:207], v[112:115]
	v_mfma_f32_16x16x32_bf16 v[100:103], v[188:191], v[212:215], v[100:103]
	v_mfma_f32_16x16x32_bf16 v[96:99], v[196:199], v[212:215], v[96:99]
	v_mfma_f32_16x16x32_bf16 v[84:87], v[188:191], v[220:223], v[84:87]
	v_mfma_f32_16x16x32_bf16 v[80:83], v[196:199], v[220:223], v[80:83]
	v_mfma_f32_16x16x32_bf16 v[68:71], v[188:191], v[228:231], v[68:71]
	v_mfma_f32_16x16x32_bf16 v[64:67], v[196:199], v[228:231], v[64:67]
	v_mfma_f32_16x16x32_bf16 v[116:119], v[192:195], v[208:211], v[116:119]
	v_mfma_f32_16x16x32_bf16 v[112:115], v[200:203], v[208:211], v[112:115]
	v_mfma_f32_16x16x32_bf16 v[100:103], v[192:195], v[216:219], v[100:103]
	v_mfma_f32_16x16x32_bf16 v[96:99], v[200:203], v[216:219], v[96:99]
	v_mfma_f32_16x16x32_bf16 v[84:87], v[192:195], v[224:227], v[84:87]
	v_mfma_f32_16x16x32_bf16 v[80:83], v[200:203], v[224:227], v[80:83]
	v_mfma_f32_16x16x32_bf16 v[68:71], v[192:195], v[232:235], v[68:71]
	v_mfma_f32_16x16x32_bf16 v[64:67], v[200:203], v[232:235], v[64:67]
	s_barrier
	s_add_i32 s45, s19, s52
	v_lshl_add_u64 v[168:169], s[4:5], 0, v[144:145]
	s_mov_b32 m0, s45
	ds_read_b128 v[204:207], v182 offset:16384
	ds_read_b128 v[208:211], v182 offset:17408
	ds_read_b128 v[212:215], v182 offset:18432
	ds_read_b128 v[216:219], v182 offset:19456
	ds_read_b128 v[220:223], v182 offset:20480
	ds_read_b128 v[224:227], v182 offset:21504
	ds_read_b128 v[228:231], v182 offset:22528
	ds_read_b128 v[232:235], v182 offset:23552
	global_load_lds_dwordx4 v[168:169], off
	s_add_i32 m0, s45, 0x2000
	s_add_u32 s50, s4, 0x80000
	v_lshl_add_u64 v[236:237], s[4:5], 0, v[148:149]
	s_addc_u32 s51, s5, 0
	s_add_i32 s45, s21, s52
	global_load_lds_dwordx4 v[236:237], off
	v_lshl_add_u64 v[238:239], s[50:51], 0, v[144:145]
	s_mov_b32 m0, s45
	v_lshl_add_u64 v[240:241], s[48:49], 0, v[146:147]
	global_load_lds_dwordx4 v[238:239], off
	v_lshl_add_u64 v[238:239], s[50:51], 0, v[148:149]
	s_add_i32 m0, s45, 0x2000
	s_nop 0
	global_load_lds_dwordx4 v[238:239], off
	v_lshl_add_u64 v[238:239], s[48:49], 0, v[142:143]
	s_mov_b32 m0, s47
	s_nop 0
	global_load_lds_dwordx4 v[238:239], off
	s_mov_b32 m0, s53
	s_nop 0
	global_load_lds_dwordx4 v[240:241], off
	s_waitcnt vmcnt(8)
	s_waitcnt lgkmcnt(0)
	s_barrier
	s_waitcnt lgkmcnt(0)
	v_mfma_f32_16x16x32_bf16 v[60:63], v[128:131], v[204:207], v[60:63]
	v_mfma_f32_16x16x32_bf16 v[56:59], v[136:139], v[204:207], v[56:59]
	v_mfma_f32_16x16x32_bf16 v[44:47], v[128:131], v[212:215], v[44:47]
	v_mfma_f32_16x16x32_bf16 v[40:43], v[136:139], v[212:215], v[40:43]
	v_mfma_f32_16x16x32_bf16 v[28:31], v[128:131], v[220:223], v[28:31]
	v_mfma_f32_16x16x32_bf16 v[24:27], v[136:139], v[220:223], v[24:27]
	v_mfma_f32_16x16x32_bf16 v[12:15], v[128:131], v[228:231], v[12:15]
	v_mfma_f32_16x16x32_bf16 v[8:11], v[136:139], v[228:231], v[8:11]
	v_mfma_f32_16x16x32_bf16 v[60:63], v[132:135], v[208:211], v[60:63]
	v_mfma_f32_16x16x32_bf16 v[56:59], v[184:187], v[208:211], v[56:59]
	v_mfma_f32_16x16x32_bf16 v[44:47], v[132:135], v[216:219], v[44:47]
	v_mfma_f32_16x16x32_bf16 v[40:43], v[184:187], v[216:219], v[40:43]
	v_mfma_f32_16x16x32_bf16 v[28:31], v[132:135], v[224:227], v[28:31]
	v_mfma_f32_16x16x32_bf16 v[24:27], v[184:187], v[224:227], v[24:27]
	v_mfma_f32_16x16x32_bf16 v[12:15], v[132:135], v[232:235], v[12:15]
	v_mfma_f32_16x16x32_bf16 v[8:11], v[184:187], v[232:235], v[8:11]
	v_mfma_f32_16x16x32_bf16 v[52:55], v[188:191], v[204:207], v[52:55]
	v_mfma_f32_16x16x32_bf16 v[48:51], v[196:199], v[204:207], v[48:51]
	v_mfma_f32_16x16x32_bf16 v[36:39], v[188:191], v[212:215], v[36:39]
	v_mfma_f32_16x16x32_bf16 v[32:35], v[196:199], v[212:215], v[32:35]
	v_mfma_f32_16x16x32_bf16 v[20:23], v[188:191], v[220:223], v[20:23]
	v_mfma_f32_16x16x32_bf16 v[16:19], v[196:199], v[220:223], v[16:19]
	v_mfma_f32_16x16x32_bf16 v[4:7], v[188:191], v[228:231], v[4:7]
	v_mfma_f32_16x16x32_bf16 v[0:3], v[196:199], v[228:231], v[0:3]
	v_mfma_f32_16x16x32_bf16 v[52:55], v[192:195], v[208:211], v[52:55]
	v_mfma_f32_16x16x32_bf16 v[48:51], v[200:203], v[208:211], v[48:51]
	v_mfma_f32_16x16x32_bf16 v[36:39], v[192:195], v[216:219], v[36:39]
	v_mfma_f32_16x16x32_bf16 v[32:35], v[200:203], v[216:219], v[32:35]
	v_mfma_f32_16x16x32_bf16 v[20:23], v[192:195], v[224:227], v[20:23]
	v_mfma_f32_16x16x32_bf16 v[16:19], v[200:203], v[224:227], v[16:19]
	v_mfma_f32_16x16x32_bf16 v[4:7], v[192:195], v[232:235], v[4:7]
	v_mfma_f32_16x16x32_bf16 v[0:3], v[200:203], v[232:235], v[0:3]
	s_barrier
; #define PG8_STAGE(bufoff, gbase, voff) do { _Pragma("unroll") for (int _i = 0; _i < 2; ++_i) \
;         __builtin_amdgcn_global_load_lds((const unsigned*)((const char*)(gbase) + (voff)[_i]), (LAS unsigned*)(lds + (bufoff) + ldsw + _i * 8192), 16, 0, 0); } while (0)
; #define PG8_LDA(dst, b, h) do { _Pragma("unroll") for (int m = 0; m < 4; ++m) _Pragma("unroll") for (int k = 0; k < 2; ++k) dst[m][k] = *(const LAS bf16x8*)(lds + PG8_SA(b, h) + aoff + m * 2048 + k * 1024); } while (0)
; #define PG8_LDB(dst, b, h) do { _Pragma("unroll") for (int n = 0; n < 2; ++n) _Pragma("unroll") for (int k = 0; k < 2; ++k) dst[n][k] = *(const LAS bf16x8*)(lds + PG8_SB(b, h) + boff + n * 2048 + k * 1024); } while (0)
; #define PG8_MMA(ai, bj, At, Bt) do { __builtin_amdgcn_s_setprio(1); _Pragma("unroll") for (int m = 0; m < 4; ++m) _Pragma("unroll") for (int n = 0; n < 2; ++n) _Pragma("unroll") for (int k = 0; k < 2; ++k) \
;         acc[ai][bj][m][n] = __builtin_amdgcn_mfma_f32_16x16x32_bf16(Bt[n][k], At[m][k], acc[ai][bj][m][n], 0, 0, 0); __builtin_amdgcn_s_setprio(0); } while (0)
; #define PG8_WAIT_V(n) asm volatile("s_waitcnt vmcnt(" #n ")" ::: "memory")
; #define PG8_WAIT_L(n) asm volatile("s_waitcnt lgkmcnt(" #n ")" ::: "memory")
; #define PG8_BAR __builtin_amdgcn_s_barrier()
; #define PG8_SCHED __builtin_amdgcn_sched_barrier(0)
; __device__ __forceinline__ void gemm_phase(LAS unsigned char* lds, const Params& p, const bf16_t* gA, const bf16_t* gBt, const int gM, const int gN, const int gK, const int epi, const int perm, bf16_t* const Hp, const int goff, const float coef) {
;     ...
;             PG8_LDB(B0, 1, 0); PG8_LDB(B1, 1, 1); PG8_SCHED; PG8_LDA(At, 1, 0); PG8_STAGE(PG8_SA(0, 1), a2 + hstep, voffA);
;             PG8_WAIT_V(8); PG8_WAIT_L(0); PG8_BAR; PG8_MMA(0, 0, At, B0); PG8_MMA(0, 1, At, B1); PG8_BAR; PG8_SCHED;
;             PG8_LDA(At, 1, 1); PG8_STAGE(PG8_SB(1, 0), b3, voffB); PG8_STAGE(PG8_SB(1, 1), b3 + hstep, voffB); PG8_STAGE(PG8_SA(1, 0), a3, voffA);
;             PG8_WAIT_V(8); PG8_WAIT_L(0); PG8_BAR; PG8_MMA(1, 0, At, B0); PG8_MMA(1, 1, At, B1); PG8_BAR; PG8_SCHED;
	s_add_i32 s45, 0, 0x18000
	v_add_u32_e32 v150, s45, v171
	s_add_i32 s50, 0, 0x1c000
	ds_read_b128 v[128:131], v150
	ds_read_b128 v[132:135], v150 offset:1024
	ds_read_b128 v[136:139], v150 offset:2048
	ds_read_b128 v[184:187], v150 offset:3072
	v_add_u32_e32 v150, s50, v171
	ds_read_b128 v[188:191], v150
	ds_read_b128 v[192:195], v150 offset:1024
	ds_read_b128 v[196:199], v150 offset:2048
	ds_read_b128 v[200:203], v150 offset:3072
	s_add_u32 s48, s48, 0x80000
	s_addc_u32 s49, s49, 0
	s_mov_b32 m0, s54
	v_lshl_add_u64 v[242:243], s[48:49], 0, v[142:143]
	ds_read_b128 v[204:207], v182 offset:32768
	ds_read_b128 v[208:211], v182 offset:33792
	ds_read_b128 v[212:215], v182 offset:34816
	ds_read_b128 v[216:219], v182 offset:35840
	ds_read_b128 v[220:223], v182 offset:36864
	ds_read_b128 v[224:227], v182 offset:37888
	ds_read_b128 v[228:231], v182 offset:38912
	ds_read_b128 v[232:235], v182 offset:39936
	global_load_lds_dwordx4 v[242:243], off
	v_lshl_add_u64 v[242:243], s[48:49], 0, v[146:147]
	s_mov_b32 m0, s55
	s_nop 0
	global_load_lds_dwordx4 v[242:243], off
	s_waitcnt vmcnt(8)
	s_waitcnt lgkmcnt(0)
	s_barrier
	s_waitcnt lgkmcnt(0)
	v_mfma_f32_16x16x32_bf16 v[124:127], v[128:131], v[204:207], v[124:127]
	v_mfma_f32_16x16x32_bf16 v[120:123], v[136:139], v[204:207], v[120:123]
	v_mfma_f32_16x16x32_bf16 v[108:111], v[128:131], v[212:215], v[108:111]
	v_mfma_f32_16x16x32_bf16 v[104:107], v[136:139], v[212:215], v[104:107]
	v_mfma_f32_16x16x32_bf16 v[92:95], v[128:131], v[220:223], v[92:95]
	v_mfma_f32_16x16x32_bf16 v[88:91], v[136:139], v[220:223], v[88:91]
	v_mfma_f32_16x16x32_bf16 v[76:79], v[128:131], v[228:231], v[76:79]
	v_mfma_f32_16x16x32_bf16 v[72:75], v[136:139], v[228:231], v[72:75]
	v_mfma_f32_16x16x32_bf16 v[124:127], v[132:135], v[208:211], v[124:127]
	v_mfma_f32_16x16x32_bf16 v[120:123], v[184:187], v[208:211], v[120:123]
	v_mfma_f32_16x16x32_bf16 v[108:111], v[132:135], v[216:219], v[108:111]
	v_mfma_f32_16x16x32_bf16 v[104:107], v[184:187], v[216:219], v[104:107]
	v_mfma_f32_16x16x32_bf16 v[92:95], v[132:135], v[224:227], v[92:95]
	v_mfma_f32_16x16x32_bf16 v[88:91], v[184:187], v[224:227], v[88:91]
	v_mfma_f32_16x16x32_bf16 v[76:79], v[132:135], v[232:235], v[76:79]
	v_mfma_f32_16x16x32_bf16 v[72:75], v[184:187], v[232:235], v[72:75]
	v_mfma_f32_16x16x32_bf16 v[116:119], v[188:191], v[204:207], v[116:119]
	v_mfma_f32_16x16x32_bf16 v[112:115], v[196:199], v[204:207], v[112:115]
	v_mfma_f32_16x16x32_bf16 v[100:103], v[188:191], v[212:215], v[100:103]
	v_mfma_f32_16x16x32_bf16 v[96:99], v[196:199], v[212:215], v[96:99]
	v_mfma_f32_16x16x32_bf16 v[84:87], v[188:191], v[220:223], v[84:87]
	v_mfma_f32_16x16x32_bf16 v[80:83], v[196:199], v[220:223], v[80:83]
	v_mfma_f32_16x16x32_bf16 v[68:71], v[188:191], v[228:231], v[68:71]
	v_mfma_f32_16x16x32_bf16 v[64:67], v[196:199], v[228:231], v[64:67]
	v_mfma_f32_16x16x32_bf16 v[116:119], v[192:195], v[208:211], v[116:119]
	v_mfma_f32_16x16x32_bf16 v[112:115], v[200:203], v[208:211], v[112:115]
	v_mfma_f32_16x16x32_bf16 v[100:103], v[192:195], v[216:219], v[100:103]
	v_mfma_f32_16x16x32_bf16 v[96:99], v[200:203], v[216:219], v[96:99]
	v_mfma_f32_16x16x32_bf16 v[84:87], v[192:195], v[224:227], v[84:87]
	v_mfma_f32_16x16x32_bf16 v[80:83], v[200:203], v[224:227], v[80:83]
	v_mfma_f32_16x16x32_bf16 v[68:71], v[192:195], v[232:235], v[68:71]
	v_mfma_f32_16x16x32_bf16 v[64:67], v[200:203], v[232:235], v[64:67]
	s_barrier
	s_add_i32 s45, s45, s52
	v_lshl_add_u64 v[168:169], v[168:169], 0, s[10:11]
	s_mov_b32 m0, s45
	ds_read_b128 v[204:207], v182 offset:49152
	ds_read_b128 v[208:211], v182 offset:50176
	ds_read_b128 v[212:215], v182 offset:51200
	ds_read_b128 v[216:219], v182 offset:52224
	ds_read_b128 v[220:223], v182 offset:53248
	ds_read_b128 v[224:227], v182 offset:54272
	ds_read_b128 v[228:231], v182 offset:55296
	ds_read_b128 v[232:235], v182 offset:56320
	global_load_lds_dwordx4 v[168:169], off
	s_add_i32 m0, s45, 0x2000
	s_add_u32 s4, s4, 0x80080
	v_lshl_add_u64 v[168:169], v[236:237], 0, s[10:11]
	s_addc_u32 s5, s5, 0
	s_add_i32 s45, s50, s52
	global_load_lds_dwordx4 v[168:169], off
	v_lshl_add_u64 v[168:169], s[4:5], 0, v[144:145]
	s_mov_b32 m0, s45
	s_nop 0
	global_load_lds_dwordx4 v[168:169], off
	v_lshl_add_u64 v[168:169], s[4:5], 0, v[148:149]
	s_add_i32 m0, s45, 0x2000
	s_nop 0
	global_load_lds_dwordx4 v[168:169], off
	v_lshl_add_u64 v[168:169], v[238:239], 0, s[10:11]
	s_mov_b32 m0, s57
	s_nop 0
	global_load_lds_dwordx4 v[168:169], off
	v_lshl_add_u64 v[168:169], v[240:241], 0, s[10:11]
	s_mov_b32 m0, s58
	s_nop 0
	global_load_lds_dwordx4 v[168:169], off
	s_waitcnt vmcnt(8)
	s_waitcnt lgkmcnt(0)
	s_barrier
	s_waitcnt lgkmcnt(0)
	v_mfma_f32_16x16x32_bf16 v[60:63], v[128:131], v[204:207], v[60:63]
	v_mfma_f32_16x16x32_bf16 v[56:59], v[136:139], v[204:207], v[56:59]
	v_mfma_f32_16x16x32_bf16 v[44:47], v[128:131], v[212:215], v[44:47]
	v_mfma_f32_16x16x32_bf16 v[40:43], v[136:139], v[212:215], v[40:43]
	v_mfma_f32_16x16x32_bf16 v[28:31], v[128:131], v[220:223], v[28:31]
	v_mfma_f32_16x16x32_bf16 v[24:27], v[136:139], v[220:223], v[24:27]
	v_mfma_f32_16x16x32_bf16 v[12:15], v[128:131], v[228:231], v[12:15]
	v_mfma_f32_16x16x32_bf16 v[8:11], v[136:139], v[228:231], v[8:11]
	v_mfma_f32_16x16x32_bf16 v[60:63], v[132:135], v[208:211], v[60:63]
	v_mfma_f32_16x16x32_bf16 v[56:59], v[184:187], v[208:211], v[56:59]
	v_mfma_f32_16x16x32_bf16 v[44:47], v[132:135], v[216:219], v[44:47]
	v_mfma_f32_16x16x32_bf16 v[40:43], v[184:187], v[216:219], v[40:43]
	v_mfma_f32_16x16x32_bf16 v[28:31], v[132:135], v[224:227], v[28:31]
	v_mfma_f32_16x16x32_bf16 v[24:27], v[184:187], v[224:227], v[24:27]
	v_mfma_f32_16x16x32_bf16 v[12:15], v[132:135], v[232:235], v[12:15]
	v_mfma_f32_16x16x32_bf16 v[8:11], v[184:187], v[232:235], v[8:11]
	v_mfma_f32_16x16x32_bf16 v[52:55], v[188:191], v[204:207], v[52:55]
	v_mfma_f32_16x16x32_bf16 v[48:51], v[196:199], v[204:207], v[48:51]
	v_mfma_f32_16x16x32_bf16 v[36:39], v[188:191], v[212:215], v[36:39]
	v_mfma_f32_16x16x32_bf16 v[32:35], v[196:199], v[212:215], v[32:35]
	v_mfma_f32_16x16x32_bf16 v[20:23], v[188:191], v[220:223], v[20:23]
	v_mfma_f32_16x16x32_bf16 v[16:19], v[196:199], v[220:223], v[16:19]
	v_mfma_f32_16x16x32_bf16 v[4:7], v[188:191], v[228:231], v[4:7]
	v_mfma_f32_16x16x32_bf16 v[0:3], v[196:199], v[228:231], v[0:3]
	v_mfma_f32_16x16x32_bf16 v[52:55], v[192:195], v[208:211], v[52:55]
	v_mfma_f32_16x16x32_bf16 v[48:51], v[200:203], v[208:211], v[48:51]
	v_mfma_f32_16x16x32_bf16 v[36:39], v[192:195], v[216:219], v[36:39]
	v_mfma_f32_16x16x32_bf16 v[32:35], v[200:203], v[216:219], v[32:35]
	v_mfma_f32_16x16x32_bf16 v[20:23], v[192:195], v[224:227], v[20:23]
	v_mfma_f32_16x16x32_bf16 v[16:19], v[200:203], v[224:227], v[16:19]
	v_mfma_f32_16x16x32_bf16 v[4:7], v[192:195], v[232:235], v[4:7]
	v_mfma_f32_16x16x32_bf16 v[0:3], v[200:203], v[232:235], v[0:3]
	s_barrier
	s_add_u32 s0, s0, 0x100
	s_addc_u32 s1, s1, 0
	s_add_u32 s33, s33, 0x100
	s_addc_u32 s35, s35, 0
	s_cmp_ge_u32 s37, s22
	s_mov_b32 s45, s37
	s_cbranch_scc0 .LBB0_436
; #define PG8_BAR __builtin_amdgcn_s_barrier()
; __device__ __forceinline__ void gemm_epilogue(const Params& p, const int epi, bf16_t* const Hp, const int goff, const float coef, const f32x4 (&acc)[2][2][4][2], const pg8::Unit& u, int wr, int wc, int fr, int fq) {
;     ...
;         const int seg = u.pn >> 2;
;         const bool lat = u.pm < 128;
;         if (seg < 5) {
; __device__ __forceinline__ void gemm_phase(LAS unsigned char* lds, const Params& p, const bf16_t* gA, const bf16_t* gBt, const int gM, const int gN, const int gK, const int epi, const int perm, bf16_t* const Hp, const int goff, const float coef) {
;     ...
;         if (wr == 0) PG8_BAR;
;         gemm_epilogue(p, epi, Hp, goff, coef, acc, cur, wr, wc, fr, fq);
.Lpeel_exit_2:
	s_and_b64 vcc, exec, s[12:13]
	s_cbranch_vccnz .LBB0_440
	s_ashr_i32 s14, s46, 2
	s_cmp_gt_i32 s14, 4
	s_mov_b64 s[0:1], -1
	s_cbranch_scc1 .LBB0_441

; #define PG8_STAGE(bufoff, gbase, voff) do { _Pragma("unroll") for (int _i = 0; _i < 2; ++_i) \
;         __builtin_amdgcn_global_load_lds((const unsigned*)((const char*)(gbase) + (voff)[_i]), (LAS unsigned*)(lds + (bufoff) + ldsw + _i * 8192), 16, 0, 0); } while (0)
; #define PG8_LDA(dst, b, h) do { _Pragma("unroll") for (int m = 0; m < 4; ++m) _Pragma("unroll") for (int k = 0; k < 2; ++k) dst[m][k] = *(const LAS bf16x8*)(lds + PG8_SA(b, h) + aoff + m * 2048 + k * 1024); } while (0)
; #define PG8_LDB(dst, b, h) do { _Pragma("unroll") for (int n = 0; n < 2; ++n) _Pragma("unroll") for (int k = 0; k < 2; ++k) dst[n][k] = *(const LAS bf16x8*)(lds + PG8_SB(b, h) + boff + n * 2048 + k * 1024); } while (0)
; #define PG8_WAIT_V(n) asm volatile("s_waitcnt vmcnt(" #n ")" ::: "memory")
; #define PG8_WAIT_L(n) asm volatile("s_waitcnt lgkmcnt(" #n ")" ::: "memory")
; #define PG8_BAR __builtin_amdgcn_s_barrier()
; __device__ __forceinline__ void gemm_phase(LAS unsigned char* lds, const Params& p, const bf16_t* gA, const bf16_t* gBt, const int gM, const int gN, const int gK, const int epi, const int perm, bf16_t* const Hp, const int goff, const float coef) {
;     ...
;         const bool has_next = S.next(ui + 1, nxt);
;         const char* nA = has_next ? (const char*)gA + (size_t)nxt.pm * tstep + (nxt.ks > 0 ? nxt.ks * ksl : 0) : cA; const char* nB = has_next ? (const char*)gBt + (size_t)nxt.pn * tstep + (nxt.ks > 0 ? nxt.ks * ksl : 0) : cB;
;         const int nt = cur.ks >= 0 ? ntf / 4 : ntf;
;         for (int t = 0; t < nt; t += 2) {
;             const bool last = (t == nt - 2);
;             const char* a1 = cA + (size_t)(t + 1) * kstep;
;             const char* a2 = last ? nA : cA + (size_t)(t + 2) * kstep; const char* b2 = last ? nB : cB + (size_t)(t + 2) * kstep;
;             const char* a3 = a2 + kstep; const char* b3 = b2 + kstep;
;             PG8_LDB(B0, 0, 0); PG8_LDB(B1, 0, 1); PG8_SCHED; PG8_LDA(At, 0, 0); PG8_STAGE(PG8_SA(1, 1), a1 + hstep, voffA);
;             PG8_WAIT_V(8); PG8_WAIT_L(0); PG8_BAR; PG8_MMA(0, 0, At, B0); PG8_MMA(0, 1, At, B1); PG8_BAR; PG8_SCHED;
;             PG8_LDA(At, 0, 1); PG8_STAGE(PG8_SB(0, 0), b2, voffB); PG8_STAGE(PG8_SB(0, 1), b2 + hstep, voffB); PG8_STAGE(PG8_SA(0, 0), a2, voffA);
;             PG8_WAIT_V(8); PG8_WAIT_L(0); PG8_BAR; PG8_MMA(1, 0, At, B0); PG8_MMA(1, 1, At, B1); PG8_BAR; PG8_SCHED;
.LBB0_1592:
	s_ashr_i32 s13, s12, 31
	s_lshl_b64 s[0:1], s[12:13], 20
	s_add_u32 s13, s3, s0
	s_mov_b32 s19, s5
	s_addc_u32 s15, s33, s1
	s_lshl_b64 s[0:1], s[18:19], 10
	s_cmp_gt_i32 s18, 0
	s_cselect_b32 s22, s0, 0
	s_cselect_b32 s23, s1, 0
	s_add_u32 s20, s13, s22
	s_addc_u32 s21, s15, s23
	s_and_b64 s[0:1], s[16:17], exec
	s_cselect_b32 s13, s21, s27
	s_cselect_b32 s19, s20, s26
	s_ashr_i32 s15, s14, 31
	s_lshl_b64 s[0:1], s[14:15], 20
	s_add_u32 s0, s34, s0
	s_addc_u32 s1, s35, s1
	s_add_u32 s22, s0, s22
	s_addc_u32 s23, s1, s23
	s_and_b64 s[0:1], s[16:17], exec
	s_cselect_b32 s15, s23, s29
	s_cselect_b32 s25, s22, s28
	s_cmp_gt_i32 s4, -1
	s_cselect_b64 s[0:1], -1, 0
	s_and_b64 s[52:53], s[0:1], exec
	s_cselect_b32 s52, 8, 32
	s_add_i32 s53, s52, -2
	s_add_u32 s26, s26, 0x80080
	s_addc_u32 s27, s27, 0
	s_add_u32 s54, s28, 0x100
	s_mov_b32 s30, 0
	s_addc_u32 s55, s29, 0
	ds_read_b128 v[128:131], v174
	ds_read_b128 v[132:135], v174 offset:1024
	ds_read_b128 v[152:155], v174 offset:2048
	ds_read_b128 v[156:159], v174 offset:3072
	ds_read_b128 v[160:163], v175
	ds_read_b128 v[178:181], v175 offset:1024
	ds_read_b128 v[182:185], v175 offset:2048
	ds_read_b128 v[186:189], v175 offset:3072
	s_add_i32 s56, s30, 2
	s_add_u32 s28, s26, 0xfff80080
	s_addc_u32 s29, s27, -1
	s_cmp_eq_u32 s53, s30
	s_cselect_b32 s30, s19, s28
	s_cselect_b32 s31, s13, s29
	s_cselect_b32 s29, s15, s55
	s_cselect_b32 s28, s25, s54
	v_lshl_add_u64 v[222:223], s[26:27], 0, v[146:147]
	s_add_i32 m0, s37, 0xc000
	ds_read_b128 v[190:193], v176
	ds_read_b128 v[194:197], v176 offset:1024
	ds_read_b128 v[198:201], v176 offset:2048
	ds_read_b128 v[202:205], v176 offset:3072
	ds_read_b128 v[206:209], v176 offset:4096
	ds_read_b128 v[210:213], v176 offset:5120
	ds_read_b128 v[214:217], v176 offset:6144
	ds_read_b128 v[218:221], v176 offset:7168
	global_load_lds_dwordx4 v[222:223], off
	v_lshl_add_u64 v[222:223], s[26:27], 0, v[148:149]
	s_add_i32 m0, s37, 0xe000
	s_nop 0
	global_load_lds_dwordx4 v[222:223], off
	s_waitcnt vmcnt(8)
	s_waitcnt lgkmcnt(0)
	s_barrier
	s_waitcnt lgkmcnt(0)
	v_mfma_f32_16x16x32_bf16 v[124:127], v[128:131], v[190:193], 0
	v_mfma_f32_16x16x32_bf16 v[120:123], v[152:155], v[190:193], 0
	v_mfma_f32_16x16x32_bf16 v[116:119], v[128:131], v[198:201], 0
	v_mfma_f32_16x16x32_bf16 v[112:115], v[152:155], v[198:201], 0
	v_mfma_f32_16x16x32_bf16 v[108:111], v[128:131], v[206:209], 0
	v_mfma_f32_16x16x32_bf16 v[104:107], v[152:155], v[206:209], 0
	v_mfma_f32_16x16x32_bf16 v[100:103], v[128:131], v[214:217], 0
	v_mfma_f32_16x16x32_bf16 v[96:99], v[152:155], v[214:217], 0
	v_mfma_f32_16x16x32_bf16 v[124:127], v[132:135], v[194:197], v[124:127]
	v_mfma_f32_16x16x32_bf16 v[120:123], v[156:159], v[194:197], v[120:123]
	v_mfma_f32_16x16x32_bf16 v[116:119], v[132:135], v[202:205], v[116:119]
	v_mfma_f32_16x16x32_bf16 v[112:115], v[156:159], v[202:205], v[112:115]
	v_mfma_f32_16x16x32_bf16 v[108:111], v[132:135], v[210:213], v[108:111]
	v_mfma_f32_16x16x32_bf16 v[104:107], v[156:159], v[210:213], v[104:107]
	v_mfma_f32_16x16x32_bf16 v[100:103], v[132:135], v[218:221], v[100:103]
	v_mfma_f32_16x16x32_bf16 v[96:99], v[156:159], v[218:221], v[96:99]
	v_mfma_f32_16x16x32_bf16 v[68:71], v[160:163], v[190:193], 0
	v_mfma_f32_16x16x32_bf16 v[64:67], v[182:185], v[190:193], 0
	v_mfma_f32_16x16x32_bf16 v[52:55], v[160:163], v[198:201], 0
	v_mfma_f32_16x16x32_bf16 v[48:51], v[182:185], v[198:201], 0
	v_mfma_f32_16x16x32_bf16 v[44:47], v[160:163], v[206:209], 0
	v_mfma_f32_16x16x32_bf16 v[40:43], v[182:185], v[206:209], 0
	v_mfma_f32_16x16x32_bf16 v[36:39], v[160:163], v[214:217], 0
	v_mfma_f32_16x16x32_bf16 v[32:35], v[182:185], v[214:217], 0
	v_mfma_f32_16x16x32_bf16 v[68:71], v[178:181], v[194:197], v[68:71]
	v_mfma_f32_16x16x32_bf16 v[64:67], v[186:189], v[194:197], v[64:67]
	v_mfma_f32_16x16x32_bf16 v[52:55], v[178:181], v[202:205], v[52:55]
	v_mfma_f32_16x16x32_bf16 v[48:51], v[186:189], v[202:205], v[48:51]
	v_mfma_f32_16x16x32_bf16 v[44:47], v[178:181], v[210:213], v[44:47]
	v_mfma_f32_16x16x32_bf16 v[40:43], v[186:189], v[210:213], v[40:43]
	v_mfma_f32_16x16x32_bf16 v[36:39], v[178:181], v[218:221], v[36:39]
	v_mfma_f32_16x16x32_bf16 v[32:35], v[186:189], v[218:221], v[32:35]
	s_barrier
	s_add_i32 s57, s48, s36
	v_lshl_add_u64 v[222:223], s[28:29], 0, v[138:139]
	s_mov_b32 m0, s57
	ds_read_b128 v[190:193], v176 offset:16384
	ds_read_b128 v[194:197], v176 offset:17408
	ds_read_b128 v[198:201], v176 offset:18432
	ds_read_b128 v[202:205], v176 offset:19456
	ds_read_b128 v[206:209], v176 offset:20480
	ds_read_b128 v[210:213], v176 offset:21504
	ds_read_b128 v[214:217], v176 offset:22528
	ds_read_b128 v[218:221], v176 offset:23552
	global_load_lds_dwordx4 v[222:223], off
	s_add_i32 m0, s57, 0x2000
	s_add_u32 s58, s28, 0x80000
	v_lshl_add_u64 v[224:225], s[28:29], 0, v[144:145]
	s_addc_u32 s59, s29, 0
	s_add_i32 s57, s49, s36
	global_load_lds_dwordx4 v[224:225], off
	v_lshl_add_u64 v[226:227], s[58:59], 0, v[138:139]
	s_mov_b32 m0, s57
	v_lshl_add_u64 v[228:229], s[30:31], 0, v[142:143]
	global_load_lds_dwordx4 v[226:227], off
	v_lshl_add_u64 v[226:227], s[58:59], 0, v[144:145]
	s_add_i32 m0, s57, 0x2000
	s_nop 0
	global_load_lds_dwordx4 v[226:227], off
	v_lshl_add_u64 v[226:227], s[30:31], 0, v[136:137]
	s_mov_b32 m0, s37
	s_nop 0
	global_load_lds_dwordx4 v[226:227], off
	s_mov_b32 m0, s38
	s_nop 0
	global_load_lds_dwordx4 v[228:229], off
	s_waitcnt vmcnt(8)
	s_waitcnt lgkmcnt(0)
	s_barrier
; #define PG8_STAGE(bufoff, gbase, voff) do { _Pragma("unroll") for (int _i = 0; _i < 2; ++_i) \
;         __builtin_amdgcn_global_load_lds((const unsigned*)((const char*)(gbase) + (voff)[_i]), (LAS unsigned*)(lds + (bufoff) + ldsw + _i * 8192), 16, 0, 0); } while (0)
; #define PG8_LDA(dst, b, h) do { _Pragma("unroll") for (int m = 0; m < 4; ++m) _Pragma("unroll") for (int k = 0; k < 2; ++k) dst[m][k] = *(const LAS bf16x8*)(lds + PG8_SA(b, h) + aoff + m * 2048 + k * 1024); } while (0)
; #define PG8_LDB(dst, b, h) do { _Pragma("unroll") for (int n = 0; n < 2; ++n) _Pragma("unroll") for (int k = 0; k < 2; ++k) dst[n][k] = *(const LAS bf16x8*)(lds + PG8_SB(b, h) + boff + n * 2048 + k * 1024); } while (0)
; #define PG8_MMA(ai, bj, At, Bt) do { __builtin_amdgcn_s_setprio(1); _Pragma("unroll") for (int m = 0; m < 4; ++m) _Pragma("unroll") for (int n = 0; n < 2; ++n) _Pragma("unroll") for (int k = 0; k < 2; ++k) \
;         acc[ai][bj][m][n] = __builtin_amdgcn_mfma_f32_16x16x32_bf16(Bt[n][k], At[m][k], acc[ai][bj][m][n], 0, 0, 0); __builtin_amdgcn_s_setprio(0); } while (0)
; #define PG8_WAIT_V(n) asm volatile("s_waitcnt vmcnt(" #n ")" ::: "memory")
; #define PG8_WAIT_L(n) asm volatile("s_waitcnt lgkmcnt(" #n ")" ::: "memory")
; #define PG8_BAR __builtin_amdgcn_s_barrier()
; #define PG8_SCHED __builtin_amdgcn_sched_barrier(0)
; __device__ __forceinline__ void gemm_phase(LAS unsigned char* lds, const Params& p, const bf16_t* gA, const bf16_t* gBt, const int gM, const int gN, const int gK, const int epi, const int perm, bf16_t* const Hp, const int goff, const float coef) {
;     ...
;             PG8_WAIT_V(8); PG8_WAIT_L(0); PG8_BAR; PG8_MMA(1, 0, At, B0); PG8_MMA(1, 1, At, B1); PG8_BAR; PG8_SCHED;
;             PG8_LDB(B0, 1, 0); PG8_LDB(B1, 1, 1); PG8_SCHED; PG8_LDA(At, 1, 0); PG8_STAGE(PG8_SA(0, 1), a2 + hstep, voffA);
;             PG8_WAIT_V(8); PG8_WAIT_L(0); PG8_BAR; PG8_MMA(0, 0, At, B0); PG8_MMA(0, 1, At, B1); PG8_BAR; PG8_SCHED;
	s_waitcnt lgkmcnt(0)
	v_mfma_f32_16x16x32_bf16 v[92:95], v[128:131], v[190:193], 0
	v_mfma_f32_16x16x32_bf16 v[88:91], v[152:155], v[190:193], 0
	v_mfma_f32_16x16x32_bf16 v[84:87], v[128:131], v[198:201], 0
	v_mfma_f32_16x16x32_bf16 v[80:83], v[152:155], v[198:201], 0
	v_mfma_f32_16x16x32_bf16 v[76:79], v[128:131], v[206:209], 0
	v_mfma_f32_16x16x32_bf16 v[72:75], v[152:155], v[206:209], 0
	v_mfma_f32_16x16x32_bf16 v[60:63], v[128:131], v[214:217], 0
	v_mfma_f32_16x16x32_bf16 v[56:59], v[152:155], v[214:217], 0
	v_mfma_f32_16x16x32_bf16 v[92:95], v[132:135], v[194:197], v[92:95]
	v_mfma_f32_16x16x32_bf16 v[88:91], v[156:159], v[194:197], v[88:91]
	v_mfma_f32_16x16x32_bf16 v[84:87], v[132:135], v[202:205], v[84:87]
	v_mfma_f32_16x16x32_bf16 v[80:83], v[156:159], v[202:205], v[80:83]
	v_mfma_f32_16x16x32_bf16 v[76:79], v[132:135], v[210:213], v[76:79]
	v_mfma_f32_16x16x32_bf16 v[72:75], v[156:159], v[210:213], v[72:75]
	v_mfma_f32_16x16x32_bf16 v[60:63], v[132:135], v[218:221], v[60:63]
	v_mfma_f32_16x16x32_bf16 v[56:59], v[156:159], v[218:221], v[56:59]
	v_mfma_f32_16x16x32_bf16 v[28:31], v[160:163], v[190:193], 0
	v_mfma_f32_16x16x32_bf16 v[24:27], v[182:185], v[190:193], 0
	v_mfma_f32_16x16x32_bf16 v[20:23], v[160:163], v[198:201], 0
	v_mfma_f32_16x16x32_bf16 v[16:19], v[182:185], v[198:201], 0
	v_mfma_f32_16x16x32_bf16 v[12:15], v[160:163], v[206:209], 0
	v_mfma_f32_16x16x32_bf16 v[8:11], v[182:185], v[206:209], 0
	v_mfma_f32_16x16x32_bf16 v[4:7], v[160:163], v[214:217], 0
	v_mfma_f32_16x16x32_bf16 v[0:3], v[182:185], v[214:217], 0
	v_mfma_f32_16x16x32_bf16 v[28:31], v[178:181], v[194:197], v[28:31]
	v_mfma_f32_16x16x32_bf16 v[24:27], v[186:189], v[194:197], v[24:27]
	v_mfma_f32_16x16x32_bf16 v[20:23], v[178:181], v[202:205], v[20:23]
	v_mfma_f32_16x16x32_bf16 v[16:19], v[186:189], v[202:205], v[16:19]
	v_mfma_f32_16x16x32_bf16 v[12:15], v[178:181], v[210:213], v[12:15]
	v_mfma_f32_16x16x32_bf16 v[8:11], v[186:189], v[210:213], v[8:11]
	v_mfma_f32_16x16x32_bf16 v[4:7], v[178:181], v[218:221], v[4:7]
	v_mfma_f32_16x16x32_bf16 v[0:3], v[186:189], v[218:221], v[0:3]
	s_barrier
	s_add_i32 s57, 0, 0x18000
	v_add_u32_e32 v141, s57, v165
	s_add_i32 s58, 0, 0x1c000
	ds_read_b128 v[128:131], v141
	ds_read_b128 v[132:135], v141 offset:1024
	ds_read_b128 v[152:155], v141 offset:2048
	ds_read_b128 v[156:159], v141 offset:3072
	v_add_u32_e32 v141, s58, v165
	ds_read_b128 v[160:163], v141
	ds_read_b128 v[178:181], v141 offset:1024
	ds_read_b128 v[182:185], v141 offset:2048
	ds_read_b128 v[186:189], v141 offset:3072
	s_add_u32 s30, s30, 0x80000
	s_addc_u32 s31, s31, 0
	s_mov_b32 m0, s39
	v_lshl_add_u64 v[230:231], s[30:31], 0, v[136:137]
	ds_read_b128 v[190:193], v176 offset:32768
	ds_read_b128 v[194:197], v176 offset:33792
	ds_read_b128 v[198:201], v176 offset:34816
	ds_read_b128 v[202:205], v176 offset:35840
	ds_read_b128 v[206:209], v176 offset:36864
	ds_read_b128 v[210:213], v176 offset:37888
	ds_read_b128 v[214:217], v176 offset:38912
	ds_read_b128 v[218:221], v176 offset:39936
	global_load_lds_dwordx4 v[230:231], off
	v_lshl_add_u64 v[230:231], s[30:31], 0, v[142:143]
	s_mov_b32 m0, s40
	s_nop 0
	global_load_lds_dwordx4 v[230:231], off
	s_waitcnt vmcnt(8)
	s_waitcnt lgkmcnt(0)
	s_barrier
	s_waitcnt lgkmcnt(0)
	v_mfma_f32_16x16x32_bf16 v[124:127], v[128:131], v[190:193], v[124:127]
	v_mfma_f32_16x16x32_bf16 v[120:123], v[152:155], v[190:193], v[120:123]
	v_mfma_f32_16x16x32_bf16 v[116:119], v[128:131], v[198:201], v[116:119]
	v_mfma_f32_16x16x32_bf16 v[112:115], v[152:155], v[198:201], v[112:115]
	v_mfma_f32_16x16x32_bf16 v[108:111], v[128:131], v[206:209], v[108:111]
	v_mfma_f32_16x16x32_bf16 v[104:107], v[152:155], v[206:209], v[104:107]
	v_mfma_f32_16x16x32_bf16 v[100:103], v[128:131], v[214:217], v[100:103]
	v_mfma_f32_16x16x32_bf16 v[96:99], v[152:155], v[214:217], v[96:99]
	v_mfma_f32_16x16x32_bf16 v[124:127], v[132:135], v[194:197], v[124:127]
	v_mfma_f32_16x16x32_bf16 v[120:123], v[156:159], v[194:197], v[120:123]
	v_mfma_f32_16x16x32_bf16 v[116:119], v[132:135], v[202:205], v[116:119]
	v_mfma_f32_16x16x32_bf16 v[112:115], v[156:159], v[202:205], v[112:115]
	v_mfma_f32_16x16x32_bf16 v[108:111], v[132:135], v[210:213], v[108:111]
	v_mfma_f32_16x16x32_bf16 v[104:107], v[156:159], v[210:213], v[104:107]
	v_mfma_f32_16x16x32_bf16 v[100:103], v[132:135], v[218:221], v[100:103]
	v_mfma_f32_16x16x32_bf16 v[96:99], v[156:159], v[218:221], v[96:99]
	v_mfma_f32_16x16x32_bf16 v[68:71], v[160:163], v[190:193], v[68:71]
	v_mfma_f32_16x16x32_bf16 v[64:67], v[182:185], v[190:193], v[64:67]
	v_mfma_f32_16x16x32_bf16 v[52:55], v[160:163], v[198:201], v[52:55]
	v_mfma_f32_16x16x32_bf16 v[48:51], v[182:185], v[198:201], v[48:51]
	v_mfma_f32_16x16x32_bf16 v[44:47], v[160:163], v[206:209], v[44:47]
	v_mfma_f32_16x16x32_bf16 v[40:43], v[182:185], v[206:209], v[40:43]
	v_mfma_f32_16x16x32_bf16 v[36:39], v[160:163], v[214:217], v[36:39]
	v_mfma_f32_16x16x32_bf16 v[32:35], v[182:185], v[214:217], v[32:35]
	v_mfma_f32_16x16x32_bf16 v[68:71], v[178:181], v[194:197], v[68:71]
	v_mfma_f32_16x16x32_bf16 v[64:67], v[186:189], v[194:197], v[64:67]
	v_mfma_f32_16x16x32_bf16 v[52:55], v[178:181], v[202:205], v[52:55]
	v_mfma_f32_16x16x32_bf16 v[48:51], v[186:189], v[202:205], v[48:51]
	v_mfma_f32_16x16x32_bf16 v[44:47], v[178:181], v[210:213], v[44:47]
	v_mfma_f32_16x16x32_bf16 v[40:43], v[186:189], v[210:213], v[40:43]
	v_mfma_f32_16x16x32_bf16 v[36:39], v[178:181], v[218:221], v[36:39]
	v_mfma_f32_16x16x32_bf16 v[32:35], v[186:189], v[218:221], v[32:35]
	s_barrier
; #define PG8_STAGE(bufoff, gbase, voff) do { _Pragma("unroll") for (int _i = 0; _i < 2; ++_i) \
;         __builtin_amdgcn_global_load_lds((const unsigned*)((const char*)(gbase) + (voff)[_i]), (LAS unsigned*)(lds + (bufoff) + ldsw + _i * 8192), 16, 0, 0); } while (0)
; #define PG8_LDA(dst, b, h) do { _Pragma("unroll") for (int m = 0; m < 4; ++m) _Pragma("unroll") for (int k = 0; k < 2; ++k) dst[m][k] = *(const LAS bf16x8*)(lds + PG8_SA(b, h) + aoff + m * 2048 + k * 1024); } while (0)
; #define PG8_LDB(dst, b, h) do { _Pragma("unroll") for (int n = 0; n < 2; ++n) _Pragma("unroll") for (int k = 0; k < 2; ++k) dst[n][k] = *(const LAS bf16x8*)(lds + PG8_SB(b, h) + boff + n * 2048 + k * 1024); } while (0)
; #define PG8_BAR __builtin_amdgcn_s_barrier()
; __device__ __forceinline__ void gemm_phase(LAS unsigned char* lds, const Params& p, const bf16_t* gA, const bf16_t* gBt, const int gM, const int gN, const int gK, const int epi, const int perm, bf16_t* const Hp, const int goff, const float coef) {
;     ...
;         for (int t = 0; t < nt; t += 2) {
;             const bool last = (t == nt - 2);
;             const char* a1 = cA + (size_t)(t + 1) * kstep;
;             const char* a2 = last ? nA : cA + (size_t)(t + 2) * kstep; const char* b2 = last ? nB : cB + (size_t)(t + 2) * kstep;
;             const char* a3 = a2 + kstep; const char* b3 = b2 + kstep;
;             PG8_LDB(B0, 0, 0); PG8_LDB(B1, 0, 1); PG8_SCHED; PG8_LDA(At, 0, 0); PG8_STAGE(PG8_SA(1, 1), a1 + hstep, voffA);
;             PG8_WAIT_V(8); PG8_WAIT_L(0); PG8_BAR; PG8_MMA(0, 0, At, B0); PG8_MMA(0, 1, At, B1); PG8_BAR; PG8_SCHED;
;             PG8_LDA(At, 0, 1); PG8_STAGE(PG8_SB(0, 0), b2, voffB); PG8_STAGE(PG8_SB(0, 1), b2 + hstep, voffB); PG8_STAGE(PG8_SA(0, 0), a2, voffA);
;             PG8_WAIT_V(8); PG8_WAIT_L(0); PG8_BAR; PG8_MMA(1, 0, At, B0); PG8_MMA(1, 1, At, B1); PG8_BAR; PG8_SCHED;
;             PG8_LDB(B0, 1, 0); PG8_LDB(B1, 1, 1); PG8_SCHED; PG8_LDA(At, 1, 0); PG8_STAGE(PG8_SA(0, 1), a2 + hstep, voffA);
;             PG8_WAIT_V(8); PG8_WAIT_L(0); PG8_BAR; PG8_MMA(0, 0, At, B0); PG8_MMA(0, 1, At, B1); PG8_BAR; PG8_SCHED;
;             PG8_LDA(At, 1, 1); PG8_STAGE(PG8_SB(1, 0), b3, voffB); PG8_STAGE(PG8_SB(1, 1), b3 + hstep, voffB); PG8_STAGE(PG8_SA(1, 0), a3, voffA);
;             PG8_WAIT_V(8); PG8_WAIT_L(0); PG8_BAR; PG8_MMA(1, 0, At, B0); PG8_MMA(1, 1, At, B1); PG8_BAR; PG8_SCHED;
	s_add_i32 s30, s57, s36
	v_lshl_add_u64 v[222:223], v[222:223], 0, s[8:9]
	s_mov_b32 m0, s30
	ds_read_b128 v[190:193], v176 offset:49152
	ds_read_b128 v[194:197], v176 offset:50176
	ds_read_b128 v[198:201], v176 offset:51200
	ds_read_b128 v[202:205], v176 offset:52224
	ds_read_b128 v[206:209], v176 offset:53248
	ds_read_b128 v[210:213], v176 offset:54272
	ds_read_b128 v[214:217], v176 offset:55296
	ds_read_b128 v[218:221], v176 offset:56320
	global_load_lds_dwordx4 v[222:223], off
	s_add_i32 m0, s30, 0x2000
	s_add_u32 s28, s28, 0x80080
	v_lshl_add_u64 v[222:223], v[224:225], 0, s[8:9]
	s_addc_u32 s29, s29, 0
	s_add_i32 s30, s58, s36
	global_load_lds_dwordx4 v[222:223], off
	v_lshl_add_u64 v[222:223], s[28:29], 0, v[138:139]
	s_mov_b32 m0, s30
	s_nop 0
	global_load_lds_dwordx4 v[222:223], off
	v_lshl_add_u64 v[222:223], s[28:29], 0, v[144:145]
	s_add_i32 m0, s30, 0x2000
	s_nop 0
	global_load_lds_dwordx4 v[222:223], off
	v_lshl_add_u64 v[222:223], v[226:227], 0, s[8:9]
	s_mov_b32 m0, s44
	s_nop 0
	global_load_lds_dwordx4 v[222:223], off
	v_lshl_add_u64 v[222:223], v[228:229], 0, s[8:9]
	s_mov_b32 m0, s45
	s_nop 0
	global_load_lds_dwordx4 v[222:223], off
	s_waitcnt vmcnt(8)
	s_waitcnt lgkmcnt(0)
	s_barrier
	s_waitcnt lgkmcnt(0)
	v_mfma_f32_16x16x32_bf16 v[92:95], v[128:131], v[190:193], v[92:95]
	v_mfma_f32_16x16x32_bf16 v[88:91], v[152:155], v[190:193], v[88:91]
	v_mfma_f32_16x16x32_bf16 v[84:87], v[128:131], v[198:201], v[84:87]
	v_mfma_f32_16x16x32_bf16 v[80:83], v[152:155], v[198:201], v[80:83]
	v_mfma_f32_16x16x32_bf16 v[76:79], v[128:131], v[206:209], v[76:79]
	v_mfma_f32_16x16x32_bf16 v[72:75], v[152:155], v[206:209], v[72:75]
	v_mfma_f32_16x16x32_bf16 v[60:63], v[128:131], v[214:217], v[60:63]
	v_mfma_f32_16x16x32_bf16 v[56:59], v[152:155], v[214:217], v[56:59]
	v_mfma_f32_16x16x32_bf16 v[92:95], v[132:135], v[194:197], v[92:95]
	v_mfma_f32_16x16x32_bf16 v[88:91], v[156:159], v[194:197], v[88:91]
	v_mfma_f32_16x16x32_bf16 v[84:87], v[132:135], v[202:205], v[84:87]
	v_mfma_f32_16x16x32_bf16 v[80:83], v[156:159], v[202:205], v[80:83]
	v_mfma_f32_16x16x32_bf16 v[76:79], v[132:135], v[210:213], v[76:79]
	v_mfma_f32_16x16x32_bf16 v[72:75], v[156:159], v[210:213], v[72:75]
	v_mfma_f32_16x16x32_bf16 v[60:63], v[132:135], v[218:221], v[60:63]
	v_mfma_f32_16x16x32_bf16 v[56:59], v[156:159], v[218:221], v[56:59]
	v_mfma_f32_16x16x32_bf16 v[28:31], v[160:163], v[190:193], v[28:31]
	v_mfma_f32_16x16x32_bf16 v[24:27], v[182:185], v[190:193], v[24:27]
	v_mfma_f32_16x16x32_bf16 v[20:23], v[160:163], v[198:201], v[20:23]
	v_mfma_f32_16x16x32_bf16 v[16:19], v[182:185], v[198:201], v[16:19]
	v_mfma_f32_16x16x32_bf16 v[12:15], v[160:163], v[206:209], v[12:15]
	v_mfma_f32_16x16x32_bf16 v[8:11], v[182:185], v[206:209], v[8:11]
	v_mfma_f32_16x16x32_bf16 v[4:7], v[160:163], v[214:217], v[4:7]
	v_mfma_f32_16x16x32_bf16 v[0:3], v[182:185], v[214:217], v[0:3]
	v_mfma_f32_16x16x32_bf16 v[28:31], v[178:181], v[194:197], v[28:31]
	v_mfma_f32_16x16x32_bf16 v[24:27], v[186:189], v[194:197], v[24:27]
	v_mfma_f32_16x16x32_bf16 v[20:23], v[178:181], v[202:205], v[20:23]
	v_mfma_f32_16x16x32_bf16 v[16:19], v[186:189], v[202:205], v[16:19]
	v_mfma_f32_16x16x32_bf16 v[12:15], v[178:181], v[210:213], v[12:15]
	v_mfma_f32_16x16x32_bf16 v[8:11], v[186:189], v[210:213], v[8:11]
	v_mfma_f32_16x16x32_bf16 v[4:7], v[178:181], v[218:221], v[4:7]
	v_mfma_f32_16x16x32_bf16 v[0:3], v[186:189], v[218:221], v[0:3]
	s_barrier
	s_add_u32 s26, s26, 0x100
	s_addc_u32 s27, s27, 0
	s_add_u32 s54, s54, 0x100
	s_addc_u32 s55, s55, 0
	s_cmp_ge_u32 s56, s52
	s_mov_b32 s30, s56
	s_cbranch_scc1 .Lpeel_exit_3
.LBB0_1593:
	ds_read_b128 v[128:131], v174
	ds_read_b128 v[132:135], v174 offset:1024
	ds_read_b128 v[152:155], v174 offset:2048
	ds_read_b128 v[156:159], v174 offset:3072
	ds_read_b128 v[160:163], v175
	ds_read_b128 v[178:181], v175 offset:1024
	ds_read_b128 v[182:185], v175 offset:2048
	ds_read_b128 v[186:189], v175 offset:3072
	s_add_i32 s56, s30, 2
	s_add_u32 s28, s26, 0xfff80080
	s_addc_u32 s29, s27, -1
	s_cmp_eq_u32 s53, s30
	s_cselect_b32 s30, s19, s28
	s_cselect_b32 s31, s13, s29
	s_cselect_b32 s29, s15, s55
	s_cselect_b32 s28, s25, s54
	v_lshl_add_u64 v[222:223], s[26:27], 0, v[146:147]
	s_add_i32 m0, s37, 0xc000
	ds_read_b128 v[190:193], v176
	ds_read_b128 v[194:197], v176 offset:1024
	ds_read_b128 v[198:201], v176 offset:2048
	ds_read_b128 v[202:205], v176 offset:3072
	ds_read_b128 v[206:209], v176 offset:4096
	ds_read_b128 v[210:213], v176 offset:5120
	ds_read_b128 v[214:217], v176 offset:6144
	ds_read_b128 v[218:221], v176 offset:7168
	global_load_lds_dwordx4 v[222:223], off
	v_lshl_add_u64 v[222:223], s[26:27], 0, v[148:149]
	s_add_i32 m0, s37, 0xe000
	s_nop 0
	global_load_lds_dwordx4 v[222:223], off
	s_waitcnt vmcnt(8)
	s_waitcnt lgkmcnt(0)
	s_barrier
; #define PG8_STAGE(bufoff, gbase, voff) do { _Pragma("unroll") for (int _i = 0; _i < 2; ++_i) \
;         __builtin_amdgcn_global_load_lds((const unsigned*)((const char*)(gbase) + (voff)[_i]), (LAS unsigned*)(lds + (bufoff) + ldsw + _i * 8192), 16, 0, 0); } while (0)
; #define PG8_LDA(dst, b, h) do { _Pragma("unroll") for (int m = 0; m < 4; ++m) _Pragma("unroll") for (int k = 0; k < 2; ++k) dst[m][k] = *(const LAS bf16x8*)(lds + PG8_SA(b, h) + aoff + m * 2048 + k * 1024); } while (0)
; #define PG8_MMA(ai, bj, At, Bt) do { __builtin_amdgcn_s_setprio(1); _Pragma("unroll") for (int m = 0; m < 4; ++m) _Pragma("unroll") for (int n = 0; n < 2; ++n) _Pragma("unroll") for (int k = 0; k < 2; ++k) \
;         acc[ai][bj][m][n] = __builtin_amdgcn_mfma_f32_16x16x32_bf16(Bt[n][k], At[m][k], acc[ai][bj][m][n], 0, 0, 0); __builtin_amdgcn_s_setprio(0); } while (0)
; #define PG8_WAIT_V(n) asm volatile("s_waitcnt vmcnt(" #n ")" ::: "memory")
; #define PG8_WAIT_L(n) asm volatile("s_waitcnt lgkmcnt(" #n ")" ::: "memory")
; #define PG8_BAR __builtin_amdgcn_s_barrier()
; #define PG8_SCHED __builtin_amdgcn_sched_barrier(0)
; __device__ __forceinline__ void gemm_phase(LAS unsigned char* lds, const Params& p, const bf16_t* gA, const bf16_t* gBt, const int gM, const int gN, const int gK, const int epi, const int perm, bf16_t* const Hp, const int goff, const float coef) {
;     ...
;             PG8_WAIT_V(8); PG8_WAIT_L(0); PG8_BAR; PG8_MMA(0, 0, At, B0); PG8_MMA(0, 1, At, B1); PG8_BAR; PG8_SCHED;
;             PG8_LDA(At, 0, 1); PG8_STAGE(PG8_SB(0, 0), b2, voffB); PG8_STAGE(PG8_SB(0, 1), b2 + hstep, voffB); PG8_STAGE(PG8_SA(0, 0), a2, voffA);
;             PG8_WAIT_V(8); PG8_WAIT_L(0); PG8_BAR; PG8_MMA(1, 0, At, B0); PG8_MMA(1, 1, At, B1); PG8_BAR; PG8_SCHED;
	s_waitcnt lgkmcnt(0)
	v_mfma_f32_16x16x32_bf16 v[124:127], v[128:131], v[190:193], v[124:127]
	v_mfma_f32_16x16x32_bf16 v[120:123], v[152:155], v[190:193], v[120:123]
	v_mfma_f32_16x16x32_bf16 v[116:119], v[128:131], v[198:201], v[116:119]
	v_mfma_f32_16x16x32_bf16 v[112:115], v[152:155], v[198:201], v[112:115]
	v_mfma_f32_16x16x32_bf16 v[108:111], v[128:131], v[206:209], v[108:111]
	v_mfma_f32_16x16x32_bf16 v[104:107], v[152:155], v[206:209], v[104:107]
	v_mfma_f32_16x16x32_bf16 v[100:103], v[128:131], v[214:217], v[100:103]
	v_mfma_f32_16x16x32_bf16 v[96:99], v[152:155], v[214:217], v[96:99]
	v_mfma_f32_16x16x32_bf16 v[124:127], v[132:135], v[194:197], v[124:127]
	v_mfma_f32_16x16x32_bf16 v[120:123], v[156:159], v[194:197], v[120:123]
	v_mfma_f32_16x16x32_bf16 v[116:119], v[132:135], v[202:205], v[116:119]
	v_mfma_f32_16x16x32_bf16 v[112:115], v[156:159], v[202:205], v[112:115]
	v_mfma_f32_16x16x32_bf16 v[108:111], v[132:135], v[210:213], v[108:111]
	v_mfma_f32_16x16x32_bf16 v[104:107], v[156:159], v[210:213], v[104:107]
	v_mfma_f32_16x16x32_bf16 v[100:103], v[132:135], v[218:221], v[100:103]
	v_mfma_f32_16x16x32_bf16 v[96:99], v[156:159], v[218:221], v[96:99]
	v_mfma_f32_16x16x32_bf16 v[68:71], v[160:163], v[190:193], v[68:71]
	v_mfma_f32_16x16x32_bf16 v[64:67], v[182:185], v[190:193], v[64:67]
	v_mfma_f32_16x16x32_bf16 v[52:55], v[160:163], v[198:201], v[52:55]
	v_mfma_f32_16x16x32_bf16 v[48:51], v[182:185], v[198:201], v[48:51]
	v_mfma_f32_16x16x32_bf16 v[44:47], v[160:163], v[206:209], v[44:47]
	v_mfma_f32_16x16x32_bf16 v[40:43], v[182:185], v[206:209], v[40:43]
	v_mfma_f32_16x16x32_bf16 v[36:39], v[160:163], v[214:217], v[36:39]
	v_mfma_f32_16x16x32_bf16 v[32:35], v[182:185], v[214:217], v[32:35]
	v_mfma_f32_16x16x32_bf16 v[68:71], v[178:181], v[194:197], v[68:71]
	v_mfma_f32_16x16x32_bf16 v[64:67], v[186:189], v[194:197], v[64:67]
	v_mfma_f32_16x16x32_bf16 v[52:55], v[178:181], v[202:205], v[52:55]
	v_mfma_f32_16x16x32_bf16 v[48:51], v[186:189], v[202:205], v[48:51]
	v_mfma_f32_16x16x32_bf16 v[44:47], v[178:181], v[210:213], v[44:47]
	v_mfma_f32_16x16x32_bf16 v[40:43], v[186:189], v[210:213], v[40:43]
	v_mfma_f32_16x16x32_bf16 v[36:39], v[178:181], v[218:221], v[36:39]
	v_mfma_f32_16x16x32_bf16 v[32:35], v[186:189], v[218:221], v[32:35]
	s_barrier
	s_add_i32 s57, s48, s36
	v_lshl_add_u64 v[222:223], s[28:29], 0, v[138:139]
	s_mov_b32 m0, s57
	ds_read_b128 v[190:193], v176 offset:16384
	ds_read_b128 v[194:197], v176 offset:17408
	ds_read_b128 v[198:201], v176 offset:18432
	ds_read_b128 v[202:205], v176 offset:19456
	ds_read_b128 v[206:209], v176 offset:20480
	ds_read_b128 v[210:213], v176 offset:21504
	ds_read_b128 v[214:217], v176 offset:22528
	ds_read_b128 v[218:221], v176 offset:23552
	global_load_lds_dwordx4 v[222:223], off
	s_add_i32 m0, s57, 0x2000
	s_add_u32 s58, s28, 0x80000
	v_lshl_add_u64 v[224:225], s[28:29], 0, v[144:145]
	s_addc_u32 s59, s29, 0
	s_add_i32 s57, s49, s36
	global_load_lds_dwordx4 v[224:225], off
	v_lshl_add_u64 v[226:227], s[58:59], 0, v[138:139]
	s_mov_b32 m0, s57
	v_lshl_add_u64 v[228:229], s[30:31], 0, v[142:143]
	global_load_lds_dwordx4 v[226:227], off
	v_lshl_add_u64 v[226:227], s[58:59], 0, v[144:145]
	s_add_i32 m0, s57, 0x2000
	s_nop 0
	global_load_lds_dwordx4 v[226:227], off
	v_lshl_add_u64 v[226:227], s[30:31], 0, v[136:137]
	s_mov_b32 m0, s37
	s_nop 0
	global_load_lds_dwordx4 v[226:227], off
	s_mov_b32 m0, s38
	s_nop 0
	global_load_lds_dwordx4 v[228:229], off
	s_waitcnt vmcnt(8)
	s_waitcnt lgkmcnt(0)
	s_barrier
	s_waitcnt lgkmcnt(0)
	v_mfma_f32_16x16x32_bf16 v[92:95], v[128:131], v[190:193], v[92:95]
	v_mfma_f32_16x16x32_bf16 v[88:91], v[152:155], v[190:193], v[88:91]
	v_mfma_f32_16x16x32_bf16 v[84:87], v[128:131], v[198:201], v[84:87]
	v_mfma_f32_16x16x32_bf16 v[80:83], v[152:155], v[198:201], v[80:83]
	v_mfma_f32_16x16x32_bf16 v[76:79], v[128:131], v[206:209], v[76:79]
	v_mfma_f32_16x16x32_bf16 v[72:75], v[152:155], v[206:209], v[72:75]
	v_mfma_f32_16x16x32_bf16 v[60:63], v[128:131], v[214:217], v[60:63]
	v_mfma_f32_16x16x32_bf16 v[56:59], v[152:155], v[214:217], v[56:59]
	v_mfma_f32_16x16x32_bf16 v[92:95], v[132:135], v[194:197], v[92:95]
	v_mfma_f32_16x16x32_bf16 v[88:91], v[156:159], v[194:197], v[88:91]
	v_mfma_f32_16x16x32_bf16 v[84:87], v[132:135], v[202:205], v[84:87]
	v_mfma_f32_16x16x32_bf16 v[80:83], v[156:159], v[202:205], v[80:83]
	v_mfma_f32_16x16x32_bf16 v[76:79], v[132:135], v[210:213], v[76:79]
	v_mfma_f32_16x16x32_bf16 v[72:75], v[156:159], v[210:213], v[72:75]
	v_mfma_f32_16x16x32_bf16 v[60:63], v[132:135], v[218:221], v[60:63]
	v_mfma_f32_16x16x32_bf16 v[56:59], v[156:159], v[218:221], v[56:59]
	v_mfma_f32_16x16x32_bf16 v[28:31], v[160:163], v[190:193], v[28:31]
	v_mfma_f32_16x16x32_bf16 v[24:27], v[182:185], v[190:193], v[24:27]
	v_mfma_f32_16x16x32_bf16 v[20:23], v[160:163], v[198:201], v[20:23]
	v_mfma_f32_16x16x32_bf16 v[16:19], v[182:185], v[198:201], v[16:19]
	v_mfma_f32_16x16x32_bf16 v[12:15], v[160:163], v[206:209], v[12:15]
	v_mfma_f32_16x16x32_bf16 v[8:11], v[182:185], v[206:209], v[8:11]
	v_mfma_f32_16x16x32_bf16 v[4:7], v[160:163], v[214:217], v[4:7]
	v_mfma_f32_16x16x32_bf16 v[0:3], v[182:185], v[214:217], v[0:3]
	v_mfma_f32_16x16x32_bf16 v[28:31], v[178:181], v[194:197], v[28:31]
	v_mfma_f32_16x16x32_bf16 v[24:27], v[186:189], v[194:197], v[24:27]
	v_mfma_f32_16x16x32_bf16 v[20:23], v[178:181], v[202:205], v[20:23]
	v_mfma_f32_16x16x32_bf16 v[16:19], v[186:189], v[202:205], v[16:19]
	v_mfma_f32_16x16x32_bf16 v[12:15], v[178:181], v[210:213], v[12:15]
	v_mfma_f32_16x16x32_bf16 v[8:11], v[186:189], v[210:213], v[8:11]
	v_mfma_f32_16x16x32_bf16 v[4:7], v[178:181], v[218:221], v[4:7]
	v_mfma_f32_16x16x32_bf16 v[0:3], v[186:189], v[218:221], v[0:3]
	s_barrier
; #define PG8_STAGE(bufoff, gbase, voff) do { _Pragma("unroll") for (int _i = 0; _i < 2; ++_i) \
;         __builtin_amdgcn_global_load_lds((const unsigned*)((const char*)(gbase) + (voff)[_i]), (LAS unsigned*)(lds + (bufoff) + ldsw + _i * 8192), 16, 0, 0); } while (0)
; #define PG8_LDA(dst, b, h) do { _Pragma("unroll") for (int m = 0; m < 4; ++m) _Pragma("unroll") for (int k = 0; k < 2; ++k) dst[m][k] = *(const LAS bf16x8*)(lds + PG8_SA(b, h) + aoff + m * 2048 + k * 1024); } while (0)
; #define PG8_LDB(dst, b, h) do { _Pragma("unroll") for (int n = 0; n < 2; ++n) _Pragma("unroll") for (int k = 0; k < 2; ++k) dst[n][k] = *(const LAS bf16x8*)(lds + PG8_SB(b, h) + boff + n * 2048 + k * 1024); } while (0)
; #define PG8_MMA(ai, bj, At, Bt) do { __builtin_amdgcn_s_setprio(1); _Pragma("unroll") for (int m = 0; m < 4; ++m) _Pragma("unroll") for (int n = 0; n < 2; ++n) _Pragma("unroll") for (int k = 0; k < 2; ++k) \
;         acc[ai][bj][m][n] = __builtin_amdgcn_mfma_f32_16x16x32_bf16(Bt[n][k], At[m][k], acc[ai][bj][m][n], 0, 0, 0); __builtin_amdgcn_s_setprio(0); } while (0)
; #define PG8_WAIT_V(n) asm volatile("s_waitcnt vmcnt(" #n ")" ::: "memory")
; #define PG8_WAIT_L(n) asm volatile("s_waitcnt lgkmcnt(" #n ")" ::: "memory")
; #define PG8_BAR __builtin_amdgcn_s_barrier()
; #define PG8_SCHED __builtin_amdgcn_sched_barrier(0)
; __device__ __forceinline__ void gemm_phase(LAS unsigned char* lds, const Params& p, const bf16_t* gA, const bf16_t* gBt, const int gM, const int gN, const int gK, const int epi, const int perm, bf16_t* const Hp, const int goff, const float coef) {
;     ...
;             PG8_LDB(B0, 1, 0); PG8_LDB(B1, 1, 1); PG8_SCHED; PG8_LDA(At, 1, 0); PG8_STAGE(PG8_SA(0, 1), a2 + hstep, voffA);
;             PG8_WAIT_V(8); PG8_WAIT_L(0); PG8_BAR; PG8_MMA(0, 0, At, B0); PG8_MMA(0, 1, At, B1); PG8_BAR; PG8_SCHED;
;             PG8_LDA(At, 1, 1); PG8_STAGE(PG8_SB(1, 0), b3, voffB); PG8_STAGE(PG8_SB(1, 1), b3 + hstep, voffB); PG8_STAGE(PG8_SA(1, 0), a3, voffA);
;             PG8_WAIT_V(8); PG8_WAIT_L(0); PG8_BAR; PG8_MMA(1, 0, At, B0); PG8_MMA(1, 1, At, B1); PG8_BAR; PG8_SCHED;
	s_add_i32 s57, 0, 0x18000
	v_add_u32_e32 v141, s57, v165
	s_add_i32 s58, 0, 0x1c000
	ds_read_b128 v[128:131], v141
	ds_read_b128 v[132:135], v141 offset:1024
	ds_read_b128 v[152:155], v141 offset:2048
	ds_read_b128 v[156:159], v141 offset:3072
	v_add_u32_e32 v141, s58, v165
	ds_read_b128 v[160:163], v141
	ds_read_b128 v[178:181], v141 offset:1024
	ds_read_b128 v[182:185], v141 offset:2048
	ds_read_b128 v[186:189], v141 offset:3072
	s_add_u32 s30, s30, 0x80000
	s_addc_u32 s31, s31, 0
	s_mov_b32 m0, s39
	v_lshl_add_u64 v[230:231], s[30:31], 0, v[136:137]
	ds_read_b128 v[190:193], v176 offset:32768
	ds_read_b128 v[194:197], v176 offset:33792
	ds_read_b128 v[198:201], v176 offset:34816
	ds_read_b128 v[202:205], v176 offset:35840
	ds_read_b128 v[206:209], v176 offset:36864
	ds_read_b128 v[210:213], v176 offset:37888
	ds_read_b128 v[214:217], v176 offset:38912
	ds_read_b128 v[218:221], v176 offset:39936
	global_load_lds_dwordx4 v[230:231], off
	v_lshl_add_u64 v[230:231], s[30:31], 0, v[142:143]
	s_mov_b32 m0, s40
	s_nop 0
	global_load_lds_dwordx4 v[230:231], off
	s_waitcnt vmcnt(8)
	s_waitcnt lgkmcnt(0)
	s_barrier
	s_waitcnt lgkmcnt(0)
	v_mfma_f32_16x16x32_bf16 v[124:127], v[128:131], v[190:193], v[124:127]
	v_mfma_f32_16x16x32_bf16 v[120:123], v[152:155], v[190:193], v[120:123]
	v_mfma_f32_16x16x32_bf16 v[116:119], v[128:131], v[198:201], v[116:119]
	v_mfma_f32_16x16x32_bf16 v[112:115], v[152:155], v[198:201], v[112:115]
	v_mfma_f32_16x16x32_bf16 v[108:111], v[128:131], v[206:209], v[108:111]
	v_mfma_f32_16x16x32_bf16 v[104:107], v[152:155], v[206:209], v[104:107]
	v_mfma_f32_16x16x32_bf16 v[100:103], v[128:131], v[214:217], v[100:103]
	v_mfma_f32_16x16x32_bf16 v[96:99], v[152:155], v[214:217], v[96:99]
	v_mfma_f32_16x16x32_bf16 v[124:127], v[132:135], v[194:197], v[124:127]
	v_mfma_f32_16x16x32_bf16 v[120:123], v[156:159], v[194:197], v[120:123]
	v_mfma_f32_16x16x32_bf16 v[116:119], v[132:135], v[202:205], v[116:119]
	v_mfma_f32_16x16x32_bf16 v[112:115], v[156:159], v[202:205], v[112:115]
	v_mfma_f32_16x16x32_bf16 v[108:111], v[132:135], v[210:213], v[108:111]
	v_mfma_f32_16x16x32_bf16 v[104:107], v[156:159], v[210:213], v[104:107]
	v_mfma_f32_16x16x32_bf16 v[100:103], v[132:135], v[218:221], v[100:103]
	v_mfma_f32_16x16x32_bf16 v[96:99], v[156:159], v[218:221], v[96:99]
	v_mfma_f32_16x16x32_bf16 v[68:71], v[160:163], v[190:193], v[68:71]
	v_mfma_f32_16x16x32_bf16 v[64:67], v[182:185], v[190:193], v[64:67]
	v_mfma_f32_16x16x32_bf16 v[52:55], v[160:163], v[198:201], v[52:55]
	v_mfma_f32_16x16x32_bf16 v[48:51], v[182:185], v[198:201], v[48:51]
	v_mfma_f32_16x16x32_bf16 v[44:47], v[160:163], v[206:209], v[44:47]
	v_mfma_f32_16x16x32_bf16 v[40:43], v[182:185], v[206:209], v[40:43]
	v_mfma_f32_16x16x32_bf16 v[36:39], v[160:163], v[214:217], v[36:39]
	v_mfma_f32_16x16x32_bf16 v[32:35], v[182:185], v[214:217], v[32:35]
	v_mfma_f32_16x16x32_bf16 v[68:71], v[178:181], v[194:197], v[68:71]
	v_mfma_f32_16x16x32_bf16 v[64:67], v[186:189], v[194:197], v[64:67]
	v_mfma_f32_16x16x32_bf16 v[52:55], v[178:181], v[202:205], v[52:55]
	v_mfma_f32_16x16x32_bf16 v[48:51], v[186:189], v[202:205], v[48:51]
	v_mfma_f32_16x16x32_bf16 v[44:47], v[178:181], v[210:213], v[44:47]
	v_mfma_f32_16x16x32_bf16 v[40:43], v[186:189], v[210:213], v[40:43]
	v_mfma_f32_16x16x32_bf16 v[36:39], v[178:181], v[218:221], v[36:39]
	v_mfma_f32_16x16x32_bf16 v[32:35], v[186:189], v[218:221], v[32:35]
	s_barrier
	s_add_i32 s30, s57, s36
	v_lshl_add_u64 v[222:223], v[222:223], 0, s[8:9]
	s_mov_b32 m0, s30
	ds_read_b128 v[190:193], v176 offset:49152
	ds_read_b128 v[194:197], v176 offset:50176
	ds_read_b128 v[198:201], v176 offset:51200
	ds_read_b128 v[202:205], v176 offset:52224
	ds_read_b128 v[206:209], v176 offset:53248
	ds_read_b128 v[210:213], v176 offset:54272
	ds_read_b128 v[214:217], v176 offset:55296
	ds_read_b128 v[218:221], v176 offset:56320
	global_load_lds_dwordx4 v[222:223], off
	s_add_i32 m0, s30, 0x2000
	s_add_u32 s28, s28, 0x80080
	v_lshl_add_u64 v[222:223], v[224:225], 0, s[8:9]
	s_addc_u32 s29, s29, 0
	s_add_i32 s30, s58, s36
	global_load_lds_dwordx4 v[222:223], off
	v_lshl_add_u64 v[222:223], s[28:29], 0, v[138:139]
	s_mov_b32 m0, s30
	s_nop 0
	global_load_lds_dwordx4 v[222:223], off
	v_lshl_add_u64 v[222:223], s[28:29], 0, v[144:145]
	s_add_i32 m0, s30, 0x2000
	s_nop 0
	global_load_lds_dwordx4 v[222:223], off
	v_lshl_add_u64 v[222:223], v[226:227], 0, s[8:9]
	s_mov_b32 m0, s44
	s_nop 0
	global_load_lds_dwordx4 v[222:223], off
	v_lshl_add_u64 v[222:223], v[228:229], 0, s[8:9]
	s_mov_b32 m0, s45
	s_nop 0
	global_load_lds_dwordx4 v[222:223], off
	s_waitcnt vmcnt(8)
	s_waitcnt lgkmcnt(0)
	s_barrier
	s_waitcnt lgkmcnt(0)
	v_mfma_f32_16x16x32_bf16 v[92:95], v[128:131], v[190:193], v[92:95]
	v_mfma_f32_16x16x32_bf16 v[88:91], v[152:155], v[190:193], v[88:91]
	v_mfma_f32_16x16x32_bf16 v[84:87], v[128:131], v[198:201], v[84:87]
	v_mfma_f32_16x16x32_bf16 v[80:83], v[152:155], v[198:201], v[80:83]
	v_mfma_f32_16x16x32_bf16 v[76:79], v[128:131], v[206:209], v[76:79]
	v_mfma_f32_16x16x32_bf16 v[72:75], v[152:155], v[206:209], v[72:75]
	v_mfma_f32_16x16x32_bf16 v[60:63], v[128:131], v[214:217], v[60:63]
	v_mfma_f32_16x16x32_bf16 v[56:59], v[152:155], v[214:217], v[56:59]
	v_mfma_f32_16x16x32_bf16 v[92:95], v[132:135], v[194:197], v[92:95]
	v_mfma_f32_16x16x32_bf16 v[88:91], v[156:159], v[194:197], v[88:91]
	v_mfma_f32_16x16x32_bf16 v[84:87], v[132:135], v[202:205], v[84:87]
	v_mfma_f32_16x16x32_bf16 v[80:83], v[156:159], v[202:205], v[80:83]
	v_mfma_f32_16x16x32_bf16 v[76:79], v[132:135], v[210:213], v[76:79]
	v_mfma_f32_16x16x32_bf16 v[72:75], v[156:159], v[210:213], v[72:75]
	v_mfma_f32_16x16x32_bf16 v[60:63], v[132:135], v[218:221], v[60:63]
	v_mfma_f32_16x16x32_bf16 v[56:59], v[156:159], v[218:221], v[56:59]
	v_mfma_f32_16x16x32_bf16 v[28:31], v[160:163], v[190:193], v[28:31]
	v_mfma_f32_16x16x32_bf16 v[24:27], v[182:185], v[190:193], v[24:27]
	v_mfma_f32_16x16x32_bf16 v[20:23], v[160:163], v[198:201], v[20:23]
	v_mfma_f32_16x16x32_bf16 v[16:19], v[182:185], v[198:201], v[16:19]
	v_mfma_f32_16x16x32_bf16 v[12:15], v[160:163], v[206:209], v[12:15]
	v_mfma_f32_16x16x32_bf16 v[8:11], v[182:185], v[206:209], v[8:11]
	v_mfma_f32_16x16x32_bf16 v[4:7], v[160:163], v[214:217], v[4:7]
	v_mfma_f32_16x16x32_bf16 v[0:3], v[182:185], v[214:217], v[0:3]
	v_mfma_f32_16x16x32_bf16 v[28:31], v[178:181], v[194:197], v[28:31]
	v_mfma_f32_16x16x32_bf16 v[24:27], v[186:189], v[194:197], v[24:27]
	v_mfma_f32_16x16x32_bf16 v[20:23], v[178:181], v[202:205], v[20:23]
	v_mfma_f32_16x16x32_bf16 v[16:19], v[186:189], v[202:205], v[16:19]
	v_mfma_f32_16x16x32_bf16 v[12:15], v[178:181], v[210:213], v[12:15]
	v_mfma_f32_16x16x32_bf16 v[8:11], v[186:189], v[210:213], v[8:11]
	v_mfma_f32_16x16x32_bf16 v[4:7], v[178:181], v[218:221], v[4:7]
	v_mfma_f32_16x16x32_bf16 v[0:3], v[186:189], v[218:221], v[0:3]
	s_barrier
	s_add_u32 s26, s26, 0x100
	s_addc_u32 s27, s27, 0
	s_add_u32 s54, s54, 0x100
	s_addc_u32 s55, s55, 0
	s_cmp_ge_u32 s56, s52
	s_mov_b32 s30, s56
	s_cbranch_scc0 .LBB0_1593
; #define PG8_BAR __builtin_amdgcn_s_barrier()
; __device__ __forceinline__ void gemm_phase(LAS unsigned char* lds, const Params& p, const bf16_t* gA, const bf16_t* gBt, const int gM, const int gN, const int gK, const int epi, const int perm, bf16_t* const Hp, const int goff, const float coef) {
;     ...
;         if (wr == 0) PG8_BAR;
.Lpeel_exit_3:
	s_and_b64 vcc, exec, s[10:11]
	s_cbranch_vccz .LBB0_1596
	s_barrier

; #define PG8_STAGE(bufoff, gbase, voff) do { _Pragma("unroll") for (int _i = 0; _i < 2; ++_i) \
;         __builtin_amdgcn_global_load_lds((const unsigned*)((const char*)(gbase) + (voff)[_i]), (LAS unsigned*)(lds + (bufoff) + ldsw + _i * 8192), 16, 0, 0); } while (0)
; #define PG8_LDA(dst, b, h) do { _Pragma("unroll") for (int m = 0; m < 4; ++m) _Pragma("unroll") for (int k = 0; k < 2; ++k) dst[m][k] = *(const LAS bf16x8*)(lds + PG8_SA(b, h) + aoff + m * 2048 + k * 1024); } while (0)
; #define PG8_LDB(dst, b, h) do { _Pragma("unroll") for (int n = 0; n < 2; ++n) _Pragma("unroll") for (int k = 0; k < 2; ++k) dst[n][k] = *(const LAS bf16x8*)(lds + PG8_SB(b, h) + boff + n * 2048 + k * 1024); } while (0)
; #define PG8_WAIT_V(n) asm volatile("s_waitcnt vmcnt(" #n ")" ::: "memory")
; #define PG8_WAIT_L(n) asm volatile("s_waitcnt lgkmcnt(" #n ")" ::: "memory")
; #define PG8_BAR __builtin_amdgcn_s_barrier()
; __device__ __forceinline__ void gemm_phase(LAS unsigned char* lds, const Params& p, const bf16_t* gA, const bf16_t* gBt, const int gM, const int gN, const int gK, const int epi, const int perm, bf16_t* const Hp, const int goff, const float coef) {
;     ...
;         const bool has_next = S.next(ui + 1, nxt);
;         const char* nA = has_next ? (const char*)gA + (size_t)nxt.pm * tstep + (nxt.ks > 0 ? nxt.ks * ksl : 0) : cA; const char* nB = has_next ? (const char*)gBt + (size_t)nxt.pn * tstep + (nxt.ks > 0 ? nxt.ks * ksl : 0) : cB;
;         const int nt = cur.ks >= 0 ? ntf / 4 : ntf;
;         for (int t = 0; t < nt; t += 2) {
;             const bool last = (t == nt - 2);
;             const char* a1 = cA + (size_t)(t + 1) * kstep;
;             const char* a2 = last ? nA : cA + (size_t)(t + 2) * kstep; const char* b2 = last ? nB : cB + (size_t)(t + 2) * kstep;
;             const char* a3 = a2 + kstep; const char* b3 = b2 + kstep;
;             PG8_LDB(B0, 0, 0); PG8_LDB(B1, 0, 1); PG8_SCHED; PG8_LDA(At, 0, 0); PG8_STAGE(PG8_SA(1, 1), a1 + hstep, voffA);
;             PG8_WAIT_V(8); PG8_WAIT_L(0); PG8_BAR; PG8_MMA(0, 0, At, B0); PG8_MMA(0, 1, At, B1); PG8_BAR; PG8_SCHED;
;             PG8_LDA(At, 0, 1); PG8_STAGE(PG8_SB(0, 0), b2, voffB); PG8_STAGE(PG8_SB(0, 1), b2 + hstep, voffB); PG8_STAGE(PG8_SA(0, 0), a2, voffA);
;             PG8_WAIT_V(8); PG8_WAIT_L(0); PG8_BAR; PG8_MMA(1, 0, At, B0); PG8_MMA(1, 1, At, B1); PG8_BAR; PG8_SCHED;
.LBB0_1736:
	s_ashr_i32 s13, s12, 31
	s_lshl_b64 s[18:19], s[12:13], 20
	s_add_u32 s13, s3, s18
	s_addc_u32 s15, s33, s19
	s_lshl_b64 s[18:19], s[0:1], 10
	s_cmp_gt_i32 s0, 0
	s_cselect_b32 s50, s18, 0
	s_cselect_b32 s49, s19, 0
	s_add_u32 s18, s13, s50
	s_addc_u32 s19, s15, s49
	s_and_b64 s[20:21], s[16:17], exec
	s_cselect_b32 s13, s19, s27
	s_cselect_b32 s48, s18, s26
	s_ashr_i32 s15, s14, 31
	s_lshl_b64 s[20:21], s[14:15], 20
	s_add_u32 s15, s34, s20
	s_addc_u32 s21, s35, s21
	s_add_u32 s20, s15, s50
	s_addc_u32 s21, s21, s49
	s_and_b64 s[50:51], s[16:17], exec
	s_cselect_b32 s15, s21, s29
	s_cselect_b32 s49, s20, s28
	s_cmp_gt_i32 s31, -1
	s_cselect_b32 s50, 8, 32
	s_add_i32 s51, s50, -2
	s_add_u32 s26, s26, 0x80080
	s_addc_u32 s27, s27, 0
	s_add_u32 s52, s28, 0x100
	s_mov_b32 s30, 0
	s_addc_u32 s53, s29, 0
	ds_read_b128 v[160:163], v156
	ds_read_b128 v[164:167], v156 offset:1024
	ds_read_b128 v[168:171], v156 offset:2048
	ds_read_b128 v[172:175], v156 offset:3072
	ds_read_b128 v[176:179], v157
	ds_read_b128 v[180:183], v157 offset:1024
	ds_read_b128 v[184:187], v157 offset:2048
	ds_read_b128 v[188:191], v157 offset:3072
	s_add_i32 s54, s30, 2
	s_add_u32 s28, s26, 0xfff80080
	s_addc_u32 s29, s27, -1
	s_cmp_eq_u32 s51, s30
	s_cselect_b32 s30, s48, s28
	s_cselect_b32 s31, s13, s29
	s_cselect_b32 s29, s15, s53
	s_cselect_b32 s28, s49, s52
	v_lshl_add_u64 v[144:145], s[26:27], 0, v[136:137]
	s_add_i32 m0, s23, 0xc000
	ds_read_b128 v[192:195], v158
	ds_read_b128 v[196:199], v158 offset:1024
	ds_read_b128 v[200:203], v158 offset:2048
	ds_read_b128 v[204:207], v158 offset:3072
	ds_read_b128 v[208:211], v158 offset:4096
	ds_read_b128 v[212:215], v158 offset:5120
	ds_read_b128 v[216:219], v158 offset:6144
	ds_read_b128 v[220:223], v158 offset:7168
	global_load_lds_dwordx4 v[144:145], off
	v_lshl_add_u64 v[144:145], s[26:27], 0, v[138:139]
	s_add_i32 m0, s23, 0xe000
	s_nop 0
	global_load_lds_dwordx4 v[144:145], off
	s_waitcnt vmcnt(8)
	s_waitcnt lgkmcnt(0)
	s_barrier
	s_waitcnt lgkmcnt(0)
	v_mfma_f32_16x16x32_bf16 v[124:127], v[160:163], v[192:195], 0
	v_mfma_f32_16x16x32_bf16 v[120:123], v[168:171], v[192:195], 0
	v_mfma_f32_16x16x32_bf16 v[108:111], v[160:163], v[200:203], 0
	v_mfma_f32_16x16x32_bf16 v[104:107], v[168:171], v[200:203], 0
	v_mfma_f32_16x16x32_bf16 v[92:95], v[160:163], v[208:211], 0
	v_mfma_f32_16x16x32_bf16 v[88:91], v[168:171], v[208:211], 0
	v_mfma_f32_16x16x32_bf16 v[76:79], v[160:163], v[216:219], 0
	v_mfma_f32_16x16x32_bf16 v[72:75], v[168:171], v[216:219], 0
	v_mfma_f32_16x16x32_bf16 v[124:127], v[164:167], v[196:199], v[124:127]
	v_mfma_f32_16x16x32_bf16 v[120:123], v[172:175], v[196:199], v[120:123]
	v_mfma_f32_16x16x32_bf16 v[108:111], v[164:167], v[204:207], v[108:111]
	v_mfma_f32_16x16x32_bf16 v[104:107], v[172:175], v[204:207], v[104:107]
	v_mfma_f32_16x16x32_bf16 v[92:95], v[164:167], v[212:215], v[92:95]
	v_mfma_f32_16x16x32_bf16 v[88:91], v[172:175], v[212:215], v[88:91]
	v_mfma_f32_16x16x32_bf16 v[76:79], v[164:167], v[220:223], v[76:79]
	v_mfma_f32_16x16x32_bf16 v[72:75], v[172:175], v[220:223], v[72:75]
	v_mfma_f32_16x16x32_bf16 v[116:119], v[176:179], v[192:195], 0
	v_mfma_f32_16x16x32_bf16 v[112:115], v[184:187], v[192:195], 0
	v_mfma_f32_16x16x32_bf16 v[100:103], v[176:179], v[200:203], 0
	v_mfma_f32_16x16x32_bf16 v[96:99], v[184:187], v[200:203], 0
	v_mfma_f32_16x16x32_bf16 v[84:87], v[176:179], v[208:211], 0
	v_mfma_f32_16x16x32_bf16 v[80:83], v[184:187], v[208:211], 0
	v_mfma_f32_16x16x32_bf16 v[68:71], v[176:179], v[216:219], 0
	v_mfma_f32_16x16x32_bf16 v[64:67], v[184:187], v[216:219], 0
	v_mfma_f32_16x16x32_bf16 v[116:119], v[180:183], v[196:199], v[116:119]
	v_mfma_f32_16x16x32_bf16 v[112:115], v[188:191], v[196:199], v[112:115]
	v_mfma_f32_16x16x32_bf16 v[100:103], v[180:183], v[204:207], v[100:103]
	v_mfma_f32_16x16x32_bf16 v[96:99], v[188:191], v[204:207], v[96:99]
	v_mfma_f32_16x16x32_bf16 v[84:87], v[180:183], v[212:215], v[84:87]
	v_mfma_f32_16x16x32_bf16 v[80:83], v[188:191], v[212:215], v[80:83]
	v_mfma_f32_16x16x32_bf16 v[68:71], v[180:183], v[220:223], v[68:71]
	v_mfma_f32_16x16x32_bf16 v[64:67], v[188:191], v[220:223], v[64:67]
	s_barrier
	s_add_i32 s55, s44, s36
	v_lshl_add_u64 v[144:145], s[28:29], 0, v[130:131]
	s_mov_b32 m0, s55
	ds_read_b128 v[192:195], v158 offset:16384
	ds_read_b128 v[196:199], v158 offset:17408
	ds_read_b128 v[200:203], v158 offset:18432
	ds_read_b128 v[204:207], v158 offset:19456
	ds_read_b128 v[208:211], v158 offset:20480
	ds_read_b128 v[212:215], v158 offset:21504
	ds_read_b128 v[216:219], v158 offset:22528
	ds_read_b128 v[220:223], v158 offset:23552
	global_load_lds_dwordx4 v[144:145], off
	s_add_i32 m0, s55, 0x2000
	s_add_u32 s56, s28, 0x80000
	v_lshl_add_u64 v[224:225], s[28:29], 0, v[134:135]
	s_addc_u32 s57, s29, 0
	s_add_i32 s55, s45, s36
	global_load_lds_dwordx4 v[224:225], off
	v_lshl_add_u64 v[226:227], s[56:57], 0, v[130:131]
	s_mov_b32 m0, s55
	v_lshl_add_u64 v[228:229], s[30:31], 0, v[132:133]
	global_load_lds_dwordx4 v[226:227], off
	v_lshl_add_u64 v[226:227], s[56:57], 0, v[134:135]
	s_add_i32 m0, s55, 0x2000
	s_nop 0
	global_load_lds_dwordx4 v[226:227], off
	v_lshl_add_u64 v[226:227], s[30:31], 0, v[128:129]
	s_mov_b32 m0, s23
	s_nop 0
	global_load_lds_dwordx4 v[226:227], off
	s_mov_b32 m0, s25
	s_nop 0
	global_load_lds_dwordx4 v[228:229], off
	s_waitcnt vmcnt(8)
	s_waitcnt lgkmcnt(0)
	s_barrier
; #define PG8_STAGE(bufoff, gbase, voff) do { _Pragma("unroll") for (int _i = 0; _i < 2; ++_i) \
;         __builtin_amdgcn_global_load_lds((const unsigned*)((const char*)(gbase) + (voff)[_i]), (LAS unsigned*)(lds + (bufoff) + ldsw + _i * 8192), 16, 0, 0); } while (0)
; #define PG8_LDA(dst, b, h) do { _Pragma("unroll") for (int m = 0; m < 4; ++m) _Pragma("unroll") for (int k = 0; k < 2; ++k) dst[m][k] = *(const LAS bf16x8*)(lds + PG8_SA(b, h) + aoff + m * 2048 + k * 1024); } while (0)
; #define PG8_LDB(dst, b, h) do { _Pragma("unroll") for (int n = 0; n < 2; ++n) _Pragma("unroll") for (int k = 0; k < 2; ++k) dst[n][k] = *(const LAS bf16x8*)(lds + PG8_SB(b, h) + boff + n * 2048 + k * 1024); } while (0)
; #define PG8_MMA(ai, bj, At, Bt) do { __builtin_amdgcn_s_setprio(1); _Pragma("unroll") for (int m = 0; m < 4; ++m) _Pragma("unroll") for (int n = 0; n < 2; ++n) _Pragma("unroll") for (int k = 0; k < 2; ++k) \
;         acc[ai][bj][m][n] = __builtin_amdgcn_mfma_f32_16x16x32_bf16(Bt[n][k], At[m][k], acc[ai][bj][m][n], 0, 0, 0); __builtin_amdgcn_s_setprio(0); } while (0)
; #define PG8_WAIT_V(n) asm volatile("s_waitcnt vmcnt(" #n ")" ::: "memory")
; #define PG8_WAIT_L(n) asm volatile("s_waitcnt lgkmcnt(" #n ")" ::: "memory")
; #define PG8_BAR __builtin_amdgcn_s_barrier()
; #define PG8_SCHED __builtin_amdgcn_sched_barrier(0)
; __device__ __forceinline__ void gemm_phase(LAS unsigned char* lds, const Params& p, const bf16_t* gA, const bf16_t* gBt, const int gM, const int gN, const int gK, const int epi, const int perm, bf16_t* const Hp, const int goff, const float coef) {
;     ...
;             PG8_WAIT_V(8); PG8_WAIT_L(0); PG8_BAR; PG8_MMA(1, 0, At, B0); PG8_MMA(1, 1, At, B1); PG8_BAR; PG8_SCHED;
;             PG8_LDB(B0, 1, 0); PG8_LDB(B1, 1, 1); PG8_SCHED; PG8_LDA(At, 1, 0); PG8_STAGE(PG8_SA(0, 1), a2 + hstep, voffA);
;             PG8_WAIT_V(8); PG8_WAIT_L(0); PG8_BAR; PG8_MMA(0, 0, At, B0); PG8_MMA(0, 1, At, B1); PG8_BAR; PG8_SCHED;
	s_waitcnt lgkmcnt(0)
	v_mfma_f32_16x16x32_bf16 v[60:63], v[160:163], v[192:195], 0
	v_mfma_f32_16x16x32_bf16 v[56:59], v[168:171], v[192:195], 0
	v_mfma_f32_16x16x32_bf16 v[44:47], v[160:163], v[200:203], 0
	v_mfma_f32_16x16x32_bf16 v[40:43], v[168:171], v[200:203], 0
	v_mfma_f32_16x16x32_bf16 v[28:31], v[160:163], v[208:211], 0
	v_mfma_f32_16x16x32_bf16 v[24:27], v[168:171], v[208:211], 0
	v_mfma_f32_16x16x32_bf16 v[12:15], v[160:163], v[216:219], 0
	v_mfma_f32_16x16x32_bf16 v[8:11], v[168:171], v[216:219], 0
	v_mfma_f32_16x16x32_bf16 v[60:63], v[164:167], v[196:199], v[60:63]
	v_mfma_f32_16x16x32_bf16 v[56:59], v[172:175], v[196:199], v[56:59]
	v_mfma_f32_16x16x32_bf16 v[44:47], v[164:167], v[204:207], v[44:47]
	v_mfma_f32_16x16x32_bf16 v[40:43], v[172:175], v[204:207], v[40:43]
	v_mfma_f32_16x16x32_bf16 v[28:31], v[164:167], v[212:215], v[28:31]
	v_mfma_f32_16x16x32_bf16 v[24:27], v[172:175], v[212:215], v[24:27]
	v_mfma_f32_16x16x32_bf16 v[12:15], v[164:167], v[220:223], v[12:15]
	v_mfma_f32_16x16x32_bf16 v[8:11], v[172:175], v[220:223], v[8:11]
	v_mfma_f32_16x16x32_bf16 v[52:55], v[176:179], v[192:195], 0
	v_mfma_f32_16x16x32_bf16 v[48:51], v[184:187], v[192:195], 0
	v_mfma_f32_16x16x32_bf16 v[36:39], v[176:179], v[200:203], 0
	v_mfma_f32_16x16x32_bf16 v[32:35], v[184:187], v[200:203], 0
	v_mfma_f32_16x16x32_bf16 v[20:23], v[176:179], v[208:211], 0
	v_mfma_f32_16x16x32_bf16 v[16:19], v[184:187], v[208:211], 0
	v_mfma_f32_16x16x32_bf16 v[4:7], v[176:179], v[216:219], 0
	v_mfma_f32_16x16x32_bf16 v[0:3], v[184:187], v[216:219], 0
	v_mfma_f32_16x16x32_bf16 v[52:55], v[180:183], v[196:199], v[52:55]
	v_mfma_f32_16x16x32_bf16 v[48:51], v[188:191], v[196:199], v[48:51]
	v_mfma_f32_16x16x32_bf16 v[36:39], v[180:183], v[204:207], v[36:39]
	v_mfma_f32_16x16x32_bf16 v[32:35], v[188:191], v[204:207], v[32:35]
	v_mfma_f32_16x16x32_bf16 v[20:23], v[180:183], v[212:215], v[20:23]
	v_mfma_f32_16x16x32_bf16 v[16:19], v[188:191], v[212:215], v[16:19]
	v_mfma_f32_16x16x32_bf16 v[4:7], v[180:183], v[220:223], v[4:7]
	v_mfma_f32_16x16x32_bf16 v[0:3], v[188:191], v[220:223], v[0:3]
	s_barrier
	s_add_i32 s55, 0, 0x18000
	v_add_u32_e32 v141, s55, v147
	s_add_i32 s56, 0, 0x1c000
	ds_read_b128 v[160:163], v141
	ds_read_b128 v[164:167], v141 offset:1024
	ds_read_b128 v[168:171], v141 offset:2048
	ds_read_b128 v[172:175], v141 offset:3072
	v_add_u32_e32 v141, s56, v147
	ds_read_b128 v[176:179], v141
	ds_read_b128 v[180:183], v141 offset:1024
	ds_read_b128 v[184:187], v141 offset:2048
	ds_read_b128 v[188:191], v141 offset:3072
	s_add_u32 s30, s30, 0x80000
	s_addc_u32 s31, s31, 0
	s_mov_b32 m0, s37
	v_lshl_add_u64 v[230:231], s[30:31], 0, v[128:129]
	ds_read_b128 v[192:195], v158 offset:32768
	ds_read_b128 v[196:199], v158 offset:33792
	ds_read_b128 v[200:203], v158 offset:34816
	ds_read_b128 v[204:207], v158 offset:35840
	ds_read_b128 v[208:211], v158 offset:36864
	ds_read_b128 v[212:215], v158 offset:37888
	ds_read_b128 v[216:219], v158 offset:38912
	ds_read_b128 v[220:223], v158 offset:39936
	global_load_lds_dwordx4 v[230:231], off
	v_lshl_add_u64 v[230:231], s[30:31], 0, v[132:133]
	s_mov_b32 m0, s38
	s_nop 0
	global_load_lds_dwordx4 v[230:231], off
	s_waitcnt vmcnt(8)
	s_waitcnt lgkmcnt(0)
	s_barrier
	s_waitcnt lgkmcnt(0)
	v_mfma_f32_16x16x32_bf16 v[124:127], v[160:163], v[192:195], v[124:127]
	v_mfma_f32_16x16x32_bf16 v[120:123], v[168:171], v[192:195], v[120:123]
	v_mfma_f32_16x16x32_bf16 v[108:111], v[160:163], v[200:203], v[108:111]
	v_mfma_f32_16x16x32_bf16 v[104:107], v[168:171], v[200:203], v[104:107]
	v_mfma_f32_16x16x32_bf16 v[92:95], v[160:163], v[208:211], v[92:95]
	v_mfma_f32_16x16x32_bf16 v[88:91], v[168:171], v[208:211], v[88:91]
	v_mfma_f32_16x16x32_bf16 v[76:79], v[160:163], v[216:219], v[76:79]
	v_mfma_f32_16x16x32_bf16 v[72:75], v[168:171], v[216:219], v[72:75]
	v_mfma_f32_16x16x32_bf16 v[124:127], v[164:167], v[196:199], v[124:127]
	v_mfma_f32_16x16x32_bf16 v[120:123], v[172:175], v[196:199], v[120:123]
	v_mfma_f32_16x16x32_bf16 v[108:111], v[164:167], v[204:207], v[108:111]
	v_mfma_f32_16x16x32_bf16 v[104:107], v[172:175], v[204:207], v[104:107]
	v_mfma_f32_16x16x32_bf16 v[92:95], v[164:167], v[212:215], v[92:95]
	v_mfma_f32_16x16x32_bf16 v[88:91], v[172:175], v[212:215], v[88:91]
	v_mfma_f32_16x16x32_bf16 v[76:79], v[164:167], v[220:223], v[76:79]
	v_mfma_f32_16x16x32_bf16 v[72:75], v[172:175], v[220:223], v[72:75]
	v_mfma_f32_16x16x32_bf16 v[116:119], v[176:179], v[192:195], v[116:119]
	v_mfma_f32_16x16x32_bf16 v[112:115], v[184:187], v[192:195], v[112:115]
	v_mfma_f32_16x16x32_bf16 v[100:103], v[176:179], v[200:203], v[100:103]
	v_mfma_f32_16x16x32_bf16 v[96:99], v[184:187], v[200:203], v[96:99]
	v_mfma_f32_16x16x32_bf16 v[84:87], v[176:179], v[208:211], v[84:87]
	v_mfma_f32_16x16x32_bf16 v[80:83], v[184:187], v[208:211], v[80:83]
	v_mfma_f32_16x16x32_bf16 v[68:71], v[176:179], v[216:219], v[68:71]
	v_mfma_f32_16x16x32_bf16 v[64:67], v[184:187], v[216:219], v[64:67]
	v_mfma_f32_16x16x32_bf16 v[116:119], v[180:183], v[196:199], v[116:119]
	v_mfma_f32_16x16x32_bf16 v[112:115], v[188:191], v[196:199], v[112:115]
	v_mfma_f32_16x16x32_bf16 v[100:103], v[180:183], v[204:207], v[100:103]
	v_mfma_f32_16x16x32_bf16 v[96:99], v[188:191], v[204:207], v[96:99]
	v_mfma_f32_16x16x32_bf16 v[84:87], v[180:183], v[212:215], v[84:87]
	v_mfma_f32_16x16x32_bf16 v[80:83], v[188:191], v[212:215], v[80:83]
	v_mfma_f32_16x16x32_bf16 v[68:71], v[180:183], v[220:223], v[68:71]
	v_mfma_f32_16x16x32_bf16 v[64:67], v[188:191], v[220:223], v[64:67]
	s_barrier
; #define PG8_STAGE(bufoff, gbase, voff) do { _Pragma("unroll") for (int _i = 0; _i < 2; ++_i) \
;         __builtin_amdgcn_global_load_lds((const unsigned*)((const char*)(gbase) + (voff)[_i]), (LAS unsigned*)(lds + (bufoff) + ldsw + _i * 8192), 16, 0, 0); } while (0)
; #define PG8_LDA(dst, b, h) do { _Pragma("unroll") for (int m = 0; m < 4; ++m) _Pragma("unroll") for (int k = 0; k < 2; ++k) dst[m][k] = *(const LAS bf16x8*)(lds + PG8_SA(b, h) + aoff + m * 2048 + k * 1024); } while (0)
; #define PG8_LDB(dst, b, h) do { _Pragma("unroll") for (int n = 0; n < 2; ++n) _Pragma("unroll") for (int k = 0; k < 2; ++k) dst[n][k] = *(const LAS bf16x8*)(lds + PG8_SB(b, h) + boff + n * 2048 + k * 1024); } while (0)
; #define PG8_BAR __builtin_amdgcn_s_barrier()
; __device__ __forceinline__ void gemm_phase(LAS unsigned char* lds, const Params& p, const bf16_t* gA, const bf16_t* gBt, const int gM, const int gN, const int gK, const int epi, const int perm, bf16_t* const Hp, const int goff, const float coef) {
;     ...
;         for (int t = 0; t < nt; t += 2) {
;             const bool last = (t == nt - 2);
;             const char* a1 = cA + (size_t)(t + 1) * kstep;
;             const char* a2 = last ? nA : cA + (size_t)(t + 2) * kstep; const char* b2 = last ? nB : cB + (size_t)(t + 2) * kstep;
;             const char* a3 = a2 + kstep; const char* b3 = b2 + kstep;
;             PG8_LDB(B0, 0, 0); PG8_LDB(B1, 0, 1); PG8_SCHED; PG8_LDA(At, 0, 0); PG8_STAGE(PG8_SA(1, 1), a1 + hstep, voffA);
;             PG8_WAIT_V(8); PG8_WAIT_L(0); PG8_BAR; PG8_MMA(0, 0, At, B0); PG8_MMA(0, 1, At, B1); PG8_BAR; PG8_SCHED;
;             PG8_LDA(At, 0, 1); PG8_STAGE(PG8_SB(0, 0), b2, voffB); PG8_STAGE(PG8_SB(0, 1), b2 + hstep, voffB); PG8_STAGE(PG8_SA(0, 0), a2, voffA);
;             PG8_WAIT_V(8); PG8_WAIT_L(0); PG8_BAR; PG8_MMA(1, 0, At, B0); PG8_MMA(1, 1, At, B1); PG8_BAR; PG8_SCHED;
;             PG8_LDB(B0, 1, 0); PG8_LDB(B1, 1, 1); PG8_SCHED; PG8_LDA(At, 1, 0); PG8_STAGE(PG8_SA(0, 1), a2 + hstep, voffA);
;             PG8_WAIT_V(8); PG8_WAIT_L(0); PG8_BAR; PG8_MMA(0, 0, At, B0); PG8_MMA(0, 1, At, B1); PG8_BAR; PG8_SCHED;
;             PG8_LDA(At, 1, 1); PG8_STAGE(PG8_SB(1, 0), b3, voffB); PG8_STAGE(PG8_SB(1, 1), b3 + hstep, voffB); PG8_STAGE(PG8_SA(1, 0), a3, voffA);
;             PG8_WAIT_V(8); PG8_WAIT_L(0); PG8_BAR; PG8_MMA(1, 0, At, B0); PG8_MMA(1, 1, At, B1); PG8_BAR; PG8_SCHED;
	s_add_i32 s30, s55, s36
	v_lshl_add_u64 v[144:145], v[144:145], 0, s[8:9]
	s_mov_b32 m0, s30
	ds_read_b128 v[192:195], v158 offset:49152
	ds_read_b128 v[196:199], v158 offset:50176
	ds_read_b128 v[200:203], v158 offset:51200
	ds_read_b128 v[204:207], v158 offset:52224
	ds_read_b128 v[208:211], v158 offset:53248
	ds_read_b128 v[212:215], v158 offset:54272
	ds_read_b128 v[216:219], v158 offset:55296
	ds_read_b128 v[220:223], v158 offset:56320
	global_load_lds_dwordx4 v[144:145], off
	s_add_i32 m0, s30, 0x2000
	s_add_u32 s28, s28, 0x80080
	v_lshl_add_u64 v[144:145], v[224:225], 0, s[8:9]
	s_addc_u32 s29, s29, 0
	s_add_i32 s30, s56, s36
	global_load_lds_dwordx4 v[144:145], off
	v_lshl_add_u64 v[144:145], s[28:29], 0, v[130:131]
	s_mov_b32 m0, s30
	s_nop 0
	global_load_lds_dwordx4 v[144:145], off
	v_lshl_add_u64 v[144:145], s[28:29], 0, v[134:135]
	s_add_i32 m0, s30, 0x2000
	s_nop 0
	global_load_lds_dwordx4 v[144:145], off
	v_lshl_add_u64 v[144:145], v[226:227], 0, s[8:9]
	s_mov_b32 m0, s40
	s_nop 0
	global_load_lds_dwordx4 v[144:145], off
	v_lshl_add_u64 v[144:145], v[228:229], 0, s[8:9]
	s_mov_b32 m0, s41
	s_nop 0
	global_load_lds_dwordx4 v[144:145], off
	s_waitcnt vmcnt(8)
	s_waitcnt lgkmcnt(0)
	s_barrier
	s_waitcnt lgkmcnt(0)
	v_mfma_f32_16x16x32_bf16 v[60:63], v[160:163], v[192:195], v[60:63]
	v_mfma_f32_16x16x32_bf16 v[56:59], v[168:171], v[192:195], v[56:59]
	v_mfma_f32_16x16x32_bf16 v[44:47], v[160:163], v[200:203], v[44:47]
	v_mfma_f32_16x16x32_bf16 v[40:43], v[168:171], v[200:203], v[40:43]
	v_mfma_f32_16x16x32_bf16 v[28:31], v[160:163], v[208:211], v[28:31]
	v_mfma_f32_16x16x32_bf16 v[24:27], v[168:171], v[208:211], v[24:27]
	v_mfma_f32_16x16x32_bf16 v[12:15], v[160:163], v[216:219], v[12:15]
	v_mfma_f32_16x16x32_bf16 v[8:11], v[168:171], v[216:219], v[8:11]
	v_mfma_f32_16x16x32_bf16 v[60:63], v[164:167], v[196:199], v[60:63]
	v_mfma_f32_16x16x32_bf16 v[56:59], v[172:175], v[196:199], v[56:59]
	v_mfma_f32_16x16x32_bf16 v[44:47], v[164:167], v[204:207], v[44:47]
	v_mfma_f32_16x16x32_bf16 v[40:43], v[172:175], v[204:207], v[40:43]
	v_mfma_f32_16x16x32_bf16 v[28:31], v[164:167], v[212:215], v[28:31]
	v_mfma_f32_16x16x32_bf16 v[24:27], v[172:175], v[212:215], v[24:27]
	v_mfma_f32_16x16x32_bf16 v[12:15], v[164:167], v[220:223], v[12:15]
	v_mfma_f32_16x16x32_bf16 v[8:11], v[172:175], v[220:223], v[8:11]
	v_mfma_f32_16x16x32_bf16 v[52:55], v[176:179], v[192:195], v[52:55]
	v_mfma_f32_16x16x32_bf16 v[48:51], v[184:187], v[192:195], v[48:51]
	v_mfma_f32_16x16x32_bf16 v[36:39], v[176:179], v[200:203], v[36:39]
	v_mfma_f32_16x16x32_bf16 v[32:35], v[184:187], v[200:203], v[32:35]
	v_mfma_f32_16x16x32_bf16 v[20:23], v[176:179], v[208:211], v[20:23]
	v_mfma_f32_16x16x32_bf16 v[16:19], v[184:187], v[208:211], v[16:19]
	v_mfma_f32_16x16x32_bf16 v[4:7], v[176:179], v[216:219], v[4:7]
	v_mfma_f32_16x16x32_bf16 v[0:3], v[184:187], v[216:219], v[0:3]
	v_mfma_f32_16x16x32_bf16 v[52:55], v[180:183], v[196:199], v[52:55]
	v_mfma_f32_16x16x32_bf16 v[48:51], v[188:191], v[196:199], v[48:51]
	v_mfma_f32_16x16x32_bf16 v[36:39], v[180:183], v[204:207], v[36:39]
	v_mfma_f32_16x16x32_bf16 v[32:35], v[188:191], v[204:207], v[32:35]
	v_mfma_f32_16x16x32_bf16 v[20:23], v[180:183], v[212:215], v[20:23]
	v_mfma_f32_16x16x32_bf16 v[16:19], v[188:191], v[212:215], v[16:19]
	v_mfma_f32_16x16x32_bf16 v[4:7], v[180:183], v[220:223], v[4:7]
	v_mfma_f32_16x16x32_bf16 v[0:3], v[188:191], v[220:223], v[0:3]
	s_barrier
	s_add_u32 s26, s26, 0x100
	s_addc_u32 s27, s27, 0
	s_add_u32 s52, s52, 0x100
	s_addc_u32 s53, s53, 0
	s_cmp_ge_u32 s54, s50
	s_mov_b32 s30, s54
	s_cbranch_scc1 .Lpeel_exit_4
.LBB0_1737:
	ds_read_b128 v[160:163], v156
	ds_read_b128 v[164:167], v156 offset:1024
	ds_read_b128 v[168:171], v156 offset:2048
	ds_read_b128 v[172:175], v156 offset:3072
	ds_read_b128 v[176:179], v157
	ds_read_b128 v[180:183], v157 offset:1024
	ds_read_b128 v[184:187], v157 offset:2048
	ds_read_b128 v[188:191], v157 offset:3072
	s_add_i32 s54, s30, 2
	s_add_u32 s28, s26, 0xfff80080
	s_addc_u32 s29, s27, -1
	s_cmp_eq_u32 s51, s30
	s_cselect_b32 s30, s48, s28
	s_cselect_b32 s31, s13, s29
	s_cselect_b32 s29, s15, s53
	s_cselect_b32 s28, s49, s52
	v_lshl_add_u64 v[144:145], s[26:27], 0, v[136:137]
	s_add_i32 m0, s23, 0xc000
	ds_read_b128 v[192:195], v158
	ds_read_b128 v[196:199], v158 offset:1024
	ds_read_b128 v[200:203], v158 offset:2048
	ds_read_b128 v[204:207], v158 offset:3072
	ds_read_b128 v[208:211], v158 offset:4096
	ds_read_b128 v[212:215], v158 offset:5120
	ds_read_b128 v[216:219], v158 offset:6144
	ds_read_b128 v[220:223], v158 offset:7168
	global_load_lds_dwordx4 v[144:145], off
	v_lshl_add_u64 v[144:145], s[26:27], 0, v[138:139]
	s_add_i32 m0, s23, 0xe000
	s_nop 0
	global_load_lds_dwordx4 v[144:145], off
	s_waitcnt vmcnt(8)
	s_waitcnt lgkmcnt(0)
	s_barrier
; #define PG8_STAGE(bufoff, gbase, voff) do { _Pragma("unroll") for (int _i = 0; _i < 2; ++_i) \
;         __builtin_amdgcn_global_load_lds((const unsigned*)((const char*)(gbase) + (voff)[_i]), (LAS unsigned*)(lds + (bufoff) + ldsw + _i * 8192), 16, 0, 0); } while (0)
; #define PG8_LDA(dst, b, h) do { _Pragma("unroll") for (int m = 0; m < 4; ++m) _Pragma("unroll") for (int k = 0; k < 2; ++k) dst[m][k] = *(const LAS bf16x8*)(lds + PG8_SA(b, h) + aoff + m * 2048 + k * 1024); } while (0)
; #define PG8_MMA(ai, bj, At, Bt) do { __builtin_amdgcn_s_setprio(1); _Pragma("unroll") for (int m = 0; m < 4; ++m) _Pragma("unroll") for (int n = 0; n < 2; ++n) _Pragma("unroll") for (int k = 0; k < 2; ++k) \
;         acc[ai][bj][m][n] = __builtin_amdgcn_mfma_f32_16x16x32_bf16(Bt[n][k], At[m][k], acc[ai][bj][m][n], 0, 0, 0); __builtin_amdgcn_s_setprio(0); } while (0)
; #define PG8_WAIT_V(n) asm volatile("s_waitcnt vmcnt(" #n ")" ::: "memory")
; #define PG8_WAIT_L(n) asm volatile("s_waitcnt lgkmcnt(" #n ")" ::: "memory")
; #define PG8_BAR __builtin_amdgcn_s_barrier()
; #define PG8_SCHED __builtin_amdgcn_sched_barrier(0)
; __device__ __forceinline__ void gemm_phase(LAS unsigned char* lds, const Params& p, const bf16_t* gA, const bf16_t* gBt, const int gM, const int gN, const int gK, const int epi, const int perm, bf16_t* const Hp, const int goff, const float coef) {
;     ...
;             PG8_WAIT_V(8); PG8_WAIT_L(0); PG8_BAR; PG8_MMA(0, 0, At, B0); PG8_MMA(0, 1, At, B1); PG8_BAR; PG8_SCHED;
;             PG8_LDA(At, 0, 1); PG8_STAGE(PG8_SB(0, 0), b2, voffB); PG8_STAGE(PG8_SB(0, 1), b2 + hstep, voffB); PG8_STAGE(PG8_SA(0, 0), a2, voffA);
;             PG8_WAIT_V(8); PG8_WAIT_L(0); PG8_BAR; PG8_MMA(1, 0, At, B0); PG8_MMA(1, 1, At, B1); PG8_BAR; PG8_SCHED;
	s_waitcnt lgkmcnt(0)
	v_mfma_f32_16x16x32_bf16 v[124:127], v[160:163], v[192:195], v[124:127]
	v_mfma_f32_16x16x32_bf16 v[120:123], v[168:171], v[192:195], v[120:123]
	v_mfma_f32_16x16x32_bf16 v[108:111], v[160:163], v[200:203], v[108:111]
	v_mfma_f32_16x16x32_bf16 v[104:107], v[168:171], v[200:203], v[104:107]
	v_mfma_f32_16x16x32_bf16 v[92:95], v[160:163], v[208:211], v[92:95]
	v_mfma_f32_16x16x32_bf16 v[88:91], v[168:171], v[208:211], v[88:91]
	v_mfma_f32_16x16x32_bf16 v[76:79], v[160:163], v[216:219], v[76:79]
	v_mfma_f32_16x16x32_bf16 v[72:75], v[168:171], v[216:219], v[72:75]
	v_mfma_f32_16x16x32_bf16 v[124:127], v[164:167], v[196:199], v[124:127]
	v_mfma_f32_16x16x32_bf16 v[120:123], v[172:175], v[196:199], v[120:123]
	v_mfma_f32_16x16x32_bf16 v[108:111], v[164:167], v[204:207], v[108:111]
	v_mfma_f32_16x16x32_bf16 v[104:107], v[172:175], v[204:207], v[104:107]
	v_mfma_f32_16x16x32_bf16 v[92:95], v[164:167], v[212:215], v[92:95]
	v_mfma_f32_16x16x32_bf16 v[88:91], v[172:175], v[212:215], v[88:91]
	v_mfma_f32_16x16x32_bf16 v[76:79], v[164:167], v[220:223], v[76:79]
	v_mfma_f32_16x16x32_bf16 v[72:75], v[172:175], v[220:223], v[72:75]
	v_mfma_f32_16x16x32_bf16 v[116:119], v[176:179], v[192:195], v[116:119]
	v_mfma_f32_16x16x32_bf16 v[112:115], v[184:187], v[192:195], v[112:115]
	v_mfma_f32_16x16x32_bf16 v[100:103], v[176:179], v[200:203], v[100:103]
	v_mfma_f32_16x16x32_bf16 v[96:99], v[184:187], v[200:203], v[96:99]
	v_mfma_f32_16x16x32_bf16 v[84:87], v[176:179], v[208:211], v[84:87]
	v_mfma_f32_16x16x32_bf16 v[80:83], v[184:187], v[208:211], v[80:83]
	v_mfma_f32_16x16x32_bf16 v[68:71], v[176:179], v[216:219], v[68:71]
	v_mfma_f32_16x16x32_bf16 v[64:67], v[184:187], v[216:219], v[64:67]
	v_mfma_f32_16x16x32_bf16 v[116:119], v[180:183], v[196:199], v[116:119]
	v_mfma_f32_16x16x32_bf16 v[112:115], v[188:191], v[196:199], v[112:115]
	v_mfma_f32_16x16x32_bf16 v[100:103], v[180:183], v[204:207], v[100:103]
	v_mfma_f32_16x16x32_bf16 v[96:99], v[188:191], v[204:207], v[96:99]
	v_mfma_f32_16x16x32_bf16 v[84:87], v[180:183], v[212:215], v[84:87]
	v_mfma_f32_16x16x32_bf16 v[80:83], v[188:191], v[212:215], v[80:83]
	v_mfma_f32_16x16x32_bf16 v[68:71], v[180:183], v[220:223], v[68:71]
	v_mfma_f32_16x16x32_bf16 v[64:67], v[188:191], v[220:223], v[64:67]
	s_barrier
	s_add_i32 s55, s44, s36
	v_lshl_add_u64 v[144:145], s[28:29], 0, v[130:131]
	s_mov_b32 m0, s55
	ds_read_b128 v[192:195], v158 offset:16384
	ds_read_b128 v[196:199], v158 offset:17408
	ds_read_b128 v[200:203], v158 offset:18432
	ds_read_b128 v[204:207], v158 offset:19456
	ds_read_b128 v[208:211], v158 offset:20480
	ds_read_b128 v[212:215], v158 offset:21504
	ds_read_b128 v[216:219], v158 offset:22528
	ds_read_b128 v[220:223], v158 offset:23552
	global_load_lds_dwordx4 v[144:145], off
	s_add_i32 m0, s55, 0x2000
	s_add_u32 s56, s28, 0x80000
	v_lshl_add_u64 v[224:225], s[28:29], 0, v[134:135]
	s_addc_u32 s57, s29, 0
	s_add_i32 s55, s45, s36
	global_load_lds_dwordx4 v[224:225], off
	v_lshl_add_u64 v[226:227], s[56:57], 0, v[130:131]
	s_mov_b32 m0, s55
	v_lshl_add_u64 v[228:229], s[30:31], 0, v[132:133]
	global_load_lds_dwordx4 v[226:227], off
	v_lshl_add_u64 v[226:227], s[56:57], 0, v[134:135]
	s_add_i32 m0, s55, 0x2000
	s_nop 0
	global_load_lds_dwordx4 v[226:227], off
	v_lshl_add_u64 v[226:227], s[30:31], 0, v[128:129]
	s_mov_b32 m0, s23
	s_nop 0
	global_load_lds_dwordx4 v[226:227], off
	s_mov_b32 m0, s25
	s_nop 0
	global_load_lds_dwordx4 v[228:229], off
	s_waitcnt vmcnt(8)
	s_waitcnt lgkmcnt(0)
	s_barrier
	s_waitcnt lgkmcnt(0)
	v_mfma_f32_16x16x32_bf16 v[60:63], v[160:163], v[192:195], v[60:63]
	v_mfma_f32_16x16x32_bf16 v[56:59], v[168:171], v[192:195], v[56:59]
	v_mfma_f32_16x16x32_bf16 v[44:47], v[160:163], v[200:203], v[44:47]
	v_mfma_f32_16x16x32_bf16 v[40:43], v[168:171], v[200:203], v[40:43]
	v_mfma_f32_16x16x32_bf16 v[28:31], v[160:163], v[208:211], v[28:31]
	v_mfma_f32_16x16x32_bf16 v[24:27], v[168:171], v[208:211], v[24:27]
	v_mfma_f32_16x16x32_bf16 v[12:15], v[160:163], v[216:219], v[12:15]
	v_mfma_f32_16x16x32_bf16 v[8:11], v[168:171], v[216:219], v[8:11]
	v_mfma_f32_16x16x32_bf16 v[60:63], v[164:167], v[196:199], v[60:63]
	v_mfma_f32_16x16x32_bf16 v[56:59], v[172:175], v[196:199], v[56:59]
	v_mfma_f32_16x16x32_bf16 v[44:47], v[164:167], v[204:207], v[44:47]
	v_mfma_f32_16x16x32_bf16 v[40:43], v[172:175], v[204:207], v[40:43]
	v_mfma_f32_16x16x32_bf16 v[28:31], v[164:167], v[212:215], v[28:31]
	v_mfma_f32_16x16x32_bf16 v[24:27], v[172:175], v[212:215], v[24:27]
	v_mfma_f32_16x16x32_bf16 v[12:15], v[164:167], v[220:223], v[12:15]
	v_mfma_f32_16x16x32_bf16 v[8:11], v[172:175], v[220:223], v[8:11]
	v_mfma_f32_16x16x32_bf16 v[52:55], v[176:179], v[192:195], v[52:55]
	v_mfma_f32_16x16x32_bf16 v[48:51], v[184:187], v[192:195], v[48:51]
	v_mfma_f32_16x16x32_bf16 v[36:39], v[176:179], v[200:203], v[36:39]
	v_mfma_f32_16x16x32_bf16 v[32:35], v[184:187], v[200:203], v[32:35]
	v_mfma_f32_16x16x32_bf16 v[20:23], v[176:179], v[208:211], v[20:23]
	v_mfma_f32_16x16x32_bf16 v[16:19], v[184:187], v[208:211], v[16:19]
	v_mfma_f32_16x16x32_bf16 v[4:7], v[176:179], v[216:219], v[4:7]
	v_mfma_f32_16x16x32_bf16 v[0:3], v[184:187], v[216:219], v[0:3]
	v_mfma_f32_16x16x32_bf16 v[52:55], v[180:183], v[196:199], v[52:55]
	v_mfma_f32_16x16x32_bf16 v[48:51], v[188:191], v[196:199], v[48:51]
	v_mfma_f32_16x16x32_bf16 v[36:39], v[180:183], v[204:207], v[36:39]
	v_mfma_f32_16x16x32_bf16 v[32:35], v[188:191], v[204:207], v[32:35]
	v_mfma_f32_16x16x32_bf16 v[20:23], v[180:183], v[212:215], v[20:23]
	v_mfma_f32_16x16x32_bf16 v[16:19], v[188:191], v[212:215], v[16:19]
	v_mfma_f32_16x16x32_bf16 v[4:7], v[180:183], v[220:223], v[4:7]
	v_mfma_f32_16x16x32_bf16 v[0:3], v[188:191], v[220:223], v[0:3]
	s_barrier
; #define PG8_STAGE(bufoff, gbase, voff) do { _Pragma("unroll") for (int _i = 0; _i < 2; ++_i) \
;         __builtin_amdgcn_global_load_lds((const unsigned*)((const char*)(gbase) + (voff)[_i]), (LAS unsigned*)(lds + (bufoff) + ldsw + _i * 8192), 16, 0, 0); } while (0)
; #define PG8_LDA(dst, b, h) do { _Pragma("unroll") for (int m = 0; m < 4; ++m) _Pragma("unroll") for (int k = 0; k < 2; ++k) dst[m][k] = *(const LAS bf16x8*)(lds + PG8_SA(b, h) + aoff + m * 2048 + k * 1024); } while (0)
; #define PG8_LDB(dst, b, h) do { _Pragma("unroll") for (int n = 0; n < 2; ++n) _Pragma("unroll") for (int k = 0; k < 2; ++k) dst[n][k] = *(const LAS bf16x8*)(lds + PG8_SB(b, h) + boff + n * 2048 + k * 1024); } while (0)
; #define PG8_MMA(ai, bj, At, Bt) do { __builtin_amdgcn_s_setprio(1); _Pragma("unroll") for (int m = 0; m < 4; ++m) _Pragma("unroll") for (int n = 0; n < 2; ++n) _Pragma("unroll") for (int k = 0; k < 2; ++k) \
;         acc[ai][bj][m][n] = __builtin_amdgcn_mfma_f32_16x16x32_bf16(Bt[n][k], At[m][k], acc[ai][bj][m][n], 0, 0, 0); __builtin_amdgcn_s_setprio(0); } while (0)
; #define PG8_WAIT_V(n) asm volatile("s_waitcnt vmcnt(" #n ")" ::: "memory")
; #define PG8_WAIT_L(n) asm volatile("s_waitcnt lgkmcnt(" #n ")" ::: "memory")
; #define PG8_BAR __builtin_amdgcn_s_barrier()
; #define PG8_SCHED __builtin_amdgcn_sched_barrier(0)
; __device__ __forceinline__ void gemm_phase(LAS unsigned char* lds, const Params& p, const bf16_t* gA, const bf16_t* gBt, const int gM, const int gN, const int gK, const int epi, const int perm, bf16_t* const Hp, const int goff, const float coef) {
;     ...
;             PG8_LDB(B0, 1, 0); PG8_LDB(B1, 1, 1); PG8_SCHED; PG8_LDA(At, 1, 0); PG8_STAGE(PG8_SA(0, 1), a2 + hstep, voffA);
;             PG8_WAIT_V(8); PG8_WAIT_L(0); PG8_BAR; PG8_MMA(0, 0, At, B0); PG8_MMA(0, 1, At, B1); PG8_BAR; PG8_SCHED;
;             PG8_LDA(At, 1, 1); PG8_STAGE(PG8_SB(1, 0), b3, voffB); PG8_STAGE(PG8_SB(1, 1), b3 + hstep, voffB); PG8_STAGE(PG8_SA(1, 0), a3, voffA);
;             PG8_WAIT_V(8); PG8_WAIT_L(0); PG8_BAR; PG8_MMA(1, 0, At, B0); PG8_MMA(1, 1, At, B1); PG8_BAR; PG8_SCHED;
	s_add_i32 s55, 0, 0x18000
	v_add_u32_e32 v141, s55, v147
	s_add_i32 s56, 0, 0x1c000
	ds_read_b128 v[160:163], v141
	ds_read_b128 v[164:167], v141 offset:1024
	ds_read_b128 v[168:171], v141 offset:2048
	ds_read_b128 v[172:175], v141 offset:3072
	v_add_u32_e32 v141, s56, v147
	ds_read_b128 v[176:179], v141
	ds_read_b128 v[180:183], v141 offset:1024
	ds_read_b128 v[184:187], v141 offset:2048
	ds_read_b128 v[188:191], v141 offset:3072
	s_add_u32 s30, s30, 0x80000
	s_addc_u32 s31, s31, 0
	s_mov_b32 m0, s37
	v_lshl_add_u64 v[230:231], s[30:31], 0, v[128:129]
	ds_read_b128 v[192:195], v158 offset:32768
	ds_read_b128 v[196:199], v158 offset:33792
	ds_read_b128 v[200:203], v158 offset:34816
	ds_read_b128 v[204:207], v158 offset:35840
	ds_read_b128 v[208:211], v158 offset:36864
	ds_read_b128 v[212:215], v158 offset:37888
	ds_read_b128 v[216:219], v158 offset:38912
	ds_read_b128 v[220:223], v158 offset:39936
	global_load_lds_dwordx4 v[230:231], off
	v_lshl_add_u64 v[230:231], s[30:31], 0, v[132:133]
	s_mov_b32 m0, s38
	s_nop 0
	global_load_lds_dwordx4 v[230:231], off
	s_waitcnt vmcnt(8)
	s_waitcnt lgkmcnt(0)
	s_barrier
	s_waitcnt lgkmcnt(0)
	v_mfma_f32_16x16x32_bf16 v[124:127], v[160:163], v[192:195], v[124:127]
	v_mfma_f32_16x16x32_bf16 v[120:123], v[168:171], v[192:195], v[120:123]
	v_mfma_f32_16x16x32_bf16 v[108:111], v[160:163], v[200:203], v[108:111]
	v_mfma_f32_16x16x32_bf16 v[104:107], v[168:171], v[200:203], v[104:107]
	v_mfma_f32_16x16x32_bf16 v[92:95], v[160:163], v[208:211], v[92:95]
	v_mfma_f32_16x16x32_bf16 v[88:91], v[168:171], v[208:211], v[88:91]
	v_mfma_f32_16x16x32_bf16 v[76:79], v[160:163], v[216:219], v[76:79]
	v_mfma_f32_16x16x32_bf16 v[72:75], v[168:171], v[216:219], v[72:75]
	v_mfma_f32_16x16x32_bf16 v[124:127], v[164:167], v[196:199], v[124:127]
	v_mfma_f32_16x16x32_bf16 v[120:123], v[172:175], v[196:199], v[120:123]
	v_mfma_f32_16x16x32_bf16 v[108:111], v[164:167], v[204:207], v[108:111]
	v_mfma_f32_16x16x32_bf16 v[104:107], v[172:175], v[204:207], v[104:107]
	v_mfma_f32_16x16x32_bf16 v[92:95], v[164:167], v[212:215], v[92:95]
	v_mfma_f32_16x16x32_bf16 v[88:91], v[172:175], v[212:215], v[88:91]
	v_mfma_f32_16x16x32_bf16 v[76:79], v[164:167], v[220:223], v[76:79]
	v_mfma_f32_16x16x32_bf16 v[72:75], v[172:175], v[220:223], v[72:75]
	v_mfma_f32_16x16x32_bf16 v[116:119], v[176:179], v[192:195], v[116:119]
	v_mfma_f32_16x16x32_bf16 v[112:115], v[184:187], v[192:195], v[112:115]
	v_mfma_f32_16x16x32_bf16 v[100:103], v[176:179], v[200:203], v[100:103]
	v_mfma_f32_16x16x32_bf16 v[96:99], v[184:187], v[200:203], v[96:99]
	v_mfma_f32_16x16x32_bf16 v[84:87], v[176:179], v[208:211], v[84:87]
	v_mfma_f32_16x16x32_bf16 v[80:83], v[184:187], v[208:211], v[80:83]
	v_mfma_f32_16x16x32_bf16 v[68:71], v[176:179], v[216:219], v[68:71]
	v_mfma_f32_16x16x32_bf16 v[64:67], v[184:187], v[216:219], v[64:67]
	v_mfma_f32_16x16x32_bf16 v[116:119], v[180:183], v[196:199], v[116:119]
	v_mfma_f32_16x16x32_bf16 v[112:115], v[188:191], v[196:199], v[112:115]
	v_mfma_f32_16x16x32_bf16 v[100:103], v[180:183], v[204:207], v[100:103]
	v_mfma_f32_16x16x32_bf16 v[96:99], v[188:191], v[204:207], v[96:99]
	v_mfma_f32_16x16x32_bf16 v[84:87], v[180:183], v[212:215], v[84:87]
	v_mfma_f32_16x16x32_bf16 v[80:83], v[188:191], v[212:215], v[80:83]
	v_mfma_f32_16x16x32_bf16 v[68:71], v[180:183], v[220:223], v[68:71]
	v_mfma_f32_16x16x32_bf16 v[64:67], v[188:191], v[220:223], v[64:67]
	s_barrier
	s_add_i32 s30, s55, s36
	v_lshl_add_u64 v[144:145], v[144:145], 0, s[8:9]
	s_mov_b32 m0, s30
	ds_read_b128 v[192:195], v158 offset:49152
	ds_read_b128 v[196:199], v158 offset:50176
	ds_read_b128 v[200:203], v158 offset:51200
	ds_read_b128 v[204:207], v158 offset:52224
	ds_read_b128 v[208:211], v158 offset:53248
	ds_read_b128 v[212:215], v158 offset:54272
	ds_read_b128 v[216:219], v158 offset:55296
	ds_read_b128 v[220:223], v158 offset:56320
	global_load_lds_dwordx4 v[144:145], off
	s_add_i32 m0, s30, 0x2000
	s_add_u32 s28, s28, 0x80080
	v_lshl_add_u64 v[144:145], v[224:225], 0, s[8:9]
	s_addc_u32 s29, s29, 0
	s_add_i32 s30, s56, s36
	global_load_lds_dwordx4 v[144:145], off
	v_lshl_add_u64 v[144:145], s[28:29], 0, v[130:131]
	s_mov_b32 m0, s30
	s_nop 0
	global_load_lds_dwordx4 v[144:145], off
	v_lshl_add_u64 v[144:145], s[28:29], 0, v[134:135]
	s_add_i32 m0, s30, 0x2000
	s_nop 0
	global_load_lds_dwordx4 v[144:145], off
	v_lshl_add_u64 v[144:145], v[226:227], 0, s[8:9]
	s_mov_b32 m0, s40
	s_nop 0
	global_load_lds_dwordx4 v[144:145], off
	v_lshl_add_u64 v[144:145], v[228:229], 0, s[8:9]
	s_mov_b32 m0, s41
	s_nop 0
	global_load_lds_dwordx4 v[144:145], off
	s_waitcnt vmcnt(8)
	s_waitcnt lgkmcnt(0)
	s_barrier
	s_waitcnt lgkmcnt(0)
	v_mfma_f32_16x16x32_bf16 v[60:63], v[160:163], v[192:195], v[60:63]
	v_mfma_f32_16x16x32_bf16 v[56:59], v[168:171], v[192:195], v[56:59]
	v_mfma_f32_16x16x32_bf16 v[44:47], v[160:163], v[200:203], v[44:47]
	v_mfma_f32_16x16x32_bf16 v[40:43], v[168:171], v[200:203], v[40:43]
	v_mfma_f32_16x16x32_bf16 v[28:31], v[160:163], v[208:211], v[28:31]
	v_mfma_f32_16x16x32_bf16 v[24:27], v[168:171], v[208:211], v[24:27]
	v_mfma_f32_16x16x32_bf16 v[12:15], v[160:163], v[216:219], v[12:15]
	v_mfma_f32_16x16x32_bf16 v[8:11], v[168:171], v[216:219], v[8:11]
	v_mfma_f32_16x16x32_bf16 v[60:63], v[164:167], v[196:199], v[60:63]
	v_mfma_f32_16x16x32_bf16 v[56:59], v[172:175], v[196:199], v[56:59]
	v_mfma_f32_16x16x32_bf16 v[44:47], v[164:167], v[204:207], v[44:47]
	v_mfma_f32_16x16x32_bf16 v[40:43], v[172:175], v[204:207], v[40:43]
	v_mfma_f32_16x16x32_bf16 v[28:31], v[164:167], v[212:215], v[28:31]
	v_mfma_f32_16x16x32_bf16 v[24:27], v[172:175], v[212:215], v[24:27]
	v_mfma_f32_16x16x32_bf16 v[12:15], v[164:167], v[220:223], v[12:15]
	v_mfma_f32_16x16x32_bf16 v[8:11], v[172:175], v[220:223], v[8:11]
	v_mfma_f32_16x16x32_bf16 v[52:55], v[176:179], v[192:195], v[52:55]
	v_mfma_f32_16x16x32_bf16 v[48:51], v[184:187], v[192:195], v[48:51]
	v_mfma_f32_16x16x32_bf16 v[36:39], v[176:179], v[200:203], v[36:39]
	v_mfma_f32_16x16x32_bf16 v[32:35], v[184:187], v[200:203], v[32:35]
	v_mfma_f32_16x16x32_bf16 v[20:23], v[176:179], v[208:211], v[20:23]
	v_mfma_f32_16x16x32_bf16 v[16:19], v[184:187], v[208:211], v[16:19]
	v_mfma_f32_16x16x32_bf16 v[4:7], v[176:179], v[216:219], v[4:7]
	v_mfma_f32_16x16x32_bf16 v[0:3], v[184:187], v[216:219], v[0:3]
	v_mfma_f32_16x16x32_bf16 v[52:55], v[180:183], v[196:199], v[52:55]
	v_mfma_f32_16x16x32_bf16 v[48:51], v[188:191], v[196:199], v[48:51]
	v_mfma_f32_16x16x32_bf16 v[36:39], v[180:183], v[204:207], v[36:39]
	v_mfma_f32_16x16x32_bf16 v[32:35], v[188:191], v[204:207], v[32:35]
	v_mfma_f32_16x16x32_bf16 v[20:23], v[180:183], v[212:215], v[20:23]
	v_mfma_f32_16x16x32_bf16 v[16:19], v[188:191], v[212:215], v[16:19]
	v_mfma_f32_16x16x32_bf16 v[4:7], v[180:183], v[220:223], v[4:7]
	v_mfma_f32_16x16x32_bf16 v[0:3], v[188:191], v[220:223], v[0:3]
	s_barrier
	s_add_u32 s26, s26, 0x100
	s_addc_u32 s27, s27, 0
	s_add_u32 s52, s52, 0x100
	s_addc_u32 s53, s53, 0
	s_cmp_ge_u32 s54, s50
	s_mov_b32 s30, s54
	s_cbranch_scc0 .LBB0_1737

; #define PG8_STAGE(bufoff, gbase, voff) do { _Pragma("unroll") for (int _i = 0; _i < 2; ++_i) \
;         __builtin_amdgcn_global_load_lds((const unsigned*)((const char*)(gbase) + (voff)[_i]), (LAS unsigned*)(lds + (bufoff) + ldsw + _i * 8192), 16, 0, 0); } while (0)
; #define PG8_LDA(dst, b, h) do { _Pragma("unroll") for (int m = 0; m < 4; ++m) _Pragma("unroll") for (int k = 0; k < 2; ++k) dst[m][k] = *(const LAS bf16x8*)(lds + PG8_SA(b, h) + aoff + m * 2048 + k * 1024); } while (0)
; #define PG8_LDB(dst, b, h) do { _Pragma("unroll") for (int n = 0; n < 2; ++n) _Pragma("unroll") for (int k = 0; k < 2; ++k) dst[n][k] = *(const LAS bf16x8*)(lds + PG8_SB(b, h) + boff + n * 2048 + k * 1024); } while (0)
; #define PG8_WAIT_V(n) asm volatile("s_waitcnt vmcnt(" #n ")" ::: "memory")
; #define PG8_WAIT_L(n) asm volatile("s_waitcnt lgkmcnt(" #n ")" ::: "memory")
; #define PG8_BAR __builtin_amdgcn_s_barrier()
; __device__ __forceinline__ void gemm_phase(LAS unsigned char* lds, const Params& p, const bf16_t* gA, const bf16_t* gBt, const int gM, const int gN, const int gK, const int epi, const int perm, bf16_t* const Hp, const int goff, const float coef) {
;     ...
;         const bool has_next = S.next(ui + 1, nxt);
;         const char* nA = has_next ? (const char*)gA + (size_t)nxt.pm * tstep + (nxt.ks > 0 ? nxt.ks * ksl : 0) : cA; const char* nB = has_next ? (const char*)gBt + (size_t)nxt.pn * tstep + (nxt.ks > 0 ? nxt.ks * ksl : 0) : cB;
;         const int nt = cur.ks >= 0 ? ntf / 4 : ntf;
;         for (int t = 0; t < nt; t += 2) {
;             const bool last = (t == nt - 2);
;             const char* a1 = cA + (size_t)(t + 1) * kstep;
;             const char* a2 = last ? nA : cA + (size_t)(t + 2) * kstep; const char* b2 = last ? nB : cB + (size_t)(t + 2) * kstep;
;             const char* a3 = a2 + kstep; const char* b3 = b2 + kstep;
;             PG8_LDB(B0, 0, 0); PG8_LDB(B1, 0, 1); PG8_SCHED; PG8_LDA(At, 0, 0); PG8_STAGE(PG8_SA(1, 1), a1 + hstep, voffA);
;             PG8_WAIT_V(8); PG8_WAIT_L(0); PG8_BAR; PG8_MMA(0, 0, At, B0); PG8_MMA(0, 1, At, B1); PG8_BAR; PG8_SCHED;
;             PG8_LDA(At, 0, 1); PG8_STAGE(PG8_SB(0, 0), b2, voffB); PG8_STAGE(PG8_SB(0, 1), b2 + hstep, voffB); PG8_STAGE(PG8_SA(0, 0), a2, voffA);
;             PG8_WAIT_V(8); PG8_WAIT_L(0); PG8_BAR; PG8_MMA(1, 0, At, B0); PG8_MMA(1, 1, At, B1); PG8_BAR; PG8_SCHED;
.LBB0_1826:
	s_cmp_gt_i32 s6, -1
	s_cselect_b64 s[4:5], -1, 0
	s_and_b64 s[22:23], s[4:5], exec
	s_cselect_b32 s50, 22, 0x58
	s_add_i32 s51, s50, -2
	s_add_u32 s18, s18, 0x160080
	s_addc_u32 s19, s19, 0
	s_add_u32 s52, s20, 0x100
	s_addc_u32 s53, s21, 0
	s_mov_b32 s20, 0
	ds_read_b128 v[144:147], v166
	ds_read_b128 v[148:151], v166 offset:1024
	ds_read_b128 v[152:155], v166 offset:2048
	ds_read_b128 v[170:173], v166 offset:3072
	ds_read_b128 v[174:177], v167
	ds_read_b128 v[178:181], v167 offset:1024
	ds_read_b128 v[182:185], v167 offset:2048
	ds_read_b128 v[186:189], v167 offset:3072
	s_add_i32 s54, s20, 2
	s_add_u32 s21, s18, 0xffea0080
	s_addc_u32 s22, s19, -1
	s_cmp_eq_u32 s51, s20
	s_cselect_b32 s20, s16, s52
	s_cselect_b32 s23, s15, s22
	s_cselect_b32 s22, s14, s21
	s_cselect_b32 s21, s17, s53
	v_lshl_add_u64 v[222:223], s[18:19], 0, v[136:137]
	s_add_i32 m0, s28, 0xc000
	ds_read_b128 v[190:193], v168
	ds_read_b128 v[194:197], v168 offset:1024
	ds_read_b128 v[198:201], v168 offset:2048
	ds_read_b128 v[202:205], v168 offset:3072
	ds_read_b128 v[206:209], v168 offset:4096
	ds_read_b128 v[210:213], v168 offset:5120
	ds_read_b128 v[214:217], v168 offset:6144
	ds_read_b128 v[218:221], v168 offset:7168
	global_load_lds_dwordx4 v[222:223], off
	v_lshl_add_u64 v[222:223], s[18:19], 0, v[138:139]
	s_add_i32 m0, s28, 0xe000
	s_nop 0
	global_load_lds_dwordx4 v[222:223], off
	s_waitcnt vmcnt(8)
	s_waitcnt lgkmcnt(0)
	s_barrier
	s_waitcnt lgkmcnt(0)
	v_mfma_f32_16x16x32_bf16 v[124:127], v[144:147], v[190:193], 0
	v_mfma_f32_16x16x32_bf16 v[120:123], v[152:155], v[190:193], 0
	v_mfma_f32_16x16x32_bf16 v[116:119], v[144:147], v[198:201], 0
	v_mfma_f32_16x16x32_bf16 v[112:115], v[152:155], v[198:201], 0
	v_mfma_f32_16x16x32_bf16 v[108:111], v[144:147], v[206:209], 0
	v_mfma_f32_16x16x32_bf16 v[104:107], v[152:155], v[206:209], 0
	v_mfma_f32_16x16x32_bf16 v[100:103], v[144:147], v[214:217], 0
	v_mfma_f32_16x16x32_bf16 v[96:99], v[152:155], v[214:217], 0
	v_mfma_f32_16x16x32_bf16 v[124:127], v[148:151], v[194:197], v[124:127]
	v_mfma_f32_16x16x32_bf16 v[120:123], v[170:173], v[194:197], v[120:123]
	v_mfma_f32_16x16x32_bf16 v[116:119], v[148:151], v[202:205], v[116:119]
	v_mfma_f32_16x16x32_bf16 v[112:115], v[170:173], v[202:205], v[112:115]
	v_mfma_f32_16x16x32_bf16 v[108:111], v[148:151], v[210:213], v[108:111]
	v_mfma_f32_16x16x32_bf16 v[104:107], v[170:173], v[210:213], v[104:107]
	v_mfma_f32_16x16x32_bf16 v[100:103], v[148:151], v[218:221], v[100:103]
	v_mfma_f32_16x16x32_bf16 v[96:99], v[170:173], v[218:221], v[96:99]
	v_mfma_f32_16x16x32_bf16 v[68:71], v[174:177], v[190:193], 0
	v_mfma_f32_16x16x32_bf16 v[60:63], v[182:185], v[190:193], 0
	v_mfma_f32_16x16x32_bf16 v[52:55], v[174:177], v[198:201], 0
	v_mfma_f32_16x16x32_bf16 v[48:51], v[182:185], v[198:201], 0
	v_mfma_f32_16x16x32_bf16 v[44:47], v[174:177], v[206:209], 0
	v_mfma_f32_16x16x32_bf16 v[40:43], v[182:185], v[206:209], 0
	v_mfma_f32_16x16x32_bf16 v[36:39], v[174:177], v[214:217], 0
	v_mfma_f32_16x16x32_bf16 v[32:35], v[182:185], v[214:217], 0
	v_mfma_f32_16x16x32_bf16 v[68:71], v[178:181], v[194:197], v[68:71]
	v_mfma_f32_16x16x32_bf16 v[60:63], v[186:189], v[194:197], v[60:63]
	v_mfma_f32_16x16x32_bf16 v[52:55], v[178:181], v[202:205], v[52:55]
	v_mfma_f32_16x16x32_bf16 v[48:51], v[186:189], v[202:205], v[48:51]
	v_mfma_f32_16x16x32_bf16 v[44:47], v[178:181], v[210:213], v[44:47]
	v_mfma_f32_16x16x32_bf16 v[40:43], v[186:189], v[210:213], v[40:43]
	v_mfma_f32_16x16x32_bf16 v[36:39], v[178:181], v[218:221], v[36:39]
	v_mfma_f32_16x16x32_bf16 v[32:35], v[186:189], v[218:221], v[32:35]
	s_barrier
	s_add_i32 s55, s42, s27
	v_lshl_add_u64 v[222:223], s[20:21], 0, v[130:131]
	s_mov_b32 m0, s55
	ds_read_b128 v[190:193], v168 offset:16384
	ds_read_b128 v[194:197], v168 offset:17408
	ds_read_b128 v[198:201], v168 offset:18432
	ds_read_b128 v[202:205], v168 offset:19456
	ds_read_b128 v[206:209], v168 offset:20480
	ds_read_b128 v[210:213], v168 offset:21504
	ds_read_b128 v[214:217], v168 offset:22528
	ds_read_b128 v[218:221], v168 offset:23552
	global_load_lds_dwordx4 v[222:223], off
	s_add_i32 m0, s55, 0x2000
	s_add_u32 s56, s20, 0x160000
	v_lshl_add_u64 v[224:225], s[20:21], 0, v[134:135]
	s_addc_u32 s57, s21, 0
	s_add_i32 s55, s43, s27
	global_load_lds_dwordx4 v[224:225], off
	v_lshl_add_u64 v[226:227], s[56:57], 0, v[130:131]
	s_mov_b32 m0, s55
	v_lshl_add_u64 v[228:229], s[22:23], 0, v[132:133]
	global_load_lds_dwordx4 v[226:227], off
	v_lshl_add_u64 v[226:227], s[56:57], 0, v[134:135]
	s_add_i32 m0, s55, 0x2000
	s_nop 0
	global_load_lds_dwordx4 v[226:227], off
	v_lshl_add_u64 v[226:227], s[22:23], 0, v[128:129]
	s_mov_b32 m0, s28
	s_nop 0
	global_load_lds_dwordx4 v[226:227], off
	s_mov_b32 m0, s29
	s_nop 0
	global_load_lds_dwordx4 v[228:229], off
	s_waitcnt vmcnt(8)
	s_waitcnt lgkmcnt(0)
	s_barrier
; #define PG8_STAGE(bufoff, gbase, voff) do { _Pragma("unroll") for (int _i = 0; _i < 2; ++_i) \
;         __builtin_amdgcn_global_load_lds((const unsigned*)((const char*)(gbase) + (voff)[_i]), (LAS unsigned*)(lds + (bufoff) + ldsw + _i * 8192), 16, 0, 0); } while (0)
; #define PG8_LDA(dst, b, h) do { _Pragma("unroll") for (int m = 0; m < 4; ++m) _Pragma("unroll") for (int k = 0; k < 2; ++k) dst[m][k] = *(const LAS bf16x8*)(lds + PG8_SA(b, h) + aoff + m * 2048 + k * 1024); } while (0)
; #define PG8_LDB(dst, b, h) do { _Pragma("unroll") for (int n = 0; n < 2; ++n) _Pragma("unroll") for (int k = 0; k < 2; ++k) dst[n][k] = *(const LAS bf16x8*)(lds + PG8_SB(b, h) + boff + n * 2048 + k * 1024); } while (0)
; #define PG8_MMA(ai, bj, At, Bt) do { __builtin_amdgcn_s_setprio(1); _Pragma("unroll") for (int m = 0; m < 4; ++m) _Pragma("unroll") for (int n = 0; n < 2; ++n) _Pragma("unroll") for (int k = 0; k < 2; ++k) \
;         acc[ai][bj][m][n] = __builtin_amdgcn_mfma_f32_16x16x32_bf16(Bt[n][k], At[m][k], acc[ai][bj][m][n], 0, 0, 0); __builtin_amdgcn_s_setprio(0); } while (0)
; #define PG8_WAIT_V(n) asm volatile("s_waitcnt vmcnt(" #n ")" ::: "memory")
; #define PG8_WAIT_L(n) asm volatile("s_waitcnt lgkmcnt(" #n ")" ::: "memory")
; #define PG8_BAR __builtin_amdgcn_s_barrier()
; #define PG8_SCHED __builtin_amdgcn_sched_barrier(0)
; __device__ __forceinline__ void gemm_phase(LAS unsigned char* lds, const Params& p, const bf16_t* gA, const bf16_t* gBt, const int gM, const int gN, const int gK, const int epi, const int perm, bf16_t* const Hp, const int goff, const float coef) {
;     ...
;             PG8_WAIT_V(8); PG8_WAIT_L(0); PG8_BAR; PG8_MMA(1, 0, At, B0); PG8_MMA(1, 1, At, B1); PG8_BAR; PG8_SCHED;
;             PG8_LDB(B0, 1, 0); PG8_LDB(B1, 1, 1); PG8_SCHED; PG8_LDA(At, 1, 0); PG8_STAGE(PG8_SA(0, 1), a2 + hstep, voffA);
;             PG8_WAIT_V(8); PG8_WAIT_L(0); PG8_BAR; PG8_MMA(0, 0, At, B0); PG8_MMA(0, 1, At, B1); PG8_BAR; PG8_SCHED;
	s_waitcnt lgkmcnt(0)
	v_mfma_f32_16x16x32_bf16 v[92:95], v[144:147], v[190:193], 0
	v_mfma_f32_16x16x32_bf16 v[88:91], v[152:155], v[190:193], 0
	v_mfma_f32_16x16x32_bf16 v[84:87], v[144:147], v[198:201], 0
	v_mfma_f32_16x16x32_bf16 v[80:83], v[152:155], v[198:201], 0
	v_mfma_f32_16x16x32_bf16 v[76:79], v[144:147], v[206:209], 0
	v_mfma_f32_16x16x32_bf16 v[72:75], v[152:155], v[206:209], 0
	v_mfma_f32_16x16x32_bf16 v[64:67], v[144:147], v[214:217], 0
	v_mfma_f32_16x16x32_bf16 v[56:59], v[152:155], v[214:217], 0
	v_mfma_f32_16x16x32_bf16 v[92:95], v[148:151], v[194:197], v[92:95]
	v_mfma_f32_16x16x32_bf16 v[88:91], v[170:173], v[194:197], v[88:91]
	v_mfma_f32_16x16x32_bf16 v[84:87], v[148:151], v[202:205], v[84:87]
	v_mfma_f32_16x16x32_bf16 v[80:83], v[170:173], v[202:205], v[80:83]
	v_mfma_f32_16x16x32_bf16 v[76:79], v[148:151], v[210:213], v[76:79]
	v_mfma_f32_16x16x32_bf16 v[72:75], v[170:173], v[210:213], v[72:75]
	v_mfma_f32_16x16x32_bf16 v[64:67], v[148:151], v[218:221], v[64:67]
	v_mfma_f32_16x16x32_bf16 v[56:59], v[170:173], v[218:221], v[56:59]
	v_mfma_f32_16x16x32_bf16 v[28:31], v[174:177], v[190:193], 0
	v_mfma_f32_16x16x32_bf16 v[24:27], v[182:185], v[190:193], 0
	v_mfma_f32_16x16x32_bf16 v[20:23], v[174:177], v[198:201], 0
	v_mfma_f32_16x16x32_bf16 v[16:19], v[182:185], v[198:201], 0
	v_mfma_f32_16x16x32_bf16 v[12:15], v[174:177], v[206:209], 0
	v_mfma_f32_16x16x32_bf16 v[8:11], v[182:185], v[206:209], 0
	v_mfma_f32_16x16x32_bf16 v[4:7], v[174:177], v[214:217], 0
	v_mfma_f32_16x16x32_bf16 v[0:3], v[182:185], v[214:217], 0
	v_mfma_f32_16x16x32_bf16 v[28:31], v[178:181], v[194:197], v[28:31]
	v_mfma_f32_16x16x32_bf16 v[24:27], v[186:189], v[194:197], v[24:27]
	v_mfma_f32_16x16x32_bf16 v[20:23], v[178:181], v[202:205], v[20:23]
	v_mfma_f32_16x16x32_bf16 v[16:19], v[186:189], v[202:205], v[16:19]
	v_mfma_f32_16x16x32_bf16 v[12:15], v[178:181], v[210:213], v[12:15]
	v_mfma_f32_16x16x32_bf16 v[8:11], v[186:189], v[210:213], v[8:11]
	v_mfma_f32_16x16x32_bf16 v[4:7], v[178:181], v[218:221], v[4:7]
	v_mfma_f32_16x16x32_bf16 v[0:3], v[186:189], v[218:221], v[0:3]
	s_barrier
	s_add_i32 s55, 0, 0x18000
	v_add_u32_e32 v141, s55, v157
	s_add_i32 s56, 0, 0x1c000
	ds_read_b128 v[144:147], v141
	ds_read_b128 v[148:151], v141 offset:1024
	ds_read_b128 v[152:155], v141 offset:2048
	ds_read_b128 v[170:173], v141 offset:3072
	v_add_u32_e32 v141, s56, v157
	ds_read_b128 v[174:177], v141
	ds_read_b128 v[178:181], v141 offset:1024
	ds_read_b128 v[182:185], v141 offset:2048
	ds_read_b128 v[186:189], v141 offset:3072
	s_add_u32 s22, s22, 0x160000
	s_addc_u32 s23, s23, 0
	s_mov_b32 m0, s30
	v_lshl_add_u64 v[230:231], s[22:23], 0, v[128:129]
	ds_read_b128 v[190:193], v168 offset:32768
	ds_read_b128 v[194:197], v168 offset:33792
	ds_read_b128 v[198:201], v168 offset:34816
	ds_read_b128 v[202:205], v168 offset:35840
	ds_read_b128 v[206:209], v168 offset:36864
	ds_read_b128 v[210:213], v168 offset:37888
	ds_read_b128 v[214:217], v168 offset:38912
	ds_read_b128 v[218:221], v168 offset:39936
	global_load_lds_dwordx4 v[230:231], off
	v_lshl_add_u64 v[230:231], s[22:23], 0, v[132:133]
	s_mov_b32 m0, s31
	s_nop 0
	global_load_lds_dwordx4 v[230:231], off
	s_waitcnt vmcnt(8)
	s_waitcnt lgkmcnt(0)
	s_barrier
	s_waitcnt lgkmcnt(0)
	v_mfma_f32_16x16x32_bf16 v[124:127], v[144:147], v[190:193], v[124:127]
	v_mfma_f32_16x16x32_bf16 v[120:123], v[152:155], v[190:193], v[120:123]
	v_mfma_f32_16x16x32_bf16 v[116:119], v[144:147], v[198:201], v[116:119]
	v_mfma_f32_16x16x32_bf16 v[112:115], v[152:155], v[198:201], v[112:115]
	v_mfma_f32_16x16x32_bf16 v[108:111], v[144:147], v[206:209], v[108:111]
	v_mfma_f32_16x16x32_bf16 v[104:107], v[152:155], v[206:209], v[104:107]
	v_mfma_f32_16x16x32_bf16 v[100:103], v[144:147], v[214:217], v[100:103]
	v_mfma_f32_16x16x32_bf16 v[96:99], v[152:155], v[214:217], v[96:99]
	v_mfma_f32_16x16x32_bf16 v[124:127], v[148:151], v[194:197], v[124:127]
	v_mfma_f32_16x16x32_bf16 v[120:123], v[170:173], v[194:197], v[120:123]
	v_mfma_f32_16x16x32_bf16 v[116:119], v[148:151], v[202:205], v[116:119]
	v_mfma_f32_16x16x32_bf16 v[112:115], v[170:173], v[202:205], v[112:115]
	v_mfma_f32_16x16x32_bf16 v[108:111], v[148:151], v[210:213], v[108:111]
	v_mfma_f32_16x16x32_bf16 v[104:107], v[170:173], v[210:213], v[104:107]
	v_mfma_f32_16x16x32_bf16 v[100:103], v[148:151], v[218:221], v[100:103]
	v_mfma_f32_16x16x32_bf16 v[96:99], v[170:173], v[218:221], v[96:99]
	v_mfma_f32_16x16x32_bf16 v[68:71], v[174:177], v[190:193], v[68:71]
	v_mfma_f32_16x16x32_bf16 v[60:63], v[182:185], v[190:193], v[60:63]
	v_mfma_f32_16x16x32_bf16 v[52:55], v[174:177], v[198:201], v[52:55]
	v_mfma_f32_16x16x32_bf16 v[48:51], v[182:185], v[198:201], v[48:51]
	v_mfma_f32_16x16x32_bf16 v[44:47], v[174:177], v[206:209], v[44:47]
	v_mfma_f32_16x16x32_bf16 v[40:43], v[182:185], v[206:209], v[40:43]
	v_mfma_f32_16x16x32_bf16 v[36:39], v[174:177], v[214:217], v[36:39]
	v_mfma_f32_16x16x32_bf16 v[32:35], v[182:185], v[214:217], v[32:35]
	v_mfma_f32_16x16x32_bf16 v[68:71], v[178:181], v[194:197], v[68:71]
	v_mfma_f32_16x16x32_bf16 v[60:63], v[186:189], v[194:197], v[60:63]
	v_mfma_f32_16x16x32_bf16 v[52:55], v[178:181], v[202:205], v[52:55]
	v_mfma_f32_16x16x32_bf16 v[48:51], v[186:189], v[202:205], v[48:51]
	v_mfma_f32_16x16x32_bf16 v[44:47], v[178:181], v[210:213], v[44:47]
	v_mfma_f32_16x16x32_bf16 v[40:43], v[186:189], v[210:213], v[40:43]
	v_mfma_f32_16x16x32_bf16 v[36:39], v[178:181], v[218:221], v[36:39]
	v_mfma_f32_16x16x32_bf16 v[32:35], v[186:189], v[218:221], v[32:35]
	s_barrier
; #define PG8_STAGE(bufoff, gbase, voff) do { _Pragma("unroll") for (int _i = 0; _i < 2; ++_i) \
;         __builtin_amdgcn_global_load_lds((const unsigned*)((const char*)(gbase) + (voff)[_i]), (LAS unsigned*)(lds + (bufoff) + ldsw + _i * 8192), 16, 0, 0); } while (0)
; #define PG8_LDA(dst, b, h) do { _Pragma("unroll") for (int m = 0; m < 4; ++m) _Pragma("unroll") for (int k = 0; k < 2; ++k) dst[m][k] = *(const LAS bf16x8*)(lds + PG8_SA(b, h) + aoff + m * 2048 + k * 1024); } while (0)
; #define PG8_LDB(dst, b, h) do { _Pragma("unroll") for (int n = 0; n < 2; ++n) _Pragma("unroll") for (int k = 0; k < 2; ++k) dst[n][k] = *(const LAS bf16x8*)(lds + PG8_SB(b, h) + boff + n * 2048 + k * 1024); } while (0)
; #define PG8_BAR __builtin_amdgcn_s_barrier()
; __device__ __forceinline__ void gemm_phase(LAS unsigned char* lds, const Params& p, const bf16_t* gA, const bf16_t* gBt, const int gM, const int gN, const int gK, const int epi, const int perm, bf16_t* const Hp, const int goff, const float coef) {
;     ...
;         for (int t = 0; t < nt; t += 2) {
;             const bool last = (t == nt - 2);
;             const char* a1 = cA + (size_t)(t + 1) * kstep;
;             const char* a2 = last ? nA : cA + (size_t)(t + 2) * kstep; const char* b2 = last ? nB : cB + (size_t)(t + 2) * kstep;
;             const char* a3 = a2 + kstep; const char* b3 = b2 + kstep;
;             PG8_LDB(B0, 0, 0); PG8_LDB(B1, 0, 1); PG8_SCHED; PG8_LDA(At, 0, 0); PG8_STAGE(PG8_SA(1, 1), a1 + hstep, voffA);
;             PG8_WAIT_V(8); PG8_WAIT_L(0); PG8_BAR; PG8_MMA(0, 0, At, B0); PG8_MMA(0, 1, At, B1); PG8_BAR; PG8_SCHED;
;             PG8_LDA(At, 0, 1); PG8_STAGE(PG8_SB(0, 0), b2, voffB); PG8_STAGE(PG8_SB(0, 1), b2 + hstep, voffB); PG8_STAGE(PG8_SA(0, 0), a2, voffA);
;             PG8_WAIT_V(8); PG8_WAIT_L(0); PG8_BAR; PG8_MMA(1, 0, At, B0); PG8_MMA(1, 1, At, B1); PG8_BAR; PG8_SCHED;
;             PG8_LDB(B0, 1, 0); PG8_LDB(B1, 1, 1); PG8_SCHED; PG8_LDA(At, 1, 0); PG8_STAGE(PG8_SA(0, 1), a2 + hstep, voffA);
;             PG8_WAIT_V(8); PG8_WAIT_L(0); PG8_BAR; PG8_MMA(0, 0, At, B0); PG8_MMA(0, 1, At, B1); PG8_BAR; PG8_SCHED;
;             PG8_LDA(At, 1, 1); PG8_STAGE(PG8_SB(1, 0), b3, voffB); PG8_STAGE(PG8_SB(1, 1), b3 + hstep, voffB); PG8_STAGE(PG8_SA(1, 0), a3, voffA);
;             PG8_WAIT_V(8); PG8_WAIT_L(0); PG8_BAR; PG8_MMA(1, 0, At, B0); PG8_MMA(1, 1, At, B1); PG8_BAR; PG8_SCHED;
	s_add_i32 s22, s55, s27
	v_lshl_add_u64 v[222:223], v[222:223], 0, s[10:11]
	s_mov_b32 m0, s22
	ds_read_b128 v[190:193], v168 offset:49152
	ds_read_b128 v[194:197], v168 offset:50176
	ds_read_b128 v[198:201], v168 offset:51200
	ds_read_b128 v[202:205], v168 offset:52224
	ds_read_b128 v[206:209], v168 offset:53248
	ds_read_b128 v[210:213], v168 offset:54272
	ds_read_b128 v[214:217], v168 offset:55296
	ds_read_b128 v[218:221], v168 offset:56320
	global_load_lds_dwordx4 v[222:223], off
	s_add_i32 m0, s22, 0x2000
	s_add_u32 s20, s20, 0x160080
	v_lshl_add_u64 v[222:223], v[224:225], 0, s[10:11]
	s_addc_u32 s21, s21, 0
	s_add_i32 s22, s56, s27
	global_load_lds_dwordx4 v[222:223], off
	v_lshl_add_u64 v[222:223], s[20:21], 0, v[130:131]
	s_mov_b32 m0, s22
	s_nop 0
	global_load_lds_dwordx4 v[222:223], off
	v_lshl_add_u64 v[222:223], s[20:21], 0, v[134:135]
	s_add_i32 m0, s22, 0x2000
	s_nop 0
	global_load_lds_dwordx4 v[222:223], off
	v_lshl_add_u64 v[222:223], v[226:227], 0, s[10:11]
	s_mov_b32 m0, s36
	s_nop 0
	global_load_lds_dwordx4 v[222:223], off
	v_lshl_add_u64 v[222:223], v[228:229], 0, s[10:11]
	s_mov_b32 m0, s37
	s_nop 0
	global_load_lds_dwordx4 v[222:223], off
	s_waitcnt vmcnt(8)
	s_waitcnt lgkmcnt(0)
	s_barrier
	s_waitcnt lgkmcnt(0)
	v_mfma_f32_16x16x32_bf16 v[92:95], v[144:147], v[190:193], v[92:95]
	v_mfma_f32_16x16x32_bf16 v[88:91], v[152:155], v[190:193], v[88:91]
	v_mfma_f32_16x16x32_bf16 v[84:87], v[144:147], v[198:201], v[84:87]
	v_mfma_f32_16x16x32_bf16 v[80:83], v[152:155], v[198:201], v[80:83]
	v_mfma_f32_16x16x32_bf16 v[76:79], v[144:147], v[206:209], v[76:79]
	v_mfma_f32_16x16x32_bf16 v[72:75], v[152:155], v[206:209], v[72:75]
	v_mfma_f32_16x16x32_bf16 v[64:67], v[144:147], v[214:217], v[64:67]
	v_mfma_f32_16x16x32_bf16 v[56:59], v[152:155], v[214:217], v[56:59]
	v_mfma_f32_16x16x32_bf16 v[92:95], v[148:151], v[194:197], v[92:95]
	v_mfma_f32_16x16x32_bf16 v[88:91], v[170:173], v[194:197], v[88:91]
	v_mfma_f32_16x16x32_bf16 v[84:87], v[148:151], v[202:205], v[84:87]
	v_mfma_f32_16x16x32_bf16 v[80:83], v[170:173], v[202:205], v[80:83]
	v_mfma_f32_16x16x32_bf16 v[76:79], v[148:151], v[210:213], v[76:79]
	v_mfma_f32_16x16x32_bf16 v[72:75], v[170:173], v[210:213], v[72:75]
	v_mfma_f32_16x16x32_bf16 v[64:67], v[148:151], v[218:221], v[64:67]
	v_mfma_f32_16x16x32_bf16 v[56:59], v[170:173], v[218:221], v[56:59]
	v_mfma_f32_16x16x32_bf16 v[28:31], v[174:177], v[190:193], v[28:31]
	v_mfma_f32_16x16x32_bf16 v[24:27], v[182:185], v[190:193], v[24:27]
	v_mfma_f32_16x16x32_bf16 v[20:23], v[174:177], v[198:201], v[20:23]
	v_mfma_f32_16x16x32_bf16 v[16:19], v[182:185], v[198:201], v[16:19]
	v_mfma_f32_16x16x32_bf16 v[12:15], v[174:177], v[206:209], v[12:15]
	v_mfma_f32_16x16x32_bf16 v[8:11], v[182:185], v[206:209], v[8:11]
	v_mfma_f32_16x16x32_bf16 v[4:7], v[174:177], v[214:217], v[4:7]
	v_mfma_f32_16x16x32_bf16 v[0:3], v[182:185], v[214:217], v[0:3]
	v_mfma_f32_16x16x32_bf16 v[28:31], v[178:181], v[194:197], v[28:31]
	v_mfma_f32_16x16x32_bf16 v[24:27], v[186:189], v[194:197], v[24:27]
	v_mfma_f32_16x16x32_bf16 v[20:23], v[178:181], v[202:205], v[20:23]
	v_mfma_f32_16x16x32_bf16 v[16:19], v[186:189], v[202:205], v[16:19]
	v_mfma_f32_16x16x32_bf16 v[12:15], v[178:181], v[210:213], v[12:15]
	v_mfma_f32_16x16x32_bf16 v[8:11], v[186:189], v[210:213], v[8:11]
	v_mfma_f32_16x16x32_bf16 v[4:7], v[178:181], v[218:221], v[4:7]
	v_mfma_f32_16x16x32_bf16 v[0:3], v[186:189], v[218:221], v[0:3]
	s_barrier
	s_add_u32 s18, s18, 0x100
	s_addc_u32 s19, s19, 0
	s_add_u32 s52, s52, 0x100
	s_addc_u32 s53, s53, 0
	s_cmp_ge_u32 s54, s50
	s_mov_b32 s20, s54
	s_cbranch_scc1 .Lpeel_exit_5
.LBB0_1827:
	ds_read_b128 v[144:147], v166
	ds_read_b128 v[148:151], v166 offset:1024
	ds_read_b128 v[152:155], v166 offset:2048
	ds_read_b128 v[170:173], v166 offset:3072
	ds_read_b128 v[174:177], v167
	ds_read_b128 v[178:181], v167 offset:1024
	ds_read_b128 v[182:185], v167 offset:2048
	ds_read_b128 v[186:189], v167 offset:3072
	s_add_i32 s54, s20, 2
	s_add_u32 s21, s18, 0xffea0080
	s_addc_u32 s22, s19, -1
	s_cmp_eq_u32 s51, s20
	s_cselect_b32 s20, s16, s52
	s_cselect_b32 s23, s15, s22
	s_cselect_b32 s22, s14, s21
	s_cselect_b32 s21, s17, s53
	v_lshl_add_u64 v[222:223], s[18:19], 0, v[136:137]
	s_add_i32 m0, s28, 0xc000
	ds_read_b128 v[190:193], v168
	ds_read_b128 v[194:197], v168 offset:1024
	ds_read_b128 v[198:201], v168 offset:2048
	ds_read_b128 v[202:205], v168 offset:3072
	ds_read_b128 v[206:209], v168 offset:4096
	ds_read_b128 v[210:213], v168 offset:5120
	ds_read_b128 v[214:217], v168 offset:6144
	ds_read_b128 v[218:221], v168 offset:7168
	global_load_lds_dwordx4 v[222:223], off
	v_lshl_add_u64 v[222:223], s[18:19], 0, v[138:139]
	s_add_i32 m0, s28, 0xe000
	s_nop 0
	global_load_lds_dwordx4 v[222:223], off
	s_waitcnt vmcnt(8)
	s_waitcnt lgkmcnt(0)
	s_barrier
; #define PG8_STAGE(bufoff, gbase, voff) do { _Pragma("unroll") for (int _i = 0; _i < 2; ++_i) \
;         __builtin_amdgcn_global_load_lds((const unsigned*)((const char*)(gbase) + (voff)[_i]), (LAS unsigned*)(lds + (bufoff) + ldsw + _i * 8192), 16, 0, 0); } while (0)
; #define PG8_LDA(dst, b, h) do { _Pragma("unroll") for (int m = 0; m < 4; ++m) _Pragma("unroll") for (int k = 0; k < 2; ++k) dst[m][k] = *(const LAS bf16x8*)(lds + PG8_SA(b, h) + aoff + m * 2048 + k * 1024); } while (0)
; #define PG8_MMA(ai, bj, At, Bt) do { __builtin_amdgcn_s_setprio(1); _Pragma("unroll") for (int m = 0; m < 4; ++m) _Pragma("unroll") for (int n = 0; n < 2; ++n) _Pragma("unroll") for (int k = 0; k < 2; ++k) \
;         acc[ai][bj][m][n] = __builtin_amdgcn_mfma_f32_16x16x32_bf16(Bt[n][k], At[m][k], acc[ai][bj][m][n], 0, 0, 0); __builtin_amdgcn_s_setprio(0); } while (0)
; #define PG8_WAIT_V(n) asm volatile("s_waitcnt vmcnt(" #n ")" ::: "memory")
; #define PG8_WAIT_L(n) asm volatile("s_waitcnt lgkmcnt(" #n ")" ::: "memory")
; #define PG8_BAR __builtin_amdgcn_s_barrier()
; #define PG8_SCHED __builtin_amdgcn_sched_barrier(0)
; __device__ __forceinline__ void gemm_phase(LAS unsigned char* lds, const Params& p, const bf16_t* gA, const bf16_t* gBt, const int gM, const int gN, const int gK, const int epi, const int perm, bf16_t* const Hp, const int goff, const float coef) {
;     ...
;             PG8_WAIT_V(8); PG8_WAIT_L(0); PG8_BAR; PG8_MMA(0, 0, At, B0); PG8_MMA(0, 1, At, B1); PG8_BAR; PG8_SCHED;
;             PG8_LDA(At, 0, 1); PG8_STAGE(PG8_SB(0, 0), b2, voffB); PG8_STAGE(PG8_SB(0, 1), b2 + hstep, voffB); PG8_STAGE(PG8_SA(0, 0), a2, voffA);
;             PG8_WAIT_V(8); PG8_WAIT_L(0); PG8_BAR; PG8_MMA(1, 0, At, B0); PG8_MMA(1, 1, At, B1); PG8_BAR; PG8_SCHED;
	s_waitcnt lgkmcnt(0)
	v_mfma_f32_16x16x32_bf16 v[124:127], v[144:147], v[190:193], v[124:127]
	v_mfma_f32_16x16x32_bf16 v[120:123], v[152:155], v[190:193], v[120:123]
	v_mfma_f32_16x16x32_bf16 v[116:119], v[144:147], v[198:201], v[116:119]
	v_mfma_f32_16x16x32_bf16 v[112:115], v[152:155], v[198:201], v[112:115]
	v_mfma_f32_16x16x32_bf16 v[108:111], v[144:147], v[206:209], v[108:111]
	v_mfma_f32_16x16x32_bf16 v[104:107], v[152:155], v[206:209], v[104:107]
	v_mfma_f32_16x16x32_bf16 v[100:103], v[144:147], v[214:217], v[100:103]
	v_mfma_f32_16x16x32_bf16 v[96:99], v[152:155], v[214:217], v[96:99]
	v_mfma_f32_16x16x32_bf16 v[124:127], v[148:151], v[194:197], v[124:127]
	v_mfma_f32_16x16x32_bf16 v[120:123], v[170:173], v[194:197], v[120:123]
	v_mfma_f32_16x16x32_bf16 v[116:119], v[148:151], v[202:205], v[116:119]
	v_mfma_f32_16x16x32_bf16 v[112:115], v[170:173], v[202:205], v[112:115]
	v_mfma_f32_16x16x32_bf16 v[108:111], v[148:151], v[210:213], v[108:111]
	v_mfma_f32_16x16x32_bf16 v[104:107], v[170:173], v[210:213], v[104:107]
	v_mfma_f32_16x16x32_bf16 v[100:103], v[148:151], v[218:221], v[100:103]
	v_mfma_f32_16x16x32_bf16 v[96:99], v[170:173], v[218:221], v[96:99]
	v_mfma_f32_16x16x32_bf16 v[68:71], v[174:177], v[190:193], v[68:71]
	v_mfma_f32_16x16x32_bf16 v[60:63], v[182:185], v[190:193], v[60:63]
	v_mfma_f32_16x16x32_bf16 v[52:55], v[174:177], v[198:201], v[52:55]
	v_mfma_f32_16x16x32_bf16 v[48:51], v[182:185], v[198:201], v[48:51]
	v_mfma_f32_16x16x32_bf16 v[44:47], v[174:177], v[206:209], v[44:47]
	v_mfma_f32_16x16x32_bf16 v[40:43], v[182:185], v[206:209], v[40:43]
	v_mfma_f32_16x16x32_bf16 v[36:39], v[174:177], v[214:217], v[36:39]
	v_mfma_f32_16x16x32_bf16 v[32:35], v[182:185], v[214:217], v[32:35]
	v_mfma_f32_16x16x32_bf16 v[68:71], v[178:181], v[194:197], v[68:71]
	v_mfma_f32_16x16x32_bf16 v[60:63], v[186:189], v[194:197], v[60:63]
	v_mfma_f32_16x16x32_bf16 v[52:55], v[178:181], v[202:205], v[52:55]
	v_mfma_f32_16x16x32_bf16 v[48:51], v[186:189], v[202:205], v[48:51]
	v_mfma_f32_16x16x32_bf16 v[44:47], v[178:181], v[210:213], v[44:47]
	v_mfma_f32_16x16x32_bf16 v[40:43], v[186:189], v[210:213], v[40:43]
	v_mfma_f32_16x16x32_bf16 v[36:39], v[178:181], v[218:221], v[36:39]
	v_mfma_f32_16x16x32_bf16 v[32:35], v[186:189], v[218:221], v[32:35]
	s_barrier
	s_add_i32 s55, s42, s27
	v_lshl_add_u64 v[222:223], s[20:21], 0, v[130:131]
	s_mov_b32 m0, s55
	ds_read_b128 v[190:193], v168 offset:16384
	ds_read_b128 v[194:197], v168 offset:17408
	ds_read_b128 v[198:201], v168 offset:18432
	ds_read_b128 v[202:205], v168 offset:19456
	ds_read_b128 v[206:209], v168 offset:20480
	ds_read_b128 v[210:213], v168 offset:21504
	ds_read_b128 v[214:217], v168 offset:22528
	ds_read_b128 v[218:221], v168 offset:23552
	global_load_lds_dwordx4 v[222:223], off
	s_add_i32 m0, s55, 0x2000
	s_add_u32 s56, s20, 0x160000
	v_lshl_add_u64 v[224:225], s[20:21], 0, v[134:135]
	s_addc_u32 s57, s21, 0
	s_add_i32 s55, s43, s27
	global_load_lds_dwordx4 v[224:225], off
	v_lshl_add_u64 v[226:227], s[56:57], 0, v[130:131]
	s_mov_b32 m0, s55
	v_lshl_add_u64 v[228:229], s[22:23], 0, v[132:133]
	global_load_lds_dwordx4 v[226:227], off
	v_lshl_add_u64 v[226:227], s[56:57], 0, v[134:135]
	s_add_i32 m0, s55, 0x2000
	s_nop 0
	global_load_lds_dwordx4 v[226:227], off
	v_lshl_add_u64 v[226:227], s[22:23], 0, v[128:129]
	s_mov_b32 m0, s28
	s_nop 0
	global_load_lds_dwordx4 v[226:227], off
	s_mov_b32 m0, s29
	s_nop 0
	global_load_lds_dwordx4 v[228:229], off
	s_waitcnt vmcnt(8)
	s_waitcnt lgkmcnt(0)
	s_barrier
	s_waitcnt lgkmcnt(0)
	v_mfma_f32_16x16x32_bf16 v[92:95], v[144:147], v[190:193], v[92:95]
	v_mfma_f32_16x16x32_bf16 v[88:91], v[152:155], v[190:193], v[88:91]
	v_mfma_f32_16x16x32_bf16 v[84:87], v[144:147], v[198:201], v[84:87]
	v_mfma_f32_16x16x32_bf16 v[80:83], v[152:155], v[198:201], v[80:83]
	v_mfma_f32_16x16x32_bf16 v[76:79], v[144:147], v[206:209], v[76:79]
	v_mfma_f32_16x16x32_bf16 v[72:75], v[152:155], v[206:209], v[72:75]
	v_mfma_f32_16x16x32_bf16 v[64:67], v[144:147], v[214:217], v[64:67]
	v_mfma_f32_16x16x32_bf16 v[56:59], v[152:155], v[214:217], v[56:59]
	v_mfma_f32_16x16x32_bf16 v[92:95], v[148:151], v[194:197], v[92:95]
	v_mfma_f32_16x16x32_bf16 v[88:91], v[170:173], v[194:197], v[88:91]
	v_mfma_f32_16x16x32_bf16 v[84:87], v[148:151], v[202:205], v[84:87]
	v_mfma_f32_16x16x32_bf16 v[80:83], v[170:173], v[202:205], v[80:83]
	v_mfma_f32_16x16x32_bf16 v[76:79], v[148:151], v[210:213], v[76:79]
	v_mfma_f32_16x16x32_bf16 v[72:75], v[170:173], v[210:213], v[72:75]
	v_mfma_f32_16x16x32_bf16 v[64:67], v[148:151], v[218:221], v[64:67]
	v_mfma_f32_16x16x32_bf16 v[56:59], v[170:173], v[218:221], v[56:59]
	v_mfma_f32_16x16x32_bf16 v[28:31], v[174:177], v[190:193], v[28:31]
	v_mfma_f32_16x16x32_bf16 v[24:27], v[182:185], v[190:193], v[24:27]
	v_mfma_f32_16x16x32_bf16 v[20:23], v[174:177], v[198:201], v[20:23]
	v_mfma_f32_16x16x32_bf16 v[16:19], v[182:185], v[198:201], v[16:19]
	v_mfma_f32_16x16x32_bf16 v[12:15], v[174:177], v[206:209], v[12:15]
	v_mfma_f32_16x16x32_bf16 v[8:11], v[182:185], v[206:209], v[8:11]
	v_mfma_f32_16x16x32_bf16 v[4:7], v[174:177], v[214:217], v[4:7]
	v_mfma_f32_16x16x32_bf16 v[0:3], v[182:185], v[214:217], v[0:3]
	v_mfma_f32_16x16x32_bf16 v[28:31], v[178:181], v[194:197], v[28:31]
	v_mfma_f32_16x16x32_bf16 v[24:27], v[186:189], v[194:197], v[24:27]
	v_mfma_f32_16x16x32_bf16 v[20:23], v[178:181], v[202:205], v[20:23]
	v_mfma_f32_16x16x32_bf16 v[16:19], v[186:189], v[202:205], v[16:19]
	v_mfma_f32_16x16x32_bf16 v[12:15], v[178:181], v[210:213], v[12:15]
	v_mfma_f32_16x16x32_bf16 v[8:11], v[186:189], v[210:213], v[8:11]
	v_mfma_f32_16x16x32_bf16 v[4:7], v[178:181], v[218:221], v[4:7]
	v_mfma_f32_16x16x32_bf16 v[0:3], v[186:189], v[218:221], v[0:3]
	s_barrier
; #define PG8_STAGE(bufoff, gbase, voff) do { _Pragma("unroll") for (int _i = 0; _i < 2; ++_i) \
;         __builtin_amdgcn_global_load_lds((const unsigned*)((const char*)(gbase) + (voff)[_i]), (LAS unsigned*)(lds + (bufoff) + ldsw + _i * 8192), 16, 0, 0); } while (0)
; #define PG8_LDA(dst, b, h) do { _Pragma("unroll") for (int m = 0; m < 4; ++m) _Pragma("unroll") for (int k = 0; k < 2; ++k) dst[m][k] = *(const LAS bf16x8*)(lds + PG8_SA(b, h) + aoff + m * 2048 + k * 1024); } while (0)
; #define PG8_LDB(dst, b, h) do { _Pragma("unroll") for (int n = 0; n < 2; ++n) _Pragma("unroll") for (int k = 0; k < 2; ++k) dst[n][k] = *(const LAS bf16x8*)(lds + PG8_SB(b, h) + boff + n * 2048 + k * 1024); } while (0)
; #define PG8_MMA(ai, bj, At, Bt) do { __builtin_amdgcn_s_setprio(1); _Pragma("unroll") for (int m = 0; m < 4; ++m) _Pragma("unroll") for (int n = 0; n < 2; ++n) _Pragma("unroll") for (int k = 0; k < 2; ++k) \
;         acc[ai][bj][m][n] = __builtin_amdgcn_mfma_f32_16x16x32_bf16(Bt[n][k], At[m][k], acc[ai][bj][m][n], 0, 0, 0); __builtin_amdgcn_s_setprio(0); } while (0)
; #define PG8_WAIT_V(n) asm volatile("s_waitcnt vmcnt(" #n ")" ::: "memory")
; #define PG8_WAIT_L(n) asm volatile("s_waitcnt lgkmcnt(" #n ")" ::: "memory")
; #define PG8_BAR __builtin_amdgcn_s_barrier()
; #define PG8_SCHED __builtin_amdgcn_sched_barrier(0)
; __device__ __forceinline__ void gemm_phase(LAS unsigned char* lds, const Params& p, const bf16_t* gA, const bf16_t* gBt, const int gM, const int gN, const int gK, const int epi, const int perm, bf16_t* const Hp, const int goff, const float coef) {
;     ...
;             PG8_LDB(B0, 1, 0); PG8_LDB(B1, 1, 1); PG8_SCHED; PG8_LDA(At, 1, 0); PG8_STAGE(PG8_SA(0, 1), a2 + hstep, voffA);
;             PG8_WAIT_V(8); PG8_WAIT_L(0); PG8_BAR; PG8_MMA(0, 0, At, B0); PG8_MMA(0, 1, At, B1); PG8_BAR; PG8_SCHED;
	s_add_i32 s55, 0, 0x18000
	v_add_u32_e32 v141, s55, v157
	s_add_i32 s56, 0, 0x1c000
	ds_read_b128 v[144:147], v141
	ds_read_b128 v[148:151], v141 offset:1024
	ds_read_b128 v[152:155], v141 offset:2048
	ds_read_b128 v[170:173], v141 offset:3072
	v_add_u32_e32 v141, s56, v157
	ds_read_b128 v[174:177], v141
	ds_read_b128 v[178:181], v141 offset:1024
	ds_read_b128 v[182:185], v141 offset:2048
	ds_read_b128 v[186:189], v141 offset:3072
	s_add_u32 s22, s22, 0x160000
	s_addc_u32 s23, s23, 0
	s_mov_b32 m0, s30
	v_lshl_add_u64 v[230:231], s[22:23], 0, v[128:129]
	ds_read_b128 v[190:193], v168 offset:32768
	ds_read_b128 v[194:197], v168 offset:33792
	ds_read_b128 v[198:201], v168 offset:34816
	ds_read_b128 v[202:205], v168 offset:35840
	ds_read_b128 v[206:209], v168 offset:36864
	ds_read_b128 v[210:213], v168 offset:37888
	ds_read_b128 v[214:217], v168 offset:38912
	ds_read_b128 v[218:221], v168 offset:39936
	global_load_lds_dwordx4 v[230:231], off
	v_lshl_add_u64 v[230:231], s[22:23], 0, v[132:133]
	s_mov_b32 m0, s31
	s_nop 0
	global_load_lds_dwordx4 v[230:231], off
	s_waitcnt vmcnt(8)
	s_waitcnt lgkmcnt(0)
	s_barrier
	s_waitcnt lgkmcnt(0)
	v_mfma_f32_16x16x32_bf16 v[124:127], v[144:147], v[190:193], v[124:127]
	v_mfma_f32_16x16x32_bf16 v[120:123], v[152:155], v[190:193], v[120:123]
	v_mfma_f32_16x16x32_bf16 v[116:119], v[144:147], v[198:201], v[116:119]
	v_mfma_f32_16x16x32_bf16 v[112:115], v[152:155], v[198:201], v[112:115]
	v_mfma_f32_16x16x32_bf16 v[108:111], v[144:147], v[206:209], v[108:111]
	v_mfma_f32_16x16x32_bf16 v[104:107], v[152:155], v[206:209], v[104:107]
	v_mfma_f32_16x16x32_bf16 v[100:103], v[144:147], v[214:217], v[100:103]
	v_mfma_f32_16x16x32_bf16 v[96:99], v[152:155], v[214:217], v[96:99]
	v_mfma_f32_16x16x32_bf16 v[124:127], v[148:151], v[194:197], v[124:127]
	v_mfma_f32_16x16x32_bf16 v[120:123], v[170:173], v[194:197], v[120:123]
	v_mfma_f32_16x16x32_bf16 v[116:119], v[148:151], v[202:205], v[116:119]
	v_mfma_f32_16x16x32_bf16 v[112:115], v[170:173], v[202:205], v[112:115]
	v_mfma_f32_16x16x32_bf16 v[108:111], v[148:151], v[210:213], v[108:111]
	v_mfma_f32_16x16x32_bf16 v[104:107], v[170:173], v[210:213], v[104:107]
	v_mfma_f32_16x16x32_bf16 v[100:103], v[148:151], v[218:221], v[100:103]
	v_mfma_f32_16x16x32_bf16 v[96:99], v[170:173], v[218:221], v[96:99]
	v_mfma_f32_16x16x32_bf16 v[68:71], v[174:177], v[190:193], v[68:71]
	v_mfma_f32_16x16x32_bf16 v[60:63], v[182:185], v[190:193], v[60:63]
	v_mfma_f32_16x16x32_bf16 v[52:55], v[174:177], v[198:201], v[52:55]
	v_mfma_f32_16x16x32_bf16 v[48:51], v[182:185], v[198:201], v[48:51]
	v_mfma_f32_16x16x32_bf16 v[44:47], v[174:177], v[206:209], v[44:47]
	v_mfma_f32_16x16x32_bf16 v[40:43], v[182:185], v[206:209], v[40:43]
	v_mfma_f32_16x16x32_bf16 v[36:39], v[174:177], v[214:217], v[36:39]
	v_mfma_f32_16x16x32_bf16 v[32:35], v[182:185], v[214:217], v[32:35]
	v_mfma_f32_16x16x32_bf16 v[68:71], v[178:181], v[194:197], v[68:71]
	v_mfma_f32_16x16x32_bf16 v[60:63], v[186:189], v[194:197], v[60:63]
	v_mfma_f32_16x16x32_bf16 v[52:55], v[178:181], v[202:205], v[52:55]
	v_mfma_f32_16x16x32_bf16 v[48:51], v[186:189], v[202:205], v[48:51]
	v_mfma_f32_16x16x32_bf16 v[44:47], v[178:181], v[210:213], v[44:47]
	v_mfma_f32_16x16x32_bf16 v[40:43], v[186:189], v[210:213], v[40:43]
	v_mfma_f32_16x16x32_bf16 v[36:39], v[178:181], v[218:221], v[36:39]
	v_mfma_f32_16x16x32_bf16 v[32:35], v[186:189], v[218:221], v[32:35]
	s_barrier
; #define PG8_STAGE(bufoff, gbase, voff) do { _Pragma("unroll") for (int _i = 0; _i < 2; ++_i) \
;         __builtin_amdgcn_global_load_lds((const unsigned*)((const char*)(gbase) + (voff)[_i]), (LAS unsigned*)(lds + (bufoff) + ldsw + _i * 8192), 16, 0, 0); } while (0)
; #define PG8_LDA(dst, b, h) do { _Pragma("unroll") for (int m = 0; m < 4; ++m) _Pragma("unroll") for (int k = 0; k < 2; ++k) dst[m][k] = *(const LAS bf16x8*)(lds + PG8_SA(b, h) + aoff + m * 2048 + k * 1024); } while (0)
; #define PG8_MMA(ai, bj, At, Bt) do { __builtin_amdgcn_s_setprio(1); _Pragma("unroll") for (int m = 0; m < 4; ++m) _Pragma("unroll") for (int n = 0; n < 2; ++n) _Pragma("unroll") for (int k = 0; k < 2; ++k) \
;         acc[ai][bj][m][n] = __builtin_amdgcn_mfma_f32_16x16x32_bf16(Bt[n][k], At[m][k], acc[ai][bj][m][n], 0, 0, 0); __builtin_amdgcn_s_setprio(0); } while (0)
; #define PG8_WAIT_V(n) asm volatile("s_waitcnt vmcnt(" #n ")" ::: "memory")
; #define PG8_WAIT_L(n) asm volatile("s_waitcnt lgkmcnt(" #n ")" ::: "memory")
; #define PG8_BAR __builtin_amdgcn_s_barrier()
; #define PG8_SCHED __builtin_amdgcn_sched_barrier(0)
; __device__ __forceinline__ void gemm_phase(LAS unsigned char* lds, const Params& p, const bf16_t* gA, const bf16_t* gBt, const int gM, const int gN, const int gK, const int epi, const int perm, bf16_t* const Hp, const int goff, const float coef) {
;     ...
;             PG8_LDA(At, 1, 1); PG8_STAGE(PG8_SB(1, 0), b3, voffB); PG8_STAGE(PG8_SB(1, 1), b3 + hstep, voffB); PG8_STAGE(PG8_SA(1, 0), a3, voffA);
;             PG8_WAIT_V(8); PG8_WAIT_L(0); PG8_BAR; PG8_MMA(1, 0, At, B0); PG8_MMA(1, 1, At, B1); PG8_BAR; PG8_SCHED;
	s_add_i32 s22, s55, s27
	v_lshl_add_u64 v[222:223], v[222:223], 0, s[10:11]
	s_mov_b32 m0, s22
	ds_read_b128 v[190:193], v168 offset:49152
	ds_read_b128 v[194:197], v168 offset:50176
	ds_read_b128 v[198:201], v168 offset:51200
	ds_read_b128 v[202:205], v168 offset:52224
	ds_read_b128 v[206:209], v168 offset:53248
	ds_read_b128 v[210:213], v168 offset:54272
	ds_read_b128 v[214:217], v168 offset:55296
	ds_read_b128 v[218:221], v168 offset:56320
	global_load_lds_dwordx4 v[222:223], off
	s_add_i32 m0, s22, 0x2000
	s_add_u32 s20, s20, 0x160080
	v_lshl_add_u64 v[222:223], v[224:225], 0, s[10:11]
	s_addc_u32 s21, s21, 0
	s_add_i32 s22, s56, s27
	global_load_lds_dwordx4 v[222:223], off
	v_lshl_add_u64 v[222:223], s[20:21], 0, v[130:131]
	s_mov_b32 m0, s22
	s_nop 0
	global_load_lds_dwordx4 v[222:223], off
	v_lshl_add_u64 v[222:223], s[20:21], 0, v[134:135]
	s_add_i32 m0, s22, 0x2000
	s_nop 0
	global_load_lds_dwordx4 v[222:223], off
	v_lshl_add_u64 v[222:223], v[226:227], 0, s[10:11]
	s_mov_b32 m0, s36
	s_nop 0
	global_load_lds_dwordx4 v[222:223], off
	v_lshl_add_u64 v[222:223], v[228:229], 0, s[10:11]
	s_mov_b32 m0, s37
	s_nop 0
	global_load_lds_dwordx4 v[222:223], off
	s_waitcnt vmcnt(8)
	s_waitcnt lgkmcnt(0)
	s_barrier
	s_waitcnt lgkmcnt(0)
	v_mfma_f32_16x16x32_bf16 v[92:95], v[144:147], v[190:193], v[92:95]
	v_mfma_f32_16x16x32_bf16 v[88:91], v[152:155], v[190:193], v[88:91]
	v_mfma_f32_16x16x32_bf16 v[84:87], v[144:147], v[198:201], v[84:87]
	v_mfma_f32_16x16x32_bf16 v[80:83], v[152:155], v[198:201], v[80:83]
	v_mfma_f32_16x16x32_bf16 v[76:79], v[144:147], v[206:209], v[76:79]
	v_mfma_f32_16x16x32_bf16 v[72:75], v[152:155], v[206:209], v[72:75]
	v_mfma_f32_16x16x32_bf16 v[64:67], v[144:147], v[214:217], v[64:67]
	v_mfma_f32_16x16x32_bf16 v[56:59], v[152:155], v[214:217], v[56:59]
	v_mfma_f32_16x16x32_bf16 v[92:95], v[148:151], v[194:197], v[92:95]
	v_mfma_f32_16x16x32_bf16 v[88:91], v[170:173], v[194:197], v[88:91]
	v_mfma_f32_16x16x32_bf16 v[84:87], v[148:151], v[202:205], v[84:87]
	v_mfma_f32_16x16x32_bf16 v[80:83], v[170:173], v[202:205], v[80:83]
	v_mfma_f32_16x16x32_bf16 v[76:79], v[148:151], v[210:213], v[76:79]
	v_mfma_f32_16x16x32_bf16 v[72:75], v[170:173], v[210:213], v[72:75]
	v_mfma_f32_16x16x32_bf16 v[64:67], v[148:151], v[218:221], v[64:67]
	v_mfma_f32_16x16x32_bf16 v[56:59], v[170:173], v[218:221], v[56:59]
	v_mfma_f32_16x16x32_bf16 v[28:31], v[174:177], v[190:193], v[28:31]
	v_mfma_f32_16x16x32_bf16 v[24:27], v[182:185], v[190:193], v[24:27]
	v_mfma_f32_16x16x32_bf16 v[20:23], v[174:177], v[198:201], v[20:23]
	v_mfma_f32_16x16x32_bf16 v[16:19], v[182:185], v[198:201], v[16:19]
	v_mfma_f32_16x16x32_bf16 v[12:15], v[174:177], v[206:209], v[12:15]
	v_mfma_f32_16x16x32_bf16 v[8:11], v[182:185], v[206:209], v[8:11]
	v_mfma_f32_16x16x32_bf16 v[4:7], v[174:177], v[214:217], v[4:7]
	v_mfma_f32_16x16x32_bf16 v[0:3], v[182:185], v[214:217], v[0:3]
	v_mfma_f32_16x16x32_bf16 v[28:31], v[178:181], v[194:197], v[28:31]
	v_mfma_f32_16x16x32_bf16 v[24:27], v[186:189], v[194:197], v[24:27]
	v_mfma_f32_16x16x32_bf16 v[20:23], v[178:181], v[202:205], v[20:23]
	v_mfma_f32_16x16x32_bf16 v[16:19], v[186:189], v[202:205], v[16:19]
	v_mfma_f32_16x16x32_bf16 v[12:15], v[178:181], v[210:213], v[12:15]
	v_mfma_f32_16x16x32_bf16 v[8:11], v[186:189], v[210:213], v[8:11]
	v_mfma_f32_16x16x32_bf16 v[4:7], v[178:181], v[218:221], v[4:7]
	v_mfma_f32_16x16x32_bf16 v[0:3], v[186:189], v[218:221], v[0:3]
	s_barrier
	s_add_u32 s18, s18, 0x100
	s_addc_u32 s19, s19, 0
	s_add_u32 s52, s52, 0x100
	s_addc_u32 s53, s53, 0
	s_cmp_ge_u32 s54, s50
	s_mov_b32 s20, s54
	s_cbranch_scc0 .LBB0_1827
